# P8+P9+P10 merged per workgroup (G==256): softmax and ctx tiles of own rows, two grid barriers dropped; plus gemm256 K-loop reschedule
# speedup vs baseline: 1.0369x; 1.0051x over previous
; #define LAS __attribute__((address_space(3)))
; #define VLOOP(t, N) for (int t##0_ = 2 * bid, t = min(t##0_ + vb, (N) - 1); t##0_ < (N); t##0_ += VG, t = min(t##0_ + vb, (N) - 1))
; template <int WT, class Epi>
; DEV void gemm_tile(const bf16_t* __restrict__ A, int lda, const bf16_t* __restrict__ Bt, int ldb, int K, unsigned char* lds, const Epi& epi) {
;     ...
;     const int lrow = tid >> 3, lcs = (tid & 7) ^ (lrow & 7);
;     const bf16_t* ap = A + (size_t)lrow * lda + lcs * 8;
;     const bf16_t* bp = Bt + (size_t)lrow * ldb + lcs * 8;
;     const unsigned l3a = (unsigned)(size_t)(LAS unsigned char*)lds;
;     const int nk = K >> 6;
;     ...
;     constexpr int NSTG = 65536 / STB;
; #pragma unroll
;     for (int s_ = 0; s_ < NSTG - 1; ++s_) if (s_ < nk) GLDS_STAGE(s_ * STB, s_);
;     const int aoff = (wr * WT + fr) * 128, boff = OPB + (wc * WT + fr) * 128, sw = fr & 7;
;     int cur = 0, nxt = (NSTG - 1) * STB;
;     for (int kt = 0; kt < nk; ++kt) {
;         if (NSTG == 4 && kt + 2 < nk) { if (FI == 2) asm volatile("s_waitcnt vmcnt(8)" ::: "memory"); else asm volatile("s_waitcnt vmcnt(0)" ::: "memory"); }
;         else asm volatile("s_waitcnt vmcnt(0)" ::: "memory");
;         __syncthreads();
;         if (kt + NSTG - 1 < nk) GLDS_STAGE(nxt, kt + NSTG - 1);
; #pragma unroll
;         for (int kh = 0; kh < 2; ++kh) {
;             bf16x8 af[FI], bfr[FI];
;             const int ch = ((kh * 4 + fq) ^ sw) << 4;
; #pragma unroll
;             for (int i = 0; i < FI; ++i) { af[i] = *(const bf16x8*)(lds + cur + aoff + i * 2048 + ch); bfr[i] = *(const bf16x8*)(lds + cur + boff + i * 2048 + ch); }
; #pragma unroll
;             for (int mi = 0; mi < FI; ++mi)
; #pragma unroll
;                 for (int ni = 0; ni < FI; ++ni) acc[mi][ni] = __builtin_amdgcn_mfma_f32_16x16x32_bf16(bfr[ni], af[mi], acc[mi][ni], 0, 0, 0);
;         }
;         nxt = cur; cur += STB; if (cur == NSTG * STB) cur = 0;
;     }
; __global__ void __launch_bounds__(512) hymba_fwd(Params p) {
;     ...
;         VLOOP(t, NS1) { const int bhd = t >> 5, v = t & 31, mt = v >> 1, nt = v & 1, b = bhd >> 2, hd = bhd & 3;
;             EpiF32s e{sc + (size_t)(b * SEQ + mt * 128) * 1024 + hd * 256 + nt * 128, 1024, 0.04419417382415922f};
;             gemm_tile<64>(qx + (size_t)(b * SEQ + mt * 128) * LDB + hd * 512, LDB, mkb + (size_t)(b * 256 + nt * 128) * LDB + hd * 512, LDB, 512, vlds, e);
.LBB0_1295:
	s_ashr_i32 s14, s86, 7
	s_lshl_b32 s4, s86, 6
	s_lshl_b32 s76, s86, 7
	v_mov_b32_e32 v7, v1
	s_lshl_b32 s78, s14, 11
	s_and_b32 s79, s4, 0x780
	s_lshl_b32 s15, s86, 5
	s_and_b32 s77, s76, 0x80
	s_lshl_b32 s14, s14, 8
	s_or_b32 s76, s78, s79
	v_ashrrev_i32_e32 v13, 3, v7
	s_and_b32 s4, s15, 0xc00
	s_or_b32 s14, s14, s77
	v_lshrrev_b32_e32 v4, 4, v7
	v_and_b32_e32 v6, 15, v7
	v_ashrrev_i32_e32 v15, 1, v7
	v_lshlrev_b32_e32 v16, 7, v7
	v_and_b32_e32 v17, 7, v7
	v_mad_i64_i32 v[8:9], s[78:79], s76, v12, v[132:133]
	v_xor_b32_e32 v18, v13, v7
	v_lshlrev_b32_e32 v14, 4, v7
	v_mad_i64_i32 v[10:11], s[78:79], s14, v12, v[168:169]
	v_and_or_b32 v6, v15, s85, v6
	v_and_b32_e32 v15, 0x2780, v16
	v_bitop3_b32 v4, v4, v17, 3 bitop3:0x6c
	v_lshl_add_u64 v[8:9], v[8:9], 0, s[4:5]
	v_lshlrev_b32_e32 v16, 4, v18
	v_add_u32_e32 v19, s80, v14
	v_add_u32_e32 v106, 0x4000, v14
	v_add_u32_e32 v14, s81, v14
	v_lshl_add_u64 v[10:11], v[10:11], 0, s[4:5]
	v_lshlrev_b32_e32 v20, 4, v4
	v_mad_i64_i32 v[8:9], s[86:87], v13, s84, v[8:9]
	v_and_b32_e32 v4, 0x70, v16
	v_add_u32_e32 v18, 0x4000, v19
	v_readfirstlane_b32 s92, v19
	v_readfirstlane_b32 s78, v14
	v_add_u32_e32 v87, s80, v15
	v_mad_i64_i32 v[14:15], s[86:87], v13, s84, v[10:11]
	v_lshl_add_u64 v[10:11], v[8:9], 0, v[4:5]
	s_mov_b32 vcc_lo, m0
	s_mov_b32 m0, s92
	s_nop 0
	global_load_lds_dwordx4 v[10:11], off
	s_mov_b32 m0, vcc_lo
	v_readfirstlane_b32 s14, v18
	v_lshl_add_u64 v[8:9], v[14:15], 0, v[4:5]
	s_mov_b32 vcc_lo, m0
	s_mov_b32 m0, s14
	s_nop 0
	global_load_lds_dwordx4 v[8:9], off
	s_mov_b32 m0, vcc_lo
	v_add_u32_e32 v19, s81, v106
	s_add_i32 s95, s92, 0x1000
	s_add_i32 s15, s14, 0x1000
	s_add_i32 s96, s14, 0x2000
	s_add_i32 s97, s14, 0x3000
	v_lshl_add_u64 v[14:15], v[10:11], 0, s[6:7]
	s_mov_b32 s14, m0
	s_mov_b32 m0, s95
	s_nop 0
	global_load_lds_dwordx4 v[14:15], off
	s_mov_b32 m0, s14
	v_lshl_add_u32 v86, v6, 7, s80
	v_readfirstlane_b32 s88, v19
	v_lshl_add_u64 v[18:19], v[8:9], 0, s[6:7]
	s_mov_b32 s14, m0
	s_mov_b32 m0, s15
	s_nop 0
	global_load_lds_dwordx4 v[18:19], off
	s_mov_b32 m0, s14
	s_add_i32 s94, s92, 0x2000
	v_add_u32_e32 v13, v86, v20
	v_add_u32_e32 v16, v87, v20
	v_lshl_add_u64 v[20:21], v[10:11], 0, s[8:9]
	s_mov_b32 s14, m0
	s_mov_b32 m0, s94
	s_nop 0
	global_load_lds_dwordx4 v[20:21], off
	s_mov_b32 m0, s14
	v_lshl_add_u64 v[22:23], v[8:9], 0, s[8:9]
	s_mov_b32 s14, m0
	s_mov_b32 m0, s96
	s_nop 0
	global_load_lds_dwordx4 v[22:23], off
	s_mov_b32 m0, s14
	s_add_i32 s93, s92, 0x3000
	v_lshl_add_u64 v[24:25], v[10:11], 0, s[10:11]
	s_mov_b32 s14, m0
	s_mov_b32 m0, s93
	s_nop 0
	global_load_lds_dwordx4 v[24:25], off
	s_mov_b32 m0, s14
	v_lshl_add_u64 v[26:27], v[8:9], 0, s[10:11]
	s_mov_b32 s14, m0
	s_mov_b32 m0, s97
	s_nop 0
	global_load_lds_dwordx4 v[26:27], off
	s_mov_b32 m0, s14
	v_lshl_add_u64 v[28:29], v[10:11], 0, s[12:13]
	s_waitcnt vmcnt(0)
	s_barrier
	s_mov_b32 s14, m0
	s_mov_b32 m0, s78
	s_nop 0
	global_load_lds_dwordx4 v[28:29], off
	s_mov_b32 m0, s14
	v_lshl_add_u64 v[30:31], v[8:9], 0, s[12:13]
	s_mov_b32 s14, m0
	s_mov_b32 m0, s88
	s_nop 0
	global_load_lds_dwordx4 v[30:31], off
	s_mov_b32 m0, s14
	s_add_i32 s87, s78, 0x1000
	v_lshl_add_u64 v[32:33], v[10:11], 0, s[16:17]
	s_mov_b32 s14, m0
	s_mov_b32 m0, s87
	s_nop 0
	global_load_lds_dwordx4 v[32:33], off
	s_mov_b32 m0, s14
	s_add_i32 s91, s88, 0x1000
	v_lshl_add_u64 v[34:35], v[8:9], 0, s[16:17]
	s_mov_b32 s14, m0
	s_mov_b32 m0, s91
	s_nop 0
	global_load_lds_dwordx4 v[34:35], off
	s_mov_b32 m0, s14
	s_add_i32 s86, s78, 0x2000
	v_lshl_add_u64 v[36:37], v[10:11], 0, s[18:19]
	s_mov_b32 s14, m0
	s_mov_b32 m0, s86
	s_nop 0
	global_load_lds_dwordx4 v[36:37], off
	s_mov_b32 m0, s14
	s_add_i32 s90, s88, 0x2000
	v_lshl_add_u64 v[38:39], v[8:9], 0, s[18:19]
	s_mov_b32 s14, m0
	s_mov_b32 m0, s90
	s_nop 0
	global_load_lds_dwordx4 v[38:39], off
	s_mov_b32 m0, s14
	s_add_i32 s79, s78, 0x3000
	v_lshl_add_u64 v[40:41], v[10:11], 0, s[20:21]
	s_mov_b32 s14, m0
	s_mov_b32 m0, s79
	s_nop 0
	global_load_lds_dwordx4 v[40:41], off
	s_mov_b32 m0, s14
	s_add_i32 s89, s88, 0x3000
	v_lshl_add_u64 v[42:43], v[8:9], 0, s[20:21]
	s_mov_b32 s14, m0
	s_mov_b32 m0, s89
	s_nop 0
	global_load_lds_dwordx4 v[42:43], off
	s_mov_b32 m0, s14
	ds_read_b128 v[18:21], v16 offset:16384
	ds_read_b128 v[22:25], v16 offset:18432
	ds_read_b128 v[26:29], v13
	ds_read_b128 v[30:33], v13 offset:2048
	ds_read_b128 v[38:41], v16 offset:20480
	ds_read_b128 v[46:49], v16 offset:22528
	ds_read_b128 v[66:69], v13 offset:4096
	ds_read_b128 v[70:73], v13 offset:6144
	v_bfe_u32 v4, v7, 4, 2
	v_bitop3_b32 v14, v4, v17, 4 bitop3:0x36
	v_lshlrev_b32_e32 v15, 4, v14
	v_add_u32_e32 v14, v86, v15
	v_add_u32_e32 v15, v87, v15
	s_waitcnt lgkmcnt(5)
	v_mfma_f32_16x16x32_bf16 v[34:37], v[18:21], v[26:29], 0
	ds_read_b128 v[86:89], v15 offset:16384
	ds_read_b128 v[90:93], v15 offset:18432
	v_add_u32_e32 v17, s80, v106
	v_lshl_add_u64 v[106:107], v[10:11], 0, s[22:23]
	v_mfma_f32_16x16x32_bf16 v[42:45], v[22:25], v[26:29], 0
	v_readfirstlane_b32 s96, v17
	v_lshl_add_u64 v[108:109], v[8:9], 0, s[22:23]
	v_lshl_add_u64 v[110:111], v[10:11], 0, s[24:25]
	s_waitcnt lgkmcnt(5)
	v_mfma_f32_16x16x32_bf16 v[50:53], v[38:41], v[26:29], 0
	s_add_i32 s97, s96, 0x1000
	v_lshl_add_u64 v[112:113], v[8:9], 0, s[24:25]
	s_add_i32 vcc_lo, s96, 0x2000
	s_waitcnt lgkmcnt(4)
	v_mfma_f32_16x16x32_bf16 v[26:29], v[46:49], v[26:29], 0
	v_lshl_add_u64 v[114:115], v[10:11], 0, s[26:27]
	v_lshl_add_u64 v[116:117], v[8:9], 0, s[26:27]
	v_lshl_add_u64 v[118:119], v[10:11], 0, s[30:31]
	v_mfma_f32_16x16x32_bf16 v[54:57], v[18:21], v[30:33], 0
	s_add_i32 vcc_hi, s96, 0x3000
	v_lshl_add_u64 v[120:121], v[8:9], 0, s[30:31]
	v_and_b32_e32 v7, 64, v7
	v_mfma_f32_16x16x32_bf16 v[58:61], v[22:25], v[30:33], 0
	s_add_i32 s15, s82, s83
	v_mfma_f32_16x16x32_bf16 v[62:65], v[38:41], v[30:33], 0
	v_mfma_f32_16x16x32_bf16 v[30:33], v[46:49], v[30:33], 0
	s_waitcnt lgkmcnt(3)
; #define GLDS_STAGE(st, kt_) do { \
;         _Pragma("unroll") for (int i_ = 0; i_ < FI; ++i_) { \
;             glds16(ap + (size_t)(32 * i_) * lda + (kt_) * 64, l3a + (st) + tid * 16 + i_ * 4096); \
;             glds16(bp + (size_t)(32 * i_) * ldb + (kt_) * 64, l3a + (st) + OPB + tid * 16 + i_ * 4096); } } while (0)
; #define GLDS_STAGE(st, kt_) do { \
;         _Pragma("unroll") for (int i_ = 0; i_ < 4; ++i_) { \
;             glds16(ap + (size_t)(64 * i_) * lda + (kt_) * 64, l3a + (st) + tid * 16 + i_ * 8192); \
;             glds16(bp + (size_t)(64 * i_) * ldb + (kt_) * 64, l3a + (st) + 32768 + tid * 16 + i_ * 8192); } } while (0)
; template <int WT, class Epi>
; DEV void gemm_tile(const bf16_t* __restrict__ A, int lda, const bf16_t* __restrict__ Bt, int ldb, int K, unsigned char* lds, const Epi& epi) {
;     ...
;     for (int kt = 0; kt < nk; ++kt) {
;         if (NSTG == 4 && kt + 2 < nk) { if (FI == 2) asm volatile("s_waitcnt vmcnt(8)" ::: "memory"); else asm volatile("s_waitcnt vmcnt(0)" ::: "memory"); }
;         else asm volatile("s_waitcnt vmcnt(0)" ::: "memory");
;         __syncthreads();
;         if (kt + NSTG - 1 < nk) GLDS_STAGE(nxt, kt + NSTG - 1);
; #pragma unroll
;         for (int kh = 0; kh < 2; ++kh) {
;             bf16x8 af[FI], bfr[FI];
;             const int ch = ((kh * 4 + fq) ^ sw) << 4;
; #pragma unroll
;             for (int i = 0; i < FI; ++i) { af[i] = *(const bf16x8*)(lds + cur + aoff + i * 2048 + ch); bfr[i] = *(const bf16x8*)(lds + cur + boff + i * 2048 + ch); }
; #pragma unroll
;             for (int mi = 0; mi < FI; ++mi)
; #pragma unroll
;                 for (int ni = 0; ni < FI; ++ni) acc[mi][ni] = __builtin_amdgcn_mfma_f32_16x16x32_bf16(bfr[ni], af[mi], acc[mi][ni], 0, 0, 0);
;         }
	v_mfma_f32_16x16x32_bf16 v[74:77], v[18:21], v[66:69], 0
	v_mfma_f32_16x16x32_bf16 v[78:81], v[22:25], v[66:69], 0
	v_mfma_f32_16x16x32_bf16 v[82:85], v[38:41], v[66:69], 0
	v_mfma_f32_16x16x32_bf16 v[66:69], v[46:49], v[66:69], 0
	s_waitcnt lgkmcnt(2)
	v_mfma_f32_16x16x32_bf16 v[18:21], v[18:21], v[70:73], 0
	v_mfma_f32_16x16x32_bf16 v[22:25], v[22:25], v[70:73], 0
	v_mfma_f32_16x16x32_bf16 v[38:41], v[38:41], v[70:73], 0
	v_mfma_f32_16x16x32_bf16 v[46:49], v[46:49], v[70:73], 0
	ds_read_b128 v[70:73], v14
	ds_read_b128 v[94:97], v14 offset:2048
	ds_read_b128 v[98:101], v15 offset:20480
	ds_read_b128 v[102:105], v15 offset:22528
	s_waitcnt lgkmcnt(3)
	v_mfma_f32_16x16x32_bf16 v[34:37], v[86:89], v[70:73], v[34:37]
	v_mfma_f32_16x16x32_bf16 v[42:45], v[90:93], v[70:73], v[42:45]
	s_waitcnt lgkmcnt(1)
	v_mfma_f32_16x16x32_bf16 v[50:53], v[98:101], v[70:73], v[50:53]
	s_waitcnt lgkmcnt(0)
	v_mfma_f32_16x16x32_bf16 v[26:29], v[102:105], v[70:73], v[26:29]
	v_mfma_f32_16x16x32_bf16 v[54:57], v[86:89], v[94:97], v[54:57]
	v_mfma_f32_16x16x32_bf16 v[58:61], v[90:93], v[94:97], v[58:61]
	v_mfma_f32_16x16x32_bf16 v[62:65], v[98:101], v[94:97], v[62:65]
	v_mfma_f32_16x16x32_bf16 v[30:33], v[102:105], v[94:97], v[30:33]
	ds_read_b128 v[70:73], v14 offset:4096
	ds_read_b128 v[94:97], v14 offset:6144
	s_waitcnt vmcnt(0)
	s_waitcnt lgkmcnt(0)
	s_barrier
	s_mov_b32 s14, m0
	s_mov_b32 m0, s92
	s_nop 0
	global_load_lds_dwordx4 v[106:107], off
	s_mov_b32 m0, s14
	v_mfma_f32_16x16x32_bf16 v[74:77], v[86:89], v[70:73], v[74:77]
	s_mov_b32 s14, m0
	s_mov_b32 m0, s96
	s_nop 0
	global_load_lds_dwordx4 v[108:109], off
	s_mov_b32 m0, s14
	v_lshl_add_u64 v[106:107], v[10:11], 0, s[34:35]
	s_mov_b32 s14, m0
	s_mov_b32 m0, s95
	s_nop 0
	global_load_lds_dwordx4 v[110:111], off
	s_mov_b32 m0, s14
	v_mfma_f32_16x16x32_bf16 v[78:81], v[90:93], v[70:73], v[78:81]
	s_mov_b32 s14, m0
	s_mov_b32 m0, s97
	s_nop 0
	global_load_lds_dwordx4 v[112:113], off
	s_mov_b32 m0, s14
	v_lshl_add_u64 v[108:109], v[8:9], 0, s[34:35]
	s_mov_b32 s14, m0
	s_mov_b32 m0, s94
	s_nop 0
	global_load_lds_dwordx4 v[114:115], off
	s_mov_b32 m0, s14
	v_mfma_f32_16x16x32_bf16 v[82:85], v[98:101], v[70:73], v[82:85]
	s_mov_b32 s14, m0
	s_mov_b32 m0, vcc_lo
	s_nop 0
	global_load_lds_dwordx4 v[116:117], off
	s_mov_b32 m0, s14
	v_lshl_add_u64 v[110:111], v[10:11], 0, s[36:37]
	s_mov_b32 s14, m0
	s_mov_b32 m0, s93
	s_nop 0
	global_load_lds_dwordx4 v[118:119], off
	s_mov_b32 m0, s14
	v_mfma_f32_16x16x32_bf16 v[66:69], v[102:105], v[70:73], v[66:69]
	s_mov_b32 s14, m0
	s_mov_b32 m0, vcc_hi
	s_nop 0
	global_load_lds_dwordx4 v[120:121], off
	s_mov_b32 m0, s14
	v_lshl_add_u64 v[112:113], v[8:9], 0, s[36:37]
	v_lshl_add_u64 v[114:115], v[10:11], 0, s[38:39]
	v_mfma_f32_16x16x32_bf16 v[18:21], v[86:89], v[94:97], v[18:21]
	ds_read_b128 v[70:73], v16 offset:49152
	ds_read_b128 v[86:89], v16 offset:51200
	v_lshl_add_u64 v[116:117], v[8:9], 0, s[38:39]
	v_lshl_add_u64 v[118:119], v[10:11], 0, s[40:41]
	v_mfma_f32_16x16x32_bf16 v[22:25], v[90:93], v[94:97], v[22:25]
	v_lshl_add_u64 v[120:121], v[8:9], 0, s[40:41]
	v_mfma_f32_16x16x32_bf16 v[38:41], v[98:101], v[94:97], v[38:41]
	v_mfma_f32_16x16x32_bf16 v[46:49], v[102:105], v[94:97], v[46:49]
	ds_read_b128 v[90:93], v13 offset:32768
	ds_read_b128 v[94:97], v13 offset:34816
	ds_read_b128 v[98:101], v16 offset:53248
	ds_read_b128 v[102:105], v16 offset:55296
	s_waitcnt lgkmcnt(3)
	v_mfma_f32_16x16x32_bf16 v[34:37], v[70:73], v[90:93], v[34:37]
	v_mfma_f32_16x16x32_bf16 v[42:45], v[86:89], v[90:93], v[42:45]
	s_waitcnt lgkmcnt(1)
	v_mfma_f32_16x16x32_bf16 v[50:53], v[98:101], v[90:93], v[50:53]
	s_waitcnt lgkmcnt(0)
	v_mfma_f32_16x16x32_bf16 v[26:29], v[102:105], v[90:93], v[26:29]
	v_mfma_f32_16x16x32_bf16 v[54:57], v[70:73], v[94:97], v[54:57]
	v_mfma_f32_16x16x32_bf16 v[58:61], v[86:89], v[94:97], v[58:61]
	v_mfma_f32_16x16x32_bf16 v[62:65], v[98:101], v[94:97], v[62:65]
	v_mfma_f32_16x16x32_bf16 v[30:33], v[102:105], v[94:97], v[30:33]
	ds_read_b128 v[90:93], v13 offset:36864
	ds_read_b128 v[94:97], v13 offset:38912
	s_waitcnt lgkmcnt(1)
	v_mfma_f32_16x16x32_bf16 v[74:77], v[70:73], v[90:93], v[74:77]
	v_mfma_f32_16x16x32_bf16 v[78:81], v[86:89], v[90:93], v[78:81]
	v_mfma_f32_16x16x32_bf16 v[82:85], v[98:101], v[90:93], v[82:85]
	v_mfma_f32_16x16x32_bf16 v[66:69], v[102:105], v[90:93], v[66:69]
	s_waitcnt lgkmcnt(0)
	v_mfma_f32_16x16x32_bf16 v[18:21], v[70:73], v[94:97], v[18:21]
	v_mfma_f32_16x16x32_bf16 v[22:25], v[86:89], v[94:97], v[22:25]
	ds_read_b128 v[70:73], v15 offset:49152
	ds_read_b128 v[86:89], v15 offset:51200
	v_mfma_f32_16x16x32_bf16 v[38:41], v[98:101], v[94:97], v[38:41]
	v_mfma_f32_16x16x32_bf16 v[46:49], v[102:105], v[94:97], v[46:49]
	ds_read_b128 v[90:93], v14 offset:32768
	ds_read_b128 v[94:97], v14 offset:34816
	ds_read_b128 v[98:101], v15 offset:53248
	ds_read_b128 v[102:105], v15 offset:55296
	s_waitcnt lgkmcnt(3)
	v_mfma_f32_16x16x32_bf16 v[34:37], v[70:73], v[90:93], v[34:37]
	v_mfma_f32_16x16x32_bf16 v[42:45], v[86:89], v[90:93], v[42:45]
	s_waitcnt lgkmcnt(1)
	v_mfma_f32_16x16x32_bf16 v[50:53], v[98:101], v[90:93], v[50:53]
	s_waitcnt lgkmcnt(0)
	v_mfma_f32_16x16x32_bf16 v[26:29], v[102:105], v[90:93], v[26:29]
	v_mfma_f32_16x16x32_bf16 v[54:57], v[70:73], v[94:97], v[54:57]
	v_mfma_f32_16x16x32_bf16 v[58:61], v[86:89], v[94:97], v[58:61]
	v_mfma_f32_16x16x32_bf16 v[62:65], v[98:101], v[94:97], v[62:65]
	v_mfma_f32_16x16x32_bf16 v[30:33], v[102:105], v[94:97], v[30:33]
	ds_read_b128 v[90:93], v14 offset:36864
	ds_read_b128 v[94:97], v14 offset:38912
	s_waitcnt vmcnt(0)
	s_waitcnt lgkmcnt(0)
	s_barrier
; #define GLDS_STAGE(st, kt_) do { \
;         _Pragma("unroll") for (int i_ = 0; i_ < FI; ++i_) { \
;             glds16(ap + (size_t)(32 * i_) * lda + (kt_) * 64, l3a + (st) + tid * 16 + i_ * 4096); \
;             glds16(bp + (size_t)(32 * i_) * ldb + (kt_) * 64, l3a + (st) + OPB + tid * 16 + i_ * 4096); } } while (0)
; #define GLDS_STAGE(st, kt_) do { \
;         _Pragma("unroll") for (int i_ = 0; i_ < 4; ++i_) { \
;             glds16(ap + (size_t)(64 * i_) * lda + (kt_) * 64, l3a + (st) + tid * 16 + i_ * 8192); \
;             glds16(bp + (size_t)(64 * i_) * ldb + (kt_) * 64, l3a + (st) + 32768 + tid * 16 + i_ * 8192); } } while (0)
; template <int WT, class Epi>
; DEV void gemm_tile(const bf16_t* __restrict__ A, int lda, const bf16_t* __restrict__ Bt, int ldb, int K, unsigned char* lds, const Epi& epi) {
;     ...
;     for (int kt = 0; kt < nk; ++kt) {
;         if (NSTG == 4 && kt + 2 < nk) { if (FI == 2) asm volatile("s_waitcnt vmcnt(8)" ::: "memory"); else asm volatile("s_waitcnt vmcnt(0)" ::: "memory"); }
;         else asm volatile("s_waitcnt vmcnt(0)" ::: "memory");
;         __syncthreads();
;         if (kt + NSTG - 1 < nk) GLDS_STAGE(nxt, kt + NSTG - 1);
; #pragma unroll
;         for (int kh = 0; kh < 2; ++kh) {
;             bf16x8 af[FI], bfr[FI];
;             const int ch = ((kh * 4 + fq) ^ sw) << 4;
; #pragma unroll
;             for (int i = 0; i < FI; ++i) { af[i] = *(const bf16x8*)(lds + cur + aoff + i * 2048 + ch); bfr[i] = *(const bf16x8*)(lds + cur + boff + i * 2048 + ch); }
; #pragma unroll
;             for (int mi = 0; mi < FI; ++mi)
; #pragma unroll
;                 for (int ni = 0; ni < FI; ++ni) acc[mi][ni] = __builtin_amdgcn_mfma_f32_16x16x32_bf16(bfr[ni], af[mi], acc[mi][ni], 0, 0, 0);
;         }
	s_mov_b32 s14, m0
	s_mov_b32 m0, s78
	s_nop 0
	global_load_lds_dwordx4 v[106:107], off
	s_mov_b32 m0, s14
	v_mfma_f32_16x16x32_bf16 v[74:77], v[70:73], v[90:93], v[74:77]
	s_mov_b32 s14, m0
	s_mov_b32 m0, s88
	s_nop 0
	global_load_lds_dwordx4 v[108:109], off
	s_mov_b32 m0, s14
	v_lshl_add_u64 v[106:107], v[10:11], 0, s[42:43]
	s_mov_b32 s14, m0
	s_mov_b32 m0, s87
	s_nop 0
	global_load_lds_dwordx4 v[110:111], off
	s_mov_b32 m0, s14
	v_mfma_f32_16x16x32_bf16 v[78:81], v[86:89], v[90:93], v[78:81]
	s_mov_b32 s14, m0
	s_mov_b32 m0, s91
	s_nop 0
	global_load_lds_dwordx4 v[112:113], off
	s_mov_b32 m0, s14
	v_lshl_add_u64 v[108:109], v[8:9], 0, s[42:43]
	s_mov_b32 s14, m0
	s_mov_b32 m0, s86
	s_nop 0
	global_load_lds_dwordx4 v[114:115], off
	s_mov_b32 m0, s14
	v_mfma_f32_16x16x32_bf16 v[82:85], v[98:101], v[90:93], v[82:85]
	s_mov_b32 s14, m0
	s_mov_b32 m0, s90
	s_nop 0
	global_load_lds_dwordx4 v[116:117], off
	s_mov_b32 m0, s14
	v_lshl_add_u64 v[110:111], v[10:11], 0, s[44:45]
	s_mov_b32 s14, m0
	s_mov_b32 m0, s79
	s_nop 0
	global_load_lds_dwordx4 v[118:119], off
	s_mov_b32 m0, s14
	v_mfma_f32_16x16x32_bf16 v[66:69], v[102:105], v[90:93], v[66:69]
	s_mov_b32 s14, m0
	s_mov_b32 m0, s89
	s_nop 0
	global_load_lds_dwordx4 v[120:121], off
	s_mov_b32 m0, s14
	v_lshl_add_u64 v[112:113], v[8:9], 0, s[44:45]
	v_lshl_add_u64 v[114:115], v[10:11], 0, s[46:47]
	v_mfma_f32_16x16x32_bf16 v[18:21], v[70:73], v[94:97], v[18:21]
	v_lshl_add_u64 v[116:117], v[8:9], 0, s[46:47]
	v_lshl_add_u64 v[118:119], v[10:11], 0, s[48:49]
	v_lshl_add_u64 v[120:121], v[8:9], 0, s[48:49]
	v_mfma_f32_16x16x32_bf16 v[22:25], v[86:89], v[94:97], v[22:25]
	ds_read_b128 v[70:73], v16 offset:16384
	ds_read_b128 v[86:89], v16 offset:18432
	v_mfma_f32_16x16x32_bf16 v[38:41], v[98:101], v[94:97], v[38:41]
	v_mfma_f32_16x16x32_bf16 v[46:49], v[102:105], v[94:97], v[46:49]
	ds_read_b128 v[90:93], v13
	ds_read_b128 v[94:97], v13 offset:2048
	ds_read_b128 v[98:101], v16 offset:20480
	ds_read_b128 v[102:105], v16 offset:22528
	s_waitcnt lgkmcnt(3)
	v_mfma_f32_16x16x32_bf16 v[34:37], v[70:73], v[90:93], v[34:37]
	v_mfma_f32_16x16x32_bf16 v[42:45], v[86:89], v[90:93], v[42:45]
	s_waitcnt lgkmcnt(1)
	v_mfma_f32_16x16x32_bf16 v[50:53], v[98:101], v[90:93], v[50:53]
	s_waitcnt lgkmcnt(0)
	v_mfma_f32_16x16x32_bf16 v[26:29], v[102:105], v[90:93], v[26:29]
	v_mfma_f32_16x16x32_bf16 v[54:57], v[70:73], v[94:97], v[54:57]
	v_mfma_f32_16x16x32_bf16 v[58:61], v[86:89], v[94:97], v[58:61]
	v_mfma_f32_16x16x32_bf16 v[62:65], v[98:101], v[94:97], v[62:65]
	v_mfma_f32_16x16x32_bf16 v[30:33], v[102:105], v[94:97], v[30:33]
	ds_read_b128 v[90:93], v13 offset:4096
	ds_read_b128 v[94:97], v13 offset:6144
	s_waitcnt lgkmcnt(1)
	v_mfma_f32_16x16x32_bf16 v[74:77], v[70:73], v[90:93], v[74:77]
	v_mfma_f32_16x16x32_bf16 v[78:81], v[86:89], v[90:93], v[78:81]
	v_mfma_f32_16x16x32_bf16 v[82:85], v[98:101], v[90:93], v[82:85]
	v_mfma_f32_16x16x32_bf16 v[66:69], v[102:105], v[90:93], v[66:69]
	s_waitcnt lgkmcnt(0)
	v_mfma_f32_16x16x32_bf16 v[18:21], v[70:73], v[94:97], v[18:21]
	v_mfma_f32_16x16x32_bf16 v[22:25], v[86:89], v[94:97], v[22:25]
	ds_read_b128 v[70:73], v15 offset:16384
	ds_read_b128 v[86:89], v15 offset:18432
	v_mfma_f32_16x16x32_bf16 v[38:41], v[98:101], v[94:97], v[38:41]
	v_mfma_f32_16x16x32_bf16 v[46:49], v[102:105], v[94:97], v[46:49]
	ds_read_b128 v[90:93], v14
	ds_read_b128 v[94:97], v14 offset:2048
	ds_read_b128 v[98:101], v15 offset:20480
	ds_read_b128 v[102:105], v15 offset:22528
	s_waitcnt lgkmcnt(3)
	v_mfma_f32_16x16x32_bf16 v[34:37], v[70:73], v[90:93], v[34:37]
	v_mfma_f32_16x16x32_bf16 v[42:45], v[86:89], v[90:93], v[42:45]
	s_waitcnt lgkmcnt(1)
	v_mfma_f32_16x16x32_bf16 v[50:53], v[98:101], v[90:93], v[50:53]
	s_waitcnt lgkmcnt(0)
	v_mfma_f32_16x16x32_bf16 v[26:29], v[102:105], v[90:93], v[26:29]
	v_mfma_f32_16x16x32_bf16 v[54:57], v[70:73], v[94:97], v[54:57]
	v_mfma_f32_16x16x32_bf16 v[58:61], v[86:89], v[94:97], v[58:61]
	v_mfma_f32_16x16x32_bf16 v[62:65], v[98:101], v[94:97], v[62:65]
	v_mfma_f32_16x16x32_bf16 v[30:33], v[102:105], v[94:97], v[30:33]
	ds_read_b128 v[90:93], v14 offset:4096
	ds_read_b128 v[94:97], v14 offset:6144
	s_waitcnt vmcnt(0)
	s_waitcnt lgkmcnt(0)
	s_barrier
	s_mov_b32 s14, m0
	s_mov_b32 m0, s92
	s_nop 0
	global_load_lds_dwordx4 v[106:107], off
	s_mov_b32 m0, s14
	v_mfma_f32_16x16x32_bf16 v[74:77], v[70:73], v[90:93], v[74:77]
	s_mov_b32 s14, m0
	s_mov_b32 m0, s96
	s_nop 0
	global_load_lds_dwordx4 v[108:109], off
	s_mov_b32 m0, s14
	v_lshl_add_u64 v[106:107], v[10:11], 0, s[50:51]
	s_mov_b32 s14, m0
	s_mov_b32 m0, s95
	s_nop 0
	global_load_lds_dwordx4 v[110:111], off
	s_mov_b32 m0, s14
	v_mfma_f32_16x16x32_bf16 v[78:81], v[86:89], v[90:93], v[78:81]
	s_mov_b32 s14, m0
	s_mov_b32 m0, s97
	s_nop 0
	global_load_lds_dwordx4 v[112:113], off
	s_mov_b32 m0, s14
	v_lshl_add_u64 v[108:109], v[8:9], 0, s[50:51]
	s_mov_b32 s14, m0
	s_mov_b32 m0, s94
	s_nop 0
	global_load_lds_dwordx4 v[114:115], off
	s_mov_b32 m0, s14
	v_mfma_f32_16x16x32_bf16 v[82:85], v[98:101], v[90:93], v[82:85]
	s_mov_b32 s14, m0
	s_mov_b32 m0, vcc_lo
	s_nop 0
	global_load_lds_dwordx4 v[116:117], off
	s_mov_b32 m0, s14
	v_lshl_add_u64 v[110:111], v[10:11], 0, s[52:53]
	s_mov_b32 s14, m0
	s_mov_b32 m0, s93
	s_nop 0
	global_load_lds_dwordx4 v[118:119], off
	s_mov_b32 m0, s14
	v_mfma_f32_16x16x32_bf16 v[66:69], v[102:105], v[90:93], v[66:69]
	s_mov_b32 s14, m0
	s_mov_b32 m0, vcc_hi
	s_nop 0
	global_load_lds_dwordx4 v[120:121], off
	s_mov_b32 m0, s14
	v_lshl_add_u64 v[112:113], v[8:9], 0, s[52:53]
	v_lshl_add_u64 v[114:115], v[10:11], 0, s[54:55]
	v_mfma_f32_16x16x32_bf16 v[18:21], v[70:73], v[94:97], v[18:21]
	v_lshl_add_u64 v[116:117], v[8:9], 0, s[54:55]
	v_lshl_add_u64 v[118:119], v[10:11], 0, s[56:57]
	v_lshl_add_u64 v[120:121], v[8:9], 0, s[56:57]
	v_mfma_f32_16x16x32_bf16 v[22:25], v[86:89], v[94:97], v[22:25]
	ds_read_b128 v[70:73], v16 offset:49152
	ds_read_b128 v[86:89], v16 offset:51200
	v_mfma_f32_16x16x32_bf16 v[38:41], v[98:101], v[94:97], v[38:41]
	v_mfma_f32_16x16x32_bf16 v[46:49], v[102:105], v[94:97], v[46:49]
	ds_read_b128 v[90:93], v13 offset:32768
	ds_read_b128 v[94:97], v13 offset:34816
	ds_read_b128 v[98:101], v16 offset:53248
	ds_read_b128 v[102:105], v16 offset:55296
	s_waitcnt lgkmcnt(3)
; #define GLDS_STAGE(st, kt_) do { \
;         _Pragma("unroll") for (int i_ = 0; i_ < FI; ++i_) { \
;             glds16(ap + (size_t)(32 * i_) * lda + (kt_) * 64, l3a + (st) + tid * 16 + i_ * 4096); \
;             glds16(bp + (size_t)(32 * i_) * ldb + (kt_) * 64, l3a + (st) + OPB + tid * 16 + i_ * 4096); } } while (0)
; #define GLDS_STAGE(st, kt_) do { \
;         _Pragma("unroll") for (int i_ = 0; i_ < 4; ++i_) { \
;             glds16(ap + (size_t)(64 * i_) * lda + (kt_) * 64, l3a + (st) + tid * 16 + i_ * 8192); \
;             glds16(bp + (size_t)(64 * i_) * ldb + (kt_) * 64, l3a + (st) + 32768 + tid * 16 + i_ * 8192); } } while (0)
; template <int WT, class Epi>
; DEV void gemm_tile(const bf16_t* __restrict__ A, int lda, const bf16_t* __restrict__ Bt, int ldb, int K, unsigned char* lds, const Epi& epi) {
;     ...
;     for (int kt = 0; kt < nk; ++kt) {
;         if (NSTG == 4 && kt + 2 < nk) { if (FI == 2) asm volatile("s_waitcnt vmcnt(8)" ::: "memory"); else asm volatile("s_waitcnt vmcnt(0)" ::: "memory"); }
;         else asm volatile("s_waitcnt vmcnt(0)" ::: "memory");
;         __syncthreads();
;         if (kt + NSTG - 1 < nk) GLDS_STAGE(nxt, kt + NSTG - 1);
; #pragma unroll
;         for (int kh = 0; kh < 2; ++kh) {
;             bf16x8 af[FI], bfr[FI];
;             const int ch = ((kh * 4 + fq) ^ sw) << 4;
; #pragma unroll
;             for (int i = 0; i < FI; ++i) { af[i] = *(const bf16x8*)(lds + cur + aoff + i * 2048 + ch); bfr[i] = *(const bf16x8*)(lds + cur + boff + i * 2048 + ch); }
; #pragma unroll
;             for (int mi = 0; mi < FI; ++mi)
; #pragma unroll
;                 for (int ni = 0; ni < FI; ++ni) acc[mi][ni] = __builtin_amdgcn_mfma_f32_16x16x32_bf16(bfr[ni], af[mi], acc[mi][ni], 0, 0, 0);
;         }
	v_mfma_f32_16x16x32_bf16 v[34:37], v[70:73], v[90:93], v[34:37]
	v_mfma_f32_16x16x32_bf16 v[42:45], v[86:89], v[90:93], v[42:45]
	s_waitcnt lgkmcnt(1)
	v_mfma_f32_16x16x32_bf16 v[50:53], v[98:101], v[90:93], v[50:53]
	s_waitcnt lgkmcnt(0)
	v_mfma_f32_16x16x32_bf16 v[26:29], v[102:105], v[90:93], v[26:29]
	v_mfma_f32_16x16x32_bf16 v[54:57], v[70:73], v[94:97], v[54:57]
	v_mfma_f32_16x16x32_bf16 v[58:61], v[86:89], v[94:97], v[58:61]
	v_mfma_f32_16x16x32_bf16 v[62:65], v[98:101], v[94:97], v[62:65]
	v_mfma_f32_16x16x32_bf16 v[30:33], v[102:105], v[94:97], v[30:33]
	ds_read_b128 v[90:93], v13 offset:36864
	ds_read_b128 v[94:97], v13 offset:38912
	s_waitcnt lgkmcnt(1)
	v_mfma_f32_16x16x32_bf16 v[74:77], v[70:73], v[90:93], v[74:77]
	v_mfma_f32_16x16x32_bf16 v[78:81], v[86:89], v[90:93], v[78:81]
	v_mfma_f32_16x16x32_bf16 v[82:85], v[98:101], v[90:93], v[82:85]
	v_mfma_f32_16x16x32_bf16 v[66:69], v[102:105], v[90:93], v[66:69]
	s_waitcnt lgkmcnt(0)
	v_mfma_f32_16x16x32_bf16 v[18:21], v[70:73], v[94:97], v[18:21]
	v_mfma_f32_16x16x32_bf16 v[22:25], v[86:89], v[94:97], v[22:25]
	ds_read_b128 v[70:73], v15 offset:49152
	ds_read_b128 v[86:89], v15 offset:51200
	v_mfma_f32_16x16x32_bf16 v[38:41], v[98:101], v[94:97], v[38:41]
	v_mfma_f32_16x16x32_bf16 v[46:49], v[102:105], v[94:97], v[46:49]
	ds_read_b128 v[90:93], v14 offset:32768
	ds_read_b128 v[94:97], v14 offset:34816
	ds_read_b128 v[98:101], v15 offset:53248
	ds_read_b128 v[102:105], v15 offset:55296
	s_waitcnt lgkmcnt(3)
	v_mfma_f32_16x16x32_bf16 v[34:37], v[70:73], v[90:93], v[34:37]
	v_mfma_f32_16x16x32_bf16 v[42:45], v[86:89], v[90:93], v[42:45]
	s_waitcnt lgkmcnt(1)
	v_mfma_f32_16x16x32_bf16 v[50:53], v[98:101], v[90:93], v[50:53]
	s_waitcnt lgkmcnt(0)
	v_mfma_f32_16x16x32_bf16 v[26:29], v[102:105], v[90:93], v[26:29]
	v_mfma_f32_16x16x32_bf16 v[54:57], v[70:73], v[94:97], v[54:57]
	v_mfma_f32_16x16x32_bf16 v[58:61], v[86:89], v[94:97], v[58:61]
	v_mfma_f32_16x16x32_bf16 v[62:65], v[98:101], v[94:97], v[62:65]
	v_mfma_f32_16x16x32_bf16 v[30:33], v[102:105], v[94:97], v[30:33]
	ds_read_b128 v[90:93], v14 offset:36864
	ds_read_b128 v[94:97], v14 offset:38912
	s_waitcnt vmcnt(0)
	s_waitcnt lgkmcnt(0)
	s_barrier
	s_mov_b32 s14, m0
	s_mov_b32 m0, s78
	s_nop 0
	global_load_lds_dwordx4 v[106:107], off
	s_mov_b32 m0, s14
	v_mfma_f32_16x16x32_bf16 v[74:77], v[70:73], v[90:93], v[74:77]
	s_mov_b32 s14, m0
	s_mov_b32 m0, s88
	s_nop 0
	global_load_lds_dwordx4 v[108:109], off
	s_mov_b32 m0, s14
	v_lshl_add_u64 v[106:107], v[10:11], 0, s[58:59]
	s_mov_b32 s14, m0
	s_mov_b32 m0, s87
	s_nop 0
	global_load_lds_dwordx4 v[110:111], off
	s_mov_b32 m0, s14
	v_mfma_f32_16x16x32_bf16 v[78:81], v[86:89], v[90:93], v[78:81]
	s_mov_b32 s14, m0
	s_mov_b32 m0, s91
	s_nop 0
	global_load_lds_dwordx4 v[112:113], off
	s_mov_b32 m0, s14
	v_lshl_add_u64 v[108:109], v[8:9], 0, s[58:59]
	s_mov_b32 s14, m0
	s_mov_b32 m0, s86
	s_nop 0
	global_load_lds_dwordx4 v[114:115], off
	s_mov_b32 m0, s14
	v_mfma_f32_16x16x32_bf16 v[82:85], v[98:101], v[90:93], v[82:85]
	s_mov_b32 s14, m0
	s_mov_b32 m0, s90
	s_nop 0
	global_load_lds_dwordx4 v[116:117], off
	s_mov_b32 m0, s14
	v_lshl_add_u64 v[110:111], v[10:11], 0, s[60:61]
	s_mov_b32 s14, m0
	s_mov_b32 m0, s79
	s_nop 0
	global_load_lds_dwordx4 v[118:119], off
	s_mov_b32 m0, s14
	v_mfma_f32_16x16x32_bf16 v[66:69], v[102:105], v[90:93], v[66:69]
	s_mov_b32 s14, m0
	s_mov_b32 m0, s89
	s_nop 0
	global_load_lds_dwordx4 v[120:121], off
	s_mov_b32 m0, s14
	v_lshl_add_u64 v[112:113], v[8:9], 0, s[60:61]
	v_lshl_add_u64 v[114:115], v[10:11], 0, s[62:63]
	v_mfma_f32_16x16x32_bf16 v[18:21], v[70:73], v[94:97], v[18:21]
	v_lshl_add_u64 v[116:117], v[8:9], 0, s[62:63]
	v_lshl_add_u64 v[118:119], v[10:11], 0, s[64:65]
	v_lshl_add_u64 v[120:121], v[8:9], 0, s[64:65]
	v_mfma_f32_16x16x32_bf16 v[22:25], v[86:89], v[94:97], v[22:25]
	ds_read_b128 v[70:73], v16 offset:16384
	ds_read_b128 v[86:89], v16 offset:18432
	v_mfma_f32_16x16x32_bf16 v[38:41], v[98:101], v[94:97], v[38:41]
	v_mfma_f32_16x16x32_bf16 v[46:49], v[102:105], v[94:97], v[46:49]
	ds_read_b128 v[90:93], v13
	ds_read_b128 v[94:97], v13 offset:2048
	ds_read_b128 v[98:101], v16 offset:20480
	ds_read_b128 v[102:105], v16 offset:22528
	s_waitcnt lgkmcnt(3)
	v_mfma_f32_16x16x32_bf16 v[34:37], v[70:73], v[90:93], v[34:37]
	v_mfma_f32_16x16x32_bf16 v[42:45], v[86:89], v[90:93], v[42:45]
	s_waitcnt lgkmcnt(1)
	v_mfma_f32_16x16x32_bf16 v[50:53], v[98:101], v[90:93], v[50:53]
	s_waitcnt lgkmcnt(0)
	v_mfma_f32_16x16x32_bf16 v[26:29], v[102:105], v[90:93], v[26:29]
	v_mfma_f32_16x16x32_bf16 v[54:57], v[70:73], v[94:97], v[54:57]
	v_mfma_f32_16x16x32_bf16 v[58:61], v[86:89], v[94:97], v[58:61]
	v_mfma_f32_16x16x32_bf16 v[62:65], v[98:101], v[94:97], v[62:65]
	v_mfma_f32_16x16x32_bf16 v[30:33], v[102:105], v[94:97], v[30:33]
	ds_read_b128 v[90:93], v13 offset:4096
	ds_read_b128 v[94:97], v13 offset:6144
	s_waitcnt lgkmcnt(1)
	v_mfma_f32_16x16x32_bf16 v[74:77], v[70:73], v[90:93], v[74:77]
	v_mfma_f32_16x16x32_bf16 v[78:81], v[86:89], v[90:93], v[78:81]
	v_mfma_f32_16x16x32_bf16 v[82:85], v[98:101], v[90:93], v[82:85]
	v_mfma_f32_16x16x32_bf16 v[66:69], v[102:105], v[90:93], v[66:69]
	s_waitcnt lgkmcnt(0)
	v_mfma_f32_16x16x32_bf16 v[18:21], v[70:73], v[94:97], v[18:21]
	v_mfma_f32_16x16x32_bf16 v[22:25], v[86:89], v[94:97], v[22:25]
	ds_read_b128 v[70:73], v15 offset:16384
	ds_read_b128 v[86:89], v15 offset:18432
	v_mfma_f32_16x16x32_bf16 v[38:41], v[98:101], v[94:97], v[38:41]
	v_mfma_f32_16x16x32_bf16 v[46:49], v[102:105], v[94:97], v[46:49]
	ds_read_b128 v[90:93], v14
	ds_read_b128 v[94:97], v14 offset:2048
	ds_read_b128 v[98:101], v15 offset:20480
	ds_read_b128 v[102:105], v15 offset:22528
	s_waitcnt lgkmcnt(3)
	v_mfma_f32_16x16x32_bf16 v[34:37], v[70:73], v[90:93], v[34:37]
	v_mfma_f32_16x16x32_bf16 v[42:45], v[86:89], v[90:93], v[42:45]
	s_waitcnt lgkmcnt(1)
	v_mfma_f32_16x16x32_bf16 v[50:53], v[98:101], v[90:93], v[50:53]
	s_waitcnt lgkmcnt(0)
	v_mfma_f32_16x16x32_bf16 v[26:29], v[102:105], v[90:93], v[26:29]
	v_mfma_f32_16x16x32_bf16 v[54:57], v[70:73], v[94:97], v[54:57]
	v_mfma_f32_16x16x32_bf16 v[58:61], v[86:89], v[94:97], v[58:61]
	v_mfma_f32_16x16x32_bf16 v[62:65], v[98:101], v[94:97], v[62:65]
	v_mfma_f32_16x16x32_bf16 v[30:33], v[102:105], v[94:97], v[30:33]
	ds_read_b128 v[90:93], v14 offset:4096
	ds_read_b128 v[94:97], v14 offset:6144
	s_waitcnt vmcnt(0)
	s_waitcnt lgkmcnt(0)
	s_barrier
; #define GLDS_STAGE(st, kt_) do { \
;         _Pragma("unroll") for (int i_ = 0; i_ < FI; ++i_) { \
;             glds16(ap + (size_t)(32 * i_) * lda + (kt_) * 64, l3a + (st) + tid * 16 + i_ * 4096); \
;             glds16(bp + (size_t)(32 * i_) * ldb + (kt_) * 64, l3a + (st) + OPB + tid * 16 + i_ * 4096); } } while (0)
; #define GLDS_STAGE(st, kt_) do { \
;         _Pragma("unroll") for (int i_ = 0; i_ < 4; ++i_) { \
;             glds16(ap + (size_t)(64 * i_) * lda + (kt_) * 64, l3a + (st) + tid * 16 + i_ * 8192); \
;             glds16(bp + (size_t)(64 * i_) * ldb + (kt_) * 64, l3a + (st) + 32768 + tid * 16 + i_ * 8192); } } while (0)
; template <int WT, class Epi>
; DEV void gemm_tile(const bf16_t* __restrict__ A, int lda, const bf16_t* __restrict__ Bt, int ldb, int K, unsigned char* lds, const Epi& epi) {
;     ...
;     for (int kt = 0; kt < nk; ++kt) {
;         if (NSTG == 4 && kt + 2 < nk) { if (FI == 2) asm volatile("s_waitcnt vmcnt(8)" ::: "memory"); else asm volatile("s_waitcnt vmcnt(0)" ::: "memory"); }
;         else asm volatile("s_waitcnt vmcnt(0)" ::: "memory");
;         __syncthreads();
;         if (kt + NSTG - 1 < nk) GLDS_STAGE(nxt, kt + NSTG - 1);
; #pragma unroll
;         for (int kh = 0; kh < 2; ++kh) {
;             bf16x8 af[FI], bfr[FI];
;             const int ch = ((kh * 4 + fq) ^ sw) << 4;
; #pragma unroll
;             for (int i = 0; i < FI; ++i) { af[i] = *(const bf16x8*)(lds + cur + aoff + i * 2048 + ch); bfr[i] = *(const bf16x8*)(lds + cur + boff + i * 2048 + ch); }
; #pragma unroll
;             for (int mi = 0; mi < FI; ++mi)
; #pragma unroll
;                 for (int ni = 0; ni < FI; ++ni) acc[mi][ni] = __builtin_amdgcn_mfma_f32_16x16x32_bf16(bfr[ni], af[mi], acc[mi][ni], 0, 0, 0);
;         }
	s_mov_b32 s14, m0
	s_mov_b32 m0, s92
	s_nop 0
	global_load_lds_dwordx4 v[106:107], off
	s_mov_b32 m0, s14
	v_mfma_f32_16x16x32_bf16 v[74:77], v[70:73], v[90:93], v[74:77]
	s_mov_b32 s14, m0
	s_mov_b32 m0, s96
	s_nop 0
	global_load_lds_dwordx4 v[108:109], off
	s_mov_b32 m0, s14
	v_lshl_add_u64 v[106:107], v[10:11], 0, s[66:67]
	s_mov_b32 s14, m0
	s_mov_b32 m0, s95
	s_nop 0
	global_load_lds_dwordx4 v[110:111], off
	s_mov_b32 m0, s14
	v_mfma_f32_16x16x32_bf16 v[78:81], v[86:89], v[90:93], v[78:81]
	s_mov_b32 s14, m0
	s_mov_b32 m0, s97
	s_nop 0
	global_load_lds_dwordx4 v[112:113], off
	s_mov_b32 m0, s14
	v_lshl_add_u64 v[108:109], v[8:9], 0, s[66:67]
	s_mov_b32 s14, m0
	s_mov_b32 m0, s94
	s_nop 0
	global_load_lds_dwordx4 v[114:115], off
	s_mov_b32 m0, s14
	v_mfma_f32_16x16x32_bf16 v[82:85], v[98:101], v[90:93], v[82:85]
	s_mov_b32 s14, m0
	s_mov_b32 m0, vcc_lo
	s_nop 0
	global_load_lds_dwordx4 v[116:117], off
	s_mov_b32 m0, s14
	v_lshl_add_u64 v[110:111], v[10:11], 0, s[68:69]
	s_mov_b32 s14, m0
	s_mov_b32 m0, s93
	s_nop 0
	global_load_lds_dwordx4 v[118:119], off
	s_mov_b32 m0, s14
	v_mfma_f32_16x16x32_bf16 v[66:69], v[102:105], v[90:93], v[66:69]
	s_mov_b32 s14, m0
	s_mov_b32 m0, vcc_hi
	s_nop 0
	global_load_lds_dwordx4 v[120:121], off
	s_mov_b32 m0, s14
	v_lshl_add_u64 v[112:113], v[8:9], 0, s[68:69]
	v_lshl_add_u64 v[114:115], v[10:11], 0, s[70:71]
	v_mfma_f32_16x16x32_bf16 v[18:21], v[70:73], v[94:97], v[18:21]
	v_lshl_add_u64 v[116:117], v[8:9], 0, s[70:71]
	v_lshl_add_u64 v[118:119], v[10:11], 0, s[72:73]
	v_lshl_add_u64 v[120:121], v[8:9], 0, s[72:73]
	v_mfma_f32_16x16x32_bf16 v[22:25], v[86:89], v[94:97], v[22:25]
	ds_read_b128 v[70:73], v16 offset:49152
	ds_read_b128 v[86:89], v16 offset:51200
	v_mfma_f32_16x16x32_bf16 v[38:41], v[98:101], v[94:97], v[38:41]
	v_mfma_f32_16x16x32_bf16 v[46:49], v[102:105], v[94:97], v[46:49]
	ds_read_b128 v[90:93], v13 offset:32768
	ds_read_b128 v[94:97], v13 offset:34816
	ds_read_b128 v[98:101], v16 offset:53248
	ds_read_b128 v[102:105], v16 offset:55296
	s_waitcnt lgkmcnt(3)
	v_mfma_f32_16x16x32_bf16 v[34:37], v[70:73], v[90:93], v[34:37]
	v_mfma_f32_16x16x32_bf16 v[42:45], v[86:89], v[90:93], v[42:45]
	s_waitcnt lgkmcnt(1)
	v_mfma_f32_16x16x32_bf16 v[50:53], v[98:101], v[90:93], v[50:53]
	s_waitcnt lgkmcnt(0)
	v_mfma_f32_16x16x32_bf16 v[26:29], v[102:105], v[90:93], v[26:29]
	v_mfma_f32_16x16x32_bf16 v[54:57], v[70:73], v[94:97], v[54:57]
	v_mfma_f32_16x16x32_bf16 v[58:61], v[86:89], v[94:97], v[58:61]
	v_mfma_f32_16x16x32_bf16 v[62:65], v[98:101], v[94:97], v[62:65]
	v_mfma_f32_16x16x32_bf16 v[30:33], v[102:105], v[94:97], v[30:33]
	ds_read_b128 v[90:93], v13 offset:36864
	ds_read_b128 v[94:97], v13 offset:38912
	s_waitcnt lgkmcnt(1)
	v_mfma_f32_16x16x32_bf16 v[74:77], v[70:73], v[90:93], v[74:77]
	v_mfma_f32_16x16x32_bf16 v[78:81], v[86:89], v[90:93], v[78:81]
	v_mfma_f32_16x16x32_bf16 v[82:85], v[98:101], v[90:93], v[82:85]
	v_mfma_f32_16x16x32_bf16 v[66:69], v[102:105], v[90:93], v[66:69]
	s_waitcnt lgkmcnt(0)
	v_mfma_f32_16x16x32_bf16 v[18:21], v[70:73], v[94:97], v[18:21]
	v_mfma_f32_16x16x32_bf16 v[22:25], v[86:89], v[94:97], v[22:25]
	ds_read_b128 v[70:73], v15 offset:49152
	ds_read_b128 v[86:89], v15 offset:51200
	v_mfma_f32_16x16x32_bf16 v[38:41], v[98:101], v[94:97], v[38:41]
	v_mfma_f32_16x16x32_bf16 v[46:49], v[102:105], v[94:97], v[46:49]
	ds_read_b128 v[90:93], v14 offset:32768
	ds_read_b128 v[94:97], v14 offset:34816
	ds_read_b128 v[98:101], v15 offset:53248
	ds_read_b128 v[102:105], v15 offset:55296
	s_waitcnt lgkmcnt(3)
	v_mfma_f32_16x16x32_bf16 v[34:37], v[70:73], v[90:93], v[34:37]
	v_mfma_f32_16x16x32_bf16 v[42:45], v[86:89], v[90:93], v[42:45]
	s_waitcnt lgkmcnt(1)
	v_mfma_f32_16x16x32_bf16 v[50:53], v[98:101], v[90:93], v[50:53]
	s_waitcnt lgkmcnt(0)
	v_mfma_f32_16x16x32_bf16 v[26:29], v[102:105], v[90:93], v[26:29]
	v_mfma_f32_16x16x32_bf16 v[54:57], v[70:73], v[94:97], v[54:57]
	v_mfma_f32_16x16x32_bf16 v[58:61], v[86:89], v[94:97], v[58:61]
	v_mfma_f32_16x16x32_bf16 v[62:65], v[98:101], v[94:97], v[62:65]
	v_mfma_f32_16x16x32_bf16 v[30:33], v[102:105], v[94:97], v[30:33]
	ds_read_b128 v[90:93], v14 offset:36864
	ds_read_b128 v[94:97], v14 offset:38912
	s_waitcnt vmcnt(0)
	s_waitcnt lgkmcnt(0)
	s_barrier
; #define GLDS_STAGE(st, kt_) do { \
;         _Pragma("unroll") for (int i_ = 0; i_ < FI; ++i_) { \
;             glds16(ap + (size_t)(32 * i_) * lda + (kt_) * 64, l3a + (st) + tid * 16 + i_ * 4096); \
;             glds16(bp + (size_t)(32 * i_) * ldb + (kt_) * 64, l3a + (st) + OPB + tid * 16 + i_ * 4096); } } while (0)
; #define GLDS_STAGE(st, kt_) do { \
;         _Pragma("unroll") for (int i_ = 0; i_ < 4; ++i_) { \
;             glds16(ap + (size_t)(64 * i_) * lda + (kt_) * 64, l3a + (st) + tid * 16 + i_ * 8192); \
;             glds16(bp + (size_t)(64 * i_) * ldb + (kt_) * 64, l3a + (st) + 32768 + tid * 16 + i_ * 8192); } } while (0)
; template <int WT, class Epi>
; DEV void gemm_tile(const bf16_t* __restrict__ A, int lda, const bf16_t* __restrict__ Bt, int ldb, int K, unsigned char* lds, const Epi& epi) {
;     ...
;     for (int kt = 0; kt < nk; ++kt) {
;         if (NSTG == 4 && kt + 2 < nk) { if (FI == 2) asm volatile("s_waitcnt vmcnt(8)" ::: "memory"); else asm volatile("s_waitcnt vmcnt(0)" ::: "memory"); }
;         else asm volatile("s_waitcnt vmcnt(0)" ::: "memory");
;         __syncthreads();
;         if (kt + NSTG - 1 < nk) GLDS_STAGE(nxt, kt + NSTG - 1);
; #pragma unroll
;         for (int kh = 0; kh < 2; ++kh) {
;             bf16x8 af[FI], bfr[FI];
;             const int ch = ((kh * 4 + fq) ^ sw) << 4;
; #pragma unroll
;             for (int i = 0; i < FI; ++i) { af[i] = *(const bf16x8*)(lds + cur + aoff + i * 2048 + ch); bfr[i] = *(const bf16x8*)(lds + cur + boff + i * 2048 + ch); }
; #pragma unroll
;             for (int mi = 0; mi < FI; ++mi)
; #pragma unroll
;                 for (int ni = 0; ni < FI; ++ni) acc[mi][ni] = __builtin_amdgcn_mfma_f32_16x16x32_bf16(bfr[ni], af[mi], acc[mi][ni], 0, 0, 0);
;         }
;         nxt = cur; cur += STB; if (cur == NSTG * STB) cur = 0;
;     }
; __global__ void __launch_bounds__(512) hymba_fwd(Params p) {
;     ...
;         VLOOP(t, NS1) { const int bhd = t >> 5, v = t & 31, mt = v >> 1, nt = v & 1, b = bhd >> 2, hd = bhd & 3;
;             EpiF32s e{sc + (size_t)(b * SEQ + mt * 128) * 1024 + hd * 256 + nt * 128, 1024, 0.04419417382415922f};
;             gemm_tile<64>(qx + (size_t)(b * SEQ + mt * 128) * LDB + hd * 512, LDB, mkb + (size_t)(b * 256 + nt * 128) * LDB + hd * 512, LDB, 512, vlds, e);
	s_mov_b32 s14, m0
	s_mov_b32 m0, s78
	s_nop 0
	global_load_lds_dwordx4 v[106:107], off
	s_mov_b32 m0, s14
	v_mfma_f32_16x16x32_bf16 v[74:77], v[70:73], v[90:93], v[74:77]
	s_mov_b32 s14, m0
	s_mov_b32 m0, s88
	s_nop 0
	global_load_lds_dwordx4 v[108:109], off
	s_mov_b32 m0, s14
	s_lshl_b32 s78, s77, 2
	s_mov_b32 s14, m0
	s_mov_b32 m0, s87
	s_nop 0
	global_load_lds_dwordx4 v[110:111], off
	s_mov_b32 m0, s14
	v_mfma_f32_16x16x32_bf16 v[78:81], v[86:89], v[90:93], v[78:81]
	s_mov_b32 s14, m0
	s_mov_b32 m0, s91
	s_nop 0
	global_load_lds_dwordx4 v[112:113], off
	s_mov_b32 m0, s14
	s_ashr_i32 s77, s76, 31
	s_mov_b32 s14, m0
	s_mov_b32 m0, s86
	s_nop 0
	global_load_lds_dwordx4 v[114:115], off
	s_mov_b32 m0, s14
	v_mfma_f32_16x16x32_bf16 v[8:11], v[98:101], v[90:93], v[82:85]
	s_mov_b32 s14, m0
	s_mov_b32 m0, s90
	s_nop 0
	global_load_lds_dwordx4 v[116:117], off
	s_mov_b32 m0, s14
	s_lshl_b64 s[76:77], s[76:77], 12
	s_mov_b32 s14, m0
	s_mov_b32 m0, s79
	s_nop 0
	global_load_lds_dwordx4 v[118:119], off
	s_mov_b32 m0, s14
	v_mfma_f32_16x16x32_bf16 v[66:69], v[102:105], v[90:93], v[66:69]
	s_mov_b32 s14, m0
	s_mov_b32 m0, s89
	s_nop 0
	global_load_lds_dwordx4 v[120:121], off
	s_mov_b32 m0, s14
	s_mov_b32 s79, s5
	s_add_i32 s14, s83, s75
	v_mfma_f32_16x16x32_bf16 v[18:21], v[70:73], v[94:97], v[18:21]
	ds_read_b128 v[70:73], v16 offset:16384
	ds_read_b128 v[82:85], v16 offset:18432
	s_min_i32 s86, s15, 0x1ff
	s_mov_b32 s83, s14
	v_mfma_f32_16x16x32_bf16 v[22:25], v[86:89], v[94:97], v[22:25]
	ds_read_b128 v[86:89], v13
	ds_read_b128 v[90:93], v13 offset:2048
	s_cmpk_lt_i32 s14, 0x200
	v_mfma_f32_16x16x32_bf16 v[38:41], v[98:101], v[94:97], v[38:41]
	ds_read_b128 v[98:101], v16 offset:22528
	v_mfma_f32_16x16x32_bf16 v[46:49], v[102:105], v[94:97], v[46:49]
	ds_read_b128 v[94:97], v16 offset:20480
	v_or_b32_e32 v102, 48, v6
	v_lshl_add_u64 v[104:105], v[2:3], 0, s[76:77]
	s_waitcnt lgkmcnt(3)
	v_mfma_f32_16x16x32_bf16 v[34:37], v[70:73], v[86:89], v[34:37]
	v_ashrrev_i32_e32 v103, 31, v102
	v_mfma_f32_16x16x32_bf16 v[42:45], v[82:85], v[86:89], v[42:45]
	s_waitcnt lgkmcnt(0)
	v_mfma_f32_16x16x32_bf16 v[50:53], v[94:97], v[86:89], v[50:53]
	v_mfma_f32_16x16x32_bf16 v[26:29], v[98:101], v[86:89], v[26:29]
	v_mfma_f32_16x16x32_bf16 v[54:57], v[70:73], v[90:93], v[54:57]
	v_mfma_f32_16x16x32_bf16 v[58:61], v[82:85], v[90:93], v[58:61]
	v_mfma_f32_16x16x32_bf16 v[62:65], v[94:97], v[90:93], v[62:65]
	v_mfma_f32_16x16x32_bf16 v[30:33], v[98:101], v[90:93], v[30:33]
	ds_read_b128 v[86:89], v13 offset:4096
	ds_read_b128 v[90:93], v13 offset:6144
	s_waitcnt lgkmcnt(1)
	v_mfma_f32_16x16x32_bf16 v[74:77], v[70:73], v[86:89], v[74:77]
	v_mfma_f32_16x16x32_bf16 v[78:81], v[82:85], v[86:89], v[78:81]
	v_mfma_f32_16x16x32_bf16 v[8:11], v[94:97], v[86:89], v[8:11]
	v_mfma_f32_16x16x32_bf16 v[66:69], v[98:101], v[86:89], v[66:69]
	s_waitcnt lgkmcnt(0)
	v_mfma_f32_16x16x32_bf16 v[18:21], v[70:73], v[90:93], v[18:21]
	v_mfma_f32_16x16x32_bf16 v[22:25], v[82:85], v[90:93], v[22:25]
	ds_read_b128 v[70:73], v15 offset:16384
	ds_read_b128 v[82:85], v15 offset:18432
	v_mfma_f32_16x16x32_bf16 v[38:41], v[94:97], v[90:93], v[38:41]
	v_mfma_f32_16x16x32_bf16 v[46:49], v[98:101], v[90:93], v[46:49]
	ds_read_b128 v[86:89], v14
	ds_read_b128 v[90:93], v14 offset:2048
	ds_read_b128 v[94:97], v15 offset:20480
	ds_read_b128 v[98:101], v15 offset:22528
	s_waitcnt lgkmcnt(3)
	v_mfma_f32_16x16x32_bf16 v[34:37], v[70:73], v[86:89], v[34:37]
	v_mfma_f32_16x16x32_bf16 v[42:45], v[82:85], v[86:89], v[42:45]
	s_waitcnt lgkmcnt(1)
	v_mfma_f32_16x16x32_bf16 v[50:53], v[94:97], v[86:89], v[50:53]
	s_waitcnt lgkmcnt(0)
	v_mfma_f32_16x16x32_bf16 v[26:29], v[98:101], v[86:89], v[26:29]
	v_mfma_f32_16x16x32_bf16 v[54:57], v[70:73], v[90:93], v[54:57]
	v_mfma_f32_16x16x32_bf16 v[58:61], v[82:85], v[90:93], v[58:61]
	v_mfma_f32_16x16x32_bf16 v[62:65], v[94:97], v[90:93], v[62:65]
	v_mfma_f32_16x16x32_bf16 v[30:33], v[98:101], v[90:93], v[30:33]
	ds_read_b128 v[86:89], v14 offset:4096
	ds_read_b128 v[90:93], v14 offset:6144
	s_waitcnt vmcnt(0)
	s_waitcnt lgkmcnt(0)
	v_mfma_f32_16x16x32_bf16 v[74:77], v[70:73], v[86:89], v[74:77]
	s_barrier
	v_mfma_f32_16x16x32_bf16 v[78:81], v[82:85], v[86:89], v[78:81]
	v_mfma_f32_16x16x32_bf16 v[8:11], v[94:97], v[86:89], v[8:11]
	v_mfma_f32_16x16x32_bf16 v[66:69], v[98:101], v[86:89], v[66:69]
	ds_read_b128 v[86:89], v16 offset:51200
	v_mfma_f32_16x16x32_bf16 v[18:21], v[70:73], v[90:93], v[18:21]
	ds_read_b128 v[70:73], v16 offset:49152
	v_mfma_f32_16x16x32_bf16 v[22:25], v[82:85], v[90:93], v[22:25]
	ds_read_b128 v[82:85], v13 offset:32768
	v_mfma_f32_16x16x32_bf16 v[38:41], v[94:97], v[90:93], v[38:41]
	ds_read_b128 v[94:97], v16 offset:55296
	v_mfma_f32_16x16x32_bf16 v[46:49], v[98:101], v[90:93], v[46:49]
	ds_read_b128 v[90:93], v16 offset:53248
	v_or_b32_e32 v98, 16, v6
	v_or_b32_e32 v100, 32, v6
	s_waitcnt lgkmcnt(2)
	v_mfma_f32_16x16x32_bf16 v[34:37], v[70:73], v[82:85], v[34:37]
	v_ashrrev_i32_e32 v99, 31, v98
	v_ashrrev_i32_e32 v101, 31, v100
	v_mfma_f32_16x16x32_bf16 v[42:45], v[86:89], v[82:85], v[42:45]
	s_waitcnt lgkmcnt(0)
	v_mfma_f32_16x16x32_bf16 v[50:53], v[90:93], v[82:85], v[50:53]
	v_mfma_f32_16x16x32_bf16 v[26:29], v[94:97], v[82:85], v[26:29]
	ds_read_b128 v[82:85], v13 offset:34816
	s_waitcnt lgkmcnt(0)
	v_mfma_f32_16x16x32_bf16 v[54:57], v[70:73], v[82:85], v[54:57]
	v_mfma_f32_16x16x32_bf16 v[58:61], v[86:89], v[82:85], v[58:61]
	v_mfma_f32_16x16x32_bf16 v[62:65], v[90:93], v[82:85], v[62:65]
	v_mfma_f32_16x16x32_bf16 v[30:33], v[94:97], v[82:85], v[30:33]
	ds_read_b128 v[82:85], v13 offset:36864
	s_waitcnt lgkmcnt(0)
; DEV unsigned cvt_pk_bf16(float lo, float hi) { const f32x2_t v = {lo, hi}; const bf16x2_t b = __builtin_convertvector(v, bf16x2_t); return __builtin_bit_cast(unsigned, b); }
; #define VLOOP(t, N) for (int t##0_ = 2 * bid, t = min(t##0_ + vb, (N) - 1); t##0_ < (N); t##0_ += VG, t = min(t##0_ + vb, (N) - 1))
; template <int WT, class Epi>
; DEV void gemm_tile(const bf16_t* __restrict__ A, int lda, const bf16_t* __restrict__ Bt, int ldb, int K, unsigned char* lds, const Epi& epi) {
;     ...
;             for (int mi = 0; mi < FI; ++mi)
; #pragma unroll
;                 for (int ni = 0; ni < FI; ++ni) acc[mi][ni] = __builtin_amdgcn_mfma_f32_16x16x32_bf16(bfr[ni], af[mi], acc[mi][ni], 0, 0, 0);
;         }
;         nxt = cur; cur += STB; if (cur == NSTG * STB) cur = 0;
;     }
;     ...
;     __syncthreads();
;     if constexpr (Epi::STAGE) {
;         constexpr int RB = 4 * WT, CPR = RB / 16;
; #pragma unroll
;         for (int mi = 0; mi < FI; ++mi)
; #pragma unroll
;             for (int ni = 0; ni < FI; ++ni) {
;                 const int row = wr * WT + mi * 16 + fr, col = wc * WT + ni * 16 + fq * 4;
;                 const f32x4 v = epi.xform(row, col, acc[mi][ni]);
;                 uint2 w; w.x = cvt_pk_bf16(v[0], v[1]); w.y = cvt_pk_bf16(v[2], v[3]);
;                 *(uint2*)(lds + row * RB + ((((col >> 3) ^ (row & (CPR - 1))) << 4) | (((col >> 2) & 1) << 3))) = w;
;             }
;         __syncthreads();
; #pragma unroll
;         for (int i = 0; i < (2 * WT * CPR) / 256; ++i) {
;             const int idx = tid + 256 * i, row = idx / CPR, cp = idx % CPR, c = cp ^ (row & (CPR - 1));
;             const uint4 d = *(const uint4*)(lds + row * RB + (cp << 4));
;             *(uint4*)(epi.obase + (size_t)row * epi.old + c * 8) = epi.finish(row, c * 8, d);
;         }
;         __syncthreads();
;     } else {
; #pragma unroll
;         for (int mi = 0; mi < FI; ++mi)
; #pragma unroll
;             for (int ni = 0; ni < FI; ++ni) epi(wr * WT + mi * 16 + fr, wc * WT + ni * 16 + fq * 4, acc[mi][ni]);
; __global__ void __launch_bounds__(512) hymba_fwd(Params p) {
;     ...
;         VLOOP(t, NS1) { const int bhd = t >> 5, v = t & 31, mt = v >> 1, nt = v & 1, b = bhd >> 2, hd = bhd & 3;
	v_mfma_f32_16x16x32_bf16 v[74:77], v[70:73], v[82:85], v[74:77]
	v_mfma_f32_16x16x32_bf16 v[78:81], v[86:89], v[82:85], v[78:81]
	v_mfma_f32_16x16x32_bf16 v[8:11], v[90:93], v[82:85], v[8:11]
	v_mfma_f32_16x16x32_bf16 v[66:69], v[94:97], v[82:85], v[66:69]
	ds_read_b128 v[82:85], v13 offset:38912
	v_lshlrev_b32_e32 v13, 2, v7
	v_ashrrev_i32_e32 v7, 31, v6
	s_waitcnt lgkmcnt(0)
	v_mfma_f32_16x16x32_bf16 v[16:19], v[70:73], v[82:85], v[18:21]
	ds_read_b128 v[70:73], v15 offset:49152
	v_lshlrev_b64 v[106:107], 12, v[6:7]
	v_lshl_add_u64 v[6:7], v[104:105], 0, s[4:5]
	v_mfma_f32_16x16x32_bf16 v[20:23], v[86:89], v[82:85], v[22:25]
	ds_read_b128 v[86:89], v15 offset:51200
	v_lshl_or_b32 v4, v4, 4, v13
	v_mfma_f32_16x16x32_bf16 v[38:41], v[90:93], v[82:85], v[38:41]
	ds_read_b128 v[90:93], v15 offset:53248
	v_mfma_f32_16x16x32_bf16 v[46:49], v[94:97], v[82:85], v[46:49]
	ds_read_b128 v[94:97], v15 offset:55296
	ds_read_b128 v[82:85], v14 offset:32768
	s_waitcnt lgkmcnt(0)
	v_mfma_f32_16x16x32_bf16 v[34:37], v[70:73], v[82:85], v[34:37]
	v_mfma_f32_16x16x32_bf16 v[42:45], v[86:89], v[82:85], v[42:45]
	s_nop 6
	v_mul_f32_e64 v36, v36, s74
	v_mul_f32_e64 v37, v37, s74
	v_pk_mul_f32 v[34:35], v[34:35], s[74:75] op_sel_hi:[1,0]
	v_mfma_f32_16x16x32_bf16 v[50:53], v[90:93], v[82:85], v[50:53]
	v_mfma_f32_16x16x32_bf16 v[24:27], v[94:97], v[82:85], v[26:29]
	ds_read_b128 v[82:85], v14 offset:34816
	v_pk_mul_f32 v[44:45], v[44:45], s[74:75] op_sel_hi:[1,0]
	v_pk_mul_f32 v[42:43], v[42:43], s[74:75] op_sel_hi:[1,0]
	s_waitcnt lgkmcnt(0)
	v_mfma_f32_16x16x32_bf16 v[54:57], v[70:73], v[82:85], v[54:57]
	s_nop 1
	v_mul_f32_e64 v52, v52, s74
	v_mul_f32_e64 v53, v53, s74
	v_pk_mul_f32 v[50:51], v[50:51], s[74:75] op_sel_hi:[1,0]
	v_pk_mul_f32 v[26:27], v[26:27], s[74:75] op_sel_hi:[1,0]
	v_mfma_f32_16x16x32_bf16 v[58:61], v[86:89], v[82:85], v[58:61]
	v_mul_f32_e64 v24, v24, s74
	v_mul_f32_e64 v25, v25, s74
	v_pk_mul_f32 v[56:57], v[56:57], s[74:75] op_sel_hi:[1,0]
	v_pk_mul_f32 v[54:55], v[54:55], s[74:75] op_sel_hi:[1,0]
	v_mfma_f32_16x16x32_bf16 v[62:65], v[90:93], v[82:85], v[62:65]
	v_mfma_f32_16x16x32_bf16 v[28:31], v[94:97], v[82:85], v[30:33]
	ds_read_b128 v[82:85], v14 offset:36864
	s_nop 0
	v_pk_mul_f32 v[60:61], v[60:61], s[74:75] op_sel_hi:[1,0]
	v_pk_mul_f32 v[58:59], v[58:59], s[74:75] op_sel_hi:[1,0]
	s_waitcnt lgkmcnt(0)
	v_mfma_f32_16x16x32_bf16 v[74:77], v[70:73], v[82:85], v[74:77]
	v_lshlrev_b64 v[32:33], 12, v[98:99]
	v_lshlrev_b64 v[98:99], 12, v[100:101]
	v_lshlrev_b64 v[100:101], 12, v[102:103]
	v_mfma_f32_16x16x32_bf16 v[78:81], v[86:89], v[82:85], v[78:81]
	v_lshl_add_u64 v[102:103], v[6:7], 0, s[78:79]
	v_lshl_add_u64 v[32:33], v[102:103], 0, v[32:33]
	v_pk_mul_f32 v[64:65], v[64:65], s[74:75] op_sel_hi:[1,0]
	v_mfma_f32_16x16x32_bf16 v[6:9], v[90:93], v[82:85], v[8:11]
	v_mul_f32_e64 v62, v62, s74
	v_mul_f32_e64 v63, v63, s74
	v_pk_mul_f32 v[30:31], v[30:31], s[74:75] op_sel_hi:[1,0]
	v_pk_mul_f32 v[28:29], v[28:29], s[74:75] op_sel_hi:[1,0]
	v_mfma_f32_16x16x32_bf16 v[66:69], v[94:97], v[82:85], v[66:69]
	ds_read_b128 v[82:85], v14 offset:38912
	v_lshl_add_u64 v[10:11], v[102:103], 0, v[106:107]
	v_lshl_add_u64 v[10:11], v[10:11], 0, v[4:5]
	s_waitcnt lgkmcnt(0)
	v_mfma_f32_16x16x32_bf16 v[14:17], v[70:73], v[82:85], v[16:19]
	v_lshl_add_u64 v[70:71], v[102:103], 0, v[98:99]
	v_lshl_add_u64 v[72:73], v[102:103], 0, v[100:101]
	v_mfma_f32_16x16x32_bf16 v[18:21], v[86:89], v[82:85], v[20:23]
	v_lshl_add_u64 v[86:87], v[72:73], 0, v[4:5]
	s_barrier
	v_mfma_f32_16x16x32_bf16 v[38:41], v[90:93], v[82:85], v[38:41]
	v_lshl_add_u64 v[22:23], v[32:33], 0, v[4:5]
	v_lshl_add_u64 v[32:33], v[70:71], 0, v[4:5]
	v_pk_mul_f32 v[72:73], v[76:77], s[74:75] op_sel_hi:[1,0]
	v_mfma_f32_16x16x32_bf16 v[46:49], v[94:97], v[82:85], v[46:49]
	v_mul_f32_e64 v70, v74, s74
	v_mul_f32_e64 v71, v75, s74
	v_pk_mul_f32 v[76:77], v[80:81], s[74:75] op_sel_hi:[1,0]
	v_pk_mul_f32 v[74:75], v[78:79], s[74:75] op_sel_hi:[1,0]
	v_pk_mul_f32 v[8:9], v[8:9], s[74:75] op_sel_hi:[1,0]
	v_pk_mul_f32 v[6:7], v[6:7], s[74:75] op_sel_hi:[1,0]
	v_pk_mul_f32 v[68:69], v[68:69], s[74:75] op_sel_hi:[1,0]
	v_pk_mul_f32 v[66:67], v[66:67], s[74:75] op_sel_hi:[1,0]
	v_pk_mul_f32 v[16:17], v[16:17], s[74:75] op_sel_hi:[1,0]
	v_pk_mul_f32 v[14:15], v[14:15], s[74:75] op_sel_hi:[1,0]
	v_pk_mul_f32 v[20:21], v[20:21], s[74:75] op_sel_hi:[1,0]
	v_pk_mul_f32 v[18:19], v[18:19], s[74:75] op_sel_hi:[1,0]
	v_pk_mul_f32 v[40:41], v[40:41], s[74:75] op_sel_hi:[1,0]
	v_pk_mul_f32 v[38:39], v[38:39], s[74:75] op_sel_hi:[1,0]
	v_pk_mul_f32 v[48:49], v[48:49], s[74:75] op_sel_hi:[1,0]
	v_pk_mul_f32 v[46:47], v[46:47], s[74:75] op_sel_hi:[1,0]
	global_store_dwordx4 v[10:11], v[34:37], off
	global_store_dwordx4 v[10:11], v[42:45], off offset:64
	global_store_dwordx4 v[10:11], v[50:53], off offset:128
	global_store_dwordx4 v[10:11], v[24:27], off offset:192
	global_store_dwordx4 v[22:23], v[54:57], off
	global_store_dwordx4 v[22:23], v[58:61], off offset:64
	global_store_dwordx4 v[22:23], v[62:65], off offset:128
	global_store_dwordx4 v[22:23], v[28:31], off offset:192
	global_store_dwordx4 v[32:33], v[70:73], off
	global_store_dwordx4 v[32:33], v[74:77], off offset:64
	global_store_dwordx4 v[32:33], v[6:9], off offset:128
	global_store_dwordx4 v[32:33], v[66:69], off offset:192
	global_store_dwordx4 v[86:87], v[14:17], off
	global_store_dwordx4 v[86:87], v[18:21], off offset:64
	global_store_dwordx4 v[86:87], v[38:41], off offset:128
	global_store_dwordx4 v[86:87], v[46:49], off offset:192
	s_cbranch_scc1 .LBB0_1295
	v_readlane_b32 s94, v252, 0
	v_readlane_b32 s95, v252, 1
	s_cmpk_lg_i32 s33, 0x100
	s_cbranch_scc1 .LBB0_1297
; DEV void store_bf4(bf16_t* p, f32x4 v) { uint2 w; w.x = cvt_pk_bf16(v[0], v[1]); w.y = cvt_pk_bf16(v[2], v[3]); *(uint2*)p = w; }
; DEV float wave_max(float v) {
; #pragma unroll
;     for (int o = 32; o >= 1; o >>= 1) v = fmaxf(v, __shfl_xor(v, o));
;     return v;
; __global__ void __launch_bounds__(512) hymba_fwd(Params p) {
;     ...
;     for (int r = bid * 8 + wid; r < TP * 4; r += G * 8) {
;         const f32x4 v = __builtin_nontemporal_load((const f32x4*)(sc + (size_t)r * 256 + lane * 4));
;         const float mx = wave_max(fmaxf(fmaxf(v[0], v[1]), fmaxf(v[2], v[3])));
;         f32x4 e; e[0] = __expf(v[0] - mx); e[1] = __expf(v[1] - mx); e[2] = __expf(v[2] - mx); e[3] = __expf(v[3] - mx);
;         const float inv = 1.f / wave_sum(e[0] + e[1] + e[2] + e[3]);
;         store_bf4(pb + (size_t)(r >> 2) * LDP + (r & 3) * 256 + lane * 4, e * inv);
	s_waitcnt vmcnt(0)
	s_barrier
	v_mbcnt_lo_u32_b32 v2, -1, 0
	v_mbcnt_hi_u32_b32 v2, -1, v2
	v_lshrrev_b32_e32 v6, 6, v0
	s_lshr_b32 s4, s2, 6
	s_lshl_b32 s4, s4, 11
	s_and_b32 s5, s2, 15
	s_lshl_b32 s5, s5, 7
	s_add_i32 s4, s4, s5
	s_bfe_u32 s5, s2, 0x20004
	v_xor_b32_e32 v8, 32, v2
	v_xor_b32_e32 v9, 16, v2
	v_xor_b32_e32 v10, 8, v2
	v_xor_b32_e32 v11, 4, v2
	v_xor_b32_e32 v12, 2, v2
	v_xor_b32_e32 v13, 1, v2
	v_lshlrev_b32_e32 v8, 2, v8
	v_lshlrev_b32_e32 v9, 2, v9
	v_lshlrev_b32_e32 v10, 2, v10
	v_lshlrev_b32_e32 v11, 2, v11
	v_lshlrev_b32_e32 v12, 2, v12
	v_lshlrev_b32_e32 v13, 2, v13
	v_add_u32_e32 v1, s4, v6
	s_lshl_b32 s6, s5, 10
	v_lshlrev_b32_e32 v14, 12, v1
	v_lshl_add_u32 v15, v2, 4, s6
	v_add_u32_e32 v14, v14, v15
	v_mov_b32_e32 v15, 0
	s_mov_b64 s[6:7], 0x1ef39000
	v_lshl_add_u64 v[4:5], v[158:159], 0, s[6:7]
	v_lshl_add_u64 v[4:5], v[4:5], 0, v[14:15]
	s_mov_b64 s[6:7], 0x20f39000
	v_lshl_add_u64 v[20:21], v[158:159], 0, s[6:7]
	s_movk_i32 s12, 0x880
	v_mad_i64_i32 v[20:21], s[16:17], v1, s12, v[20:21]
	s_lshl_b32 s6, s5, 9
	v_lshl_add_u32 v14, v2, 3, s6
	v_lshl_add_u64 v[20:21], v[20:21], 0, v[14:15]
	s_mov_b64 s[8:9], 0x8000
	s_mov_b64 s[10:11], 0x4400
	global_load_dwordx4 v[24:27], v[4:5], off nt
	v_lshl_add_u64 v[4:5], v[4:5], 0, s[8:9]
	global_load_dwordx4 v[28:31], v[4:5], off nt
	v_lshl_add_u64 v[4:5], v[4:5], 0, s[8:9]
	global_load_dwordx4 v[32:35], v[4:5], off nt
	v_lshl_add_u64 v[4:5], v[4:5], 0, s[8:9]
	global_load_dwordx4 v[36:39], v[4:5], off nt
	v_lshl_add_u64 v[4:5], v[4:5], 0, s[8:9]
	global_load_dwordx4 v[40:43], v[4:5], off nt
	v_lshl_add_u64 v[4:5], v[4:5], 0, s[8:9]
	global_load_dwordx4 v[44:47], v[4:5], off nt
	v_lshl_add_u64 v[4:5], v[4:5], 0, s[8:9]
	global_load_dwordx4 v[48:51], v[4:5], off nt
	v_lshl_add_u64 v[4:5], v[4:5], 0, s[8:9]
	global_load_dwordx4 v[52:55], v[4:5], off nt
	v_lshl_add_u64 v[4:5], v[4:5], 0, s[8:9]
	s_waitcnt vmcnt(4)
	v_max_f32_e32 v56, v27, v27
	v_max_f32_e32 v60, v26, v26
	v_max_f32_e32 v56, v60, v56
	v_max3_f32 v56, v24, v25, v56
	v_max_f32_e32 v57, v31, v31
	v_max_f32_e32 v61, v30, v30
	v_max_f32_e32 v57, v61, v57
	v_max3_f32 v57, v28, v29, v57
	v_max_f32_e32 v58, v35, v35
	v_max_f32_e32 v62, v34, v34
	v_max_f32_e32 v58, v62, v58
	v_max3_f32 v58, v32, v33, v58
	v_max_f32_e32 v59, v39, v39
	v_max_f32_e32 v63, v38, v38
	v_max_f32_e32 v59, v63, v59
	v_max3_f32 v59, v36, v37, v59
	ds_bpermute_b32 v60, v8, v56
	ds_bpermute_b32 v61, v8, v57
	ds_bpermute_b32 v62, v8, v58
	ds_bpermute_b32 v63, v8, v59
	s_waitcnt lgkmcnt(3)
	v_max_f32_e32 v60, v60, v60
	v_max_f32_e32 v56, v56, v60
	s_waitcnt lgkmcnt(2)
	v_max_f32_e32 v61, v61, v61
	v_max_f32_e32 v57, v57, v61
	s_waitcnt lgkmcnt(1)
	v_max_f32_e32 v62, v62, v62
	v_max_f32_e32 v58, v58, v62
	s_waitcnt lgkmcnt(0)
	v_max_f32_e32 v63, v63, v63
	v_max_f32_e32 v59, v59, v63
	ds_bpermute_b32 v60, v9, v56
	ds_bpermute_b32 v61, v9, v57
	ds_bpermute_b32 v62, v9, v58
	ds_bpermute_b32 v63, v9, v59
	s_waitcnt lgkmcnt(3)
	v_max_f32_e32 v60, v60, v60
	v_max_f32_e32 v56, v56, v60
	s_waitcnt lgkmcnt(2)
	v_max_f32_e32 v61, v61, v61
	v_max_f32_e32 v57, v57, v61
	s_waitcnt lgkmcnt(1)
	v_max_f32_e32 v62, v62, v62
	v_max_f32_e32 v58, v58, v62
	s_waitcnt lgkmcnt(0)
	v_max_f32_e32 v63, v63, v63
	v_max_f32_e32 v59, v59, v63
	ds_bpermute_b32 v60, v10, v56
	ds_bpermute_b32 v61, v10, v57
	ds_bpermute_b32 v62, v10, v58
	ds_bpermute_b32 v63, v10, v59
	s_waitcnt lgkmcnt(3)
	v_max_f32_e32 v60, v60, v60
	v_max_f32_e32 v56, v56, v60
	s_waitcnt lgkmcnt(2)
	v_max_f32_e32 v61, v61, v61
	v_max_f32_e32 v57, v57, v61
	s_waitcnt lgkmcnt(1)
	v_max_f32_e32 v62, v62, v62
	v_max_f32_e32 v58, v58, v62
	s_waitcnt lgkmcnt(0)
	v_max_f32_e32 v63, v63, v63
	v_max_f32_e32 v59, v59, v63
	ds_bpermute_b32 v60, v11, v56
	ds_bpermute_b32 v61, v11, v57
	ds_bpermute_b32 v62, v11, v58
	ds_bpermute_b32 v63, v11, v59
	s_waitcnt lgkmcnt(3)
	v_max_f32_e32 v60, v60, v60
	v_max_f32_e32 v56, v56, v60
	s_waitcnt lgkmcnt(2)
	v_max_f32_e32 v61, v61, v61
	v_max_f32_e32 v57, v57, v61
	s_waitcnt lgkmcnt(1)
	v_max_f32_e32 v62, v62, v62
	v_max_f32_e32 v58, v58, v62
	s_waitcnt lgkmcnt(0)
	v_max_f32_e32 v63, v63, v63
	v_max_f32_e32 v59, v59, v63
	ds_bpermute_b32 v60, v12, v56
	ds_bpermute_b32 v61, v12, v57
	ds_bpermute_b32 v62, v12, v58
	ds_bpermute_b32 v63, v12, v59
	s_waitcnt lgkmcnt(3)
	v_max_f32_e32 v60, v60, v60
	v_max_f32_e32 v56, v56, v60
	s_waitcnt lgkmcnt(2)
	v_max_f32_e32 v61, v61, v61
	v_max_f32_e32 v57, v57, v61
	s_waitcnt lgkmcnt(1)
	v_max_f32_e32 v62, v62, v62
	v_max_f32_e32 v58, v58, v62
	s_waitcnt lgkmcnt(0)
	v_max_f32_e32 v63, v63, v63
	v_max_f32_e32 v59, v59, v63
	ds_bpermute_b32 v60, v13, v56
	ds_bpermute_b32 v61, v13, v57
	ds_bpermute_b32 v62, v13, v58
	ds_bpermute_b32 v63, v13, v59
	s_waitcnt lgkmcnt(3)
	v_max_f32_e32 v60, v60, v60
	v_max_f32_e32 v56, v56, v60
	s_waitcnt lgkmcnt(2)
	v_max_f32_e32 v61, v61, v61
	v_max_f32_e32 v57, v57, v61
	s_waitcnt lgkmcnt(1)
	v_max_f32_e32 v62, v62, v62
	v_max_f32_e32 v58, v58, v62
	s_waitcnt lgkmcnt(0)
; DEV void store_bf4(bf16_t* p, f32x4 v) { uint2 w; w.x = cvt_pk_bf16(v[0], v[1]); w.y = cvt_pk_bf16(v[2], v[3]); *(uint2*)p = w; }
; DEV float wave_sum(float v) {
; #pragma unroll
;     for (int o = 32; o >= 1; o >>= 1) v += __shfl_xor(v, o);
;     return v;
; __global__ void __launch_bounds__(512) hymba_fwd(Params p) {
;     ...
;         const f32x4 v = __builtin_nontemporal_load((const f32x4*)(sc + (size_t)r * 256 + lane * 4));
;         const float mx = wave_max(fmaxf(fmaxf(v[0], v[1]), fmaxf(v[2], v[3])));
;         f32x4 e; e[0] = __expf(v[0] - mx); e[1] = __expf(v[1] - mx); e[2] = __expf(v[2] - mx); e[3] = __expf(v[3] - mx);
;         const float inv = 1.f / wave_sum(e[0] + e[1] + e[2] + e[3]);
;         store_bf4(pb + (size_t)(r >> 2) * LDP + (r & 3) * 256 + lane * 4, e * inv);
	v_max_f32_e32 v63, v63, v63
	v_max_f32_e32 v59, v59, v63
	v_sub_f32_e32 v24, v24, v56
	v_sub_f32_e32 v25, v25, v56
	v_sub_f32_e32 v26, v26, v56
	v_sub_f32_e32 v27, v27, v56
	v_mul_f32_e32 v24, 0x3fb8aa3b, v24
	v_mul_f32_e32 v25, 0x3fb8aa3b, v25
	v_mul_f32_e32 v26, 0x3fb8aa3b, v26
	v_mul_f32_e32 v27, 0x3fb8aa3b, v27
	v_sub_f32_e32 v28, v28, v57
	v_sub_f32_e32 v29, v29, v57
	v_sub_f32_e32 v30, v30, v57
	v_sub_f32_e32 v31, v31, v57
	v_mul_f32_e32 v28, 0x3fb8aa3b, v28
	v_mul_f32_e32 v29, 0x3fb8aa3b, v29
	v_mul_f32_e32 v30, 0x3fb8aa3b, v30
	v_mul_f32_e32 v31, 0x3fb8aa3b, v31
	v_sub_f32_e32 v32, v32, v58
	v_sub_f32_e32 v33, v33, v58
	v_sub_f32_e32 v34, v34, v58
	v_sub_f32_e32 v35, v35, v58
	v_mul_f32_e32 v32, 0x3fb8aa3b, v32
	v_mul_f32_e32 v33, 0x3fb8aa3b, v33
	v_mul_f32_e32 v34, 0x3fb8aa3b, v34
	v_mul_f32_e32 v35, 0x3fb8aa3b, v35
	v_sub_f32_e32 v36, v36, v59
	v_sub_f32_e32 v37, v37, v59
	v_sub_f32_e32 v38, v38, v59
	v_sub_f32_e32 v39, v39, v59
	v_mul_f32_e32 v36, 0x3fb8aa3b, v36
	v_mul_f32_e32 v37, 0x3fb8aa3b, v37
	v_mul_f32_e32 v38, 0x3fb8aa3b, v38
	v_mul_f32_e32 v39, 0x3fb8aa3b, v39
	v_exp_f32_e32 v24, v24
	v_exp_f32_e32 v25, v25
	v_exp_f32_e32 v26, v26
	v_exp_f32_e32 v27, v27
	v_exp_f32_e32 v28, v28
	v_exp_f32_e32 v29, v29
	v_exp_f32_e32 v30, v30
	v_exp_f32_e32 v31, v31
	v_exp_f32_e32 v32, v32
	v_exp_f32_e32 v33, v33
	v_exp_f32_e32 v34, v34
	v_exp_f32_e32 v35, v35
	v_exp_f32_e32 v36, v36
	v_exp_f32_e32 v37, v37
	v_exp_f32_e32 v38, v38
	v_exp_f32_e32 v39, v39
	v_add_f32_e32 v56, v24, v25
	v_add_f32_e32 v56, v26, v56
	v_add_f32_e32 v56, v27, v56
	v_add_f32_e32 v57, v28, v29
	v_add_f32_e32 v57, v30, v57
	v_add_f32_e32 v57, v31, v57
	v_add_f32_e32 v58, v32, v33
	v_add_f32_e32 v58, v34, v58
	v_add_f32_e32 v58, v35, v58
	v_add_f32_e32 v59, v36, v37
	v_add_f32_e32 v59, v38, v59
	v_add_f32_e32 v59, v39, v59
	ds_bpermute_b32 v60, v8, v56
	ds_bpermute_b32 v61, v8, v57
	ds_bpermute_b32 v62, v8, v58
	ds_bpermute_b32 v63, v8, v59
	s_waitcnt lgkmcnt(3)
	v_add_f32_e32 v56, v56, v60
	s_waitcnt lgkmcnt(2)
	v_add_f32_e32 v57, v57, v61
	s_waitcnt lgkmcnt(1)
	v_add_f32_e32 v58, v58, v62
	s_waitcnt lgkmcnt(0)
	v_add_f32_e32 v59, v59, v63
	ds_bpermute_b32 v60, v9, v56
	ds_bpermute_b32 v61, v9, v57
	ds_bpermute_b32 v62, v9, v58
	ds_bpermute_b32 v63, v9, v59
	s_waitcnt lgkmcnt(3)
	v_add_f32_e32 v56, v56, v60
	s_waitcnt lgkmcnt(2)
	v_add_f32_e32 v57, v57, v61
	s_waitcnt lgkmcnt(1)
	v_add_f32_e32 v58, v58, v62
	s_waitcnt lgkmcnt(0)
	v_add_f32_e32 v59, v59, v63
	ds_bpermute_b32 v60, v10, v56
	ds_bpermute_b32 v61, v10, v57
	ds_bpermute_b32 v62, v10, v58
	ds_bpermute_b32 v63, v10, v59
	s_waitcnt lgkmcnt(3)
	v_add_f32_e32 v56, v56, v60
	s_waitcnt lgkmcnt(2)
	v_add_f32_e32 v57, v57, v61
	s_waitcnt lgkmcnt(1)
	v_add_f32_e32 v58, v58, v62
	s_waitcnt lgkmcnt(0)
	v_add_f32_e32 v59, v59, v63
	ds_bpermute_b32 v60, v11, v56
	ds_bpermute_b32 v61, v11, v57
	ds_bpermute_b32 v62, v11, v58
	ds_bpermute_b32 v63, v11, v59
	s_waitcnt lgkmcnt(3)
	v_add_f32_e32 v56, v56, v60
	s_waitcnt lgkmcnt(2)
	v_add_f32_e32 v57, v57, v61
	s_waitcnt lgkmcnt(1)
	v_add_f32_e32 v58, v58, v62
	s_waitcnt lgkmcnt(0)
	v_add_f32_e32 v59, v59, v63
	ds_bpermute_b32 v60, v12, v56
	ds_bpermute_b32 v61, v12, v57
	ds_bpermute_b32 v62, v12, v58
	ds_bpermute_b32 v63, v12, v59
	s_waitcnt lgkmcnt(3)
	v_add_f32_e32 v56, v56, v60
	s_waitcnt lgkmcnt(2)
	v_add_f32_e32 v57, v57, v61
	s_waitcnt lgkmcnt(1)
	v_add_f32_e32 v58, v58, v62
	s_waitcnt lgkmcnt(0)
	v_add_f32_e32 v59, v59, v63
	ds_bpermute_b32 v60, v13, v56
	ds_bpermute_b32 v61, v13, v57
	ds_bpermute_b32 v62, v13, v58
	ds_bpermute_b32 v63, v13, v59
	s_waitcnt lgkmcnt(3)
	v_add_f32_e32 v56, v56, v60
	s_waitcnt lgkmcnt(2)
	v_add_f32_e32 v57, v57, v61
	s_waitcnt lgkmcnt(1)
	v_add_f32_e32 v58, v58, v62
	s_waitcnt lgkmcnt(0)
	v_add_f32_e32 v59, v59, v63
	v_div_scale_f32 v64, s[16:17], v56, v56, 1.0
	v_rcp_f32_e32 v65, v64
	v_div_scale_f32 v66, vcc, 1.0, v56, 1.0
	v_fma_f32 v67, -v64, v65, 1.0
	v_fmac_f32_e32 v65, v67, v65
	v_mul_f32_e32 v67, v66, v65
	v_fma_f32 v68, -v64, v67, v66
	v_fmac_f32_e32 v67, v68, v65
	v_fma_f32 v64, -v64, v67, v66
	v_div_fmas_f32 v64, v64, v65, v67
	v_div_fixup_f32 v56, v64, v56, 1.0
	v_mul_f32_e32 v24, v24, v56
	v_mul_f32_e32 v25, v25, v56
	v_mul_f32_e32 v26, v26, v56
	v_mul_f32_e32 v27, v27, v56
	v_cvt_pk_bf16_f32 v24, v24, v25
	v_cvt_pk_bf16_f32 v25, v26, v27
	global_store_dwordx2 v[20:21], v[24:25], off
	v_lshl_add_u64 v[20:21], v[20:21], 0, s[10:11]
	v_div_scale_f32 v64, s[16:17], v57, v57, 1.0
	v_rcp_f32_e32 v65, v64
	v_div_scale_f32 v66, vcc, 1.0, v57, 1.0
	v_fma_f32 v67, -v64, v65, 1.0
	v_fmac_f32_e32 v65, v67, v65
	v_mul_f32_e32 v67, v66, v65
	v_fma_f32 v68, -v64, v67, v66
	v_fmac_f32_e32 v67, v68, v65
	v_fma_f32 v64, -v64, v67, v66
	v_div_fmas_f32 v64, v64, v65, v67
	v_div_fixup_f32 v57, v64, v57, 1.0
	v_mul_f32_e32 v28, v28, v57
	v_mul_f32_e32 v29, v29, v57
	v_mul_f32_e32 v30, v30, v57
	v_mul_f32_e32 v31, v31, v57
	v_cvt_pk_bf16_f32 v28, v28, v29
	v_cvt_pk_bf16_f32 v29, v30, v31
	global_store_dwordx2 v[20:21], v[28:29], off
	v_lshl_add_u64 v[20:21], v[20:21], 0, s[10:11]
	v_div_scale_f32 v64, s[16:17], v58, v58, 1.0
	v_rcp_f32_e32 v65, v64
	v_div_scale_f32 v66, vcc, 1.0, v58, 1.0
	v_fma_f32 v67, -v64, v65, 1.0
	v_fmac_f32_e32 v65, v67, v65
	v_mul_f32_e32 v67, v66, v65
	v_fma_f32 v68, -v64, v67, v66
	v_fmac_f32_e32 v67, v68, v65
	v_fma_f32 v64, -v64, v67, v66
	v_div_fmas_f32 v64, v64, v65, v67
	v_div_fixup_f32 v58, v64, v58, 1.0
	v_mul_f32_e32 v32, v32, v58
	v_mul_f32_e32 v33, v33, v58
	v_mul_f32_e32 v34, v34, v58
	v_mul_f32_e32 v35, v35, v58
	v_cvt_pk_bf16_f32 v32, v32, v33
	v_cvt_pk_bf16_f32 v33, v34, v35
	global_store_dwordx2 v[20:21], v[32:33], off
	v_lshl_add_u64 v[20:21], v[20:21], 0, s[10:11]
	v_div_scale_f32 v64, s[16:17], v59, v59, 1.0
	v_rcp_f32_e32 v65, v64
	v_div_scale_f32 v66, vcc, 1.0, v59, 1.0
	v_fma_f32 v67, -v64, v65, 1.0
	v_fmac_f32_e32 v65, v67, v65
	v_mul_f32_e32 v67, v66, v65
	v_fma_f32 v68, -v64, v67, v66
	v_fmac_f32_e32 v67, v68, v65
	v_fma_f32 v64, -v64, v67, v66
	v_div_fmas_f32 v64, v64, v65, v67
	v_div_fixup_f32 v59, v64, v59, 1.0
	v_mul_f32_e32 v36, v36, v59
	v_mul_f32_e32 v37, v37, v59
	v_mul_f32_e32 v38, v38, v59
	v_mul_f32_e32 v39, v39, v59
	v_cvt_pk_bf16_f32 v36, v36, v37
	v_cvt_pk_bf16_f32 v37, v38, v39
	global_store_dwordx2 v[20:21], v[36:37], off
	v_lshl_add_u64 v[20:21], v[20:21], 0, s[10:11]
	global_load_dwordx4 v[24:27], v[4:5], off nt
	v_lshl_add_u64 v[4:5], v[4:5], 0, s[8:9]
	global_load_dwordx4 v[28:31], v[4:5], off nt
	v_lshl_add_u64 v[4:5], v[4:5], 0, s[8:9]
	global_load_dwordx4 v[32:35], v[4:5], off nt
	v_lshl_add_u64 v[4:5], v[4:5], 0, s[8:9]
	global_load_dwordx4 v[36:39], v[4:5], off nt
	v_lshl_add_u64 v[4:5], v[4:5], 0, s[8:9]
	s_waitcnt vmcnt(8)
; DEV float wave_sum(float v) {
; #pragma unroll
;     for (int o = 32; o >= 1; o >>= 1) v += __shfl_xor(v, o);
;     return v;
; }
; DEV float wave_max(float v) {
; #pragma unroll
;     for (int o = 32; o >= 1; o >>= 1) v = fmaxf(v, __shfl_xor(v, o));
;     return v;
; __global__ void __launch_bounds__(512) hymba_fwd(Params p) {
;     ...
;         const f32x4 v = __builtin_nontemporal_load((const f32x4*)(sc + (size_t)r * 256 + lane * 4));
;         const float mx = wave_max(fmaxf(fmaxf(v[0], v[1]), fmaxf(v[2], v[3])));
;         f32x4 e; e[0] = __expf(v[0] - mx); e[1] = __expf(v[1] - mx); e[2] = __expf(v[2] - mx); e[3] = __expf(v[3] - mx);
;         const float inv = 1.f / wave_sum(e[0] + e[1] + e[2] + e[3]);
	v_max_f32_e32 v56, v43, v43
	v_max_f32_e32 v60, v42, v42
	v_max_f32_e32 v56, v60, v56
	v_max3_f32 v56, v40, v41, v56
	v_max_f32_e32 v57, v47, v47
	v_max_f32_e32 v61, v46, v46
	v_max_f32_e32 v57, v61, v57
	v_max3_f32 v57, v44, v45, v57
	v_max_f32_e32 v58, v51, v51
	v_max_f32_e32 v62, v50, v50
	v_max_f32_e32 v58, v62, v58
	v_max3_f32 v58, v48, v49, v58
	v_max_f32_e32 v59, v55, v55
	v_max_f32_e32 v63, v54, v54
	v_max_f32_e32 v59, v63, v59
	v_max3_f32 v59, v52, v53, v59
	ds_bpermute_b32 v60, v8, v56
	ds_bpermute_b32 v61, v8, v57
	ds_bpermute_b32 v62, v8, v58
	ds_bpermute_b32 v63, v8, v59
	s_waitcnt lgkmcnt(3)
	v_max_f32_e32 v60, v60, v60
	v_max_f32_e32 v56, v56, v60
	s_waitcnt lgkmcnt(2)
	v_max_f32_e32 v61, v61, v61
	v_max_f32_e32 v57, v57, v61
	s_waitcnt lgkmcnt(1)
	v_max_f32_e32 v62, v62, v62
	v_max_f32_e32 v58, v58, v62
	s_waitcnt lgkmcnt(0)
	v_max_f32_e32 v63, v63, v63
	v_max_f32_e32 v59, v59, v63
	ds_bpermute_b32 v60, v9, v56
	ds_bpermute_b32 v61, v9, v57
	ds_bpermute_b32 v62, v9, v58
	ds_bpermute_b32 v63, v9, v59
	s_waitcnt lgkmcnt(3)
	v_max_f32_e32 v60, v60, v60
	v_max_f32_e32 v56, v56, v60
	s_waitcnt lgkmcnt(2)
	v_max_f32_e32 v61, v61, v61
	v_max_f32_e32 v57, v57, v61
	s_waitcnt lgkmcnt(1)
	v_max_f32_e32 v62, v62, v62
	v_max_f32_e32 v58, v58, v62
	s_waitcnt lgkmcnt(0)
	v_max_f32_e32 v63, v63, v63
	v_max_f32_e32 v59, v59, v63
	ds_bpermute_b32 v60, v10, v56
	ds_bpermute_b32 v61, v10, v57
	ds_bpermute_b32 v62, v10, v58
	ds_bpermute_b32 v63, v10, v59
	s_waitcnt lgkmcnt(3)
	v_max_f32_e32 v60, v60, v60
	v_max_f32_e32 v56, v56, v60
	s_waitcnt lgkmcnt(2)
	v_max_f32_e32 v61, v61, v61
	v_max_f32_e32 v57, v57, v61
	s_waitcnt lgkmcnt(1)
	v_max_f32_e32 v62, v62, v62
	v_max_f32_e32 v58, v58, v62
	s_waitcnt lgkmcnt(0)
	v_max_f32_e32 v63, v63, v63
	v_max_f32_e32 v59, v59, v63
	ds_bpermute_b32 v60, v11, v56
	ds_bpermute_b32 v61, v11, v57
	ds_bpermute_b32 v62, v11, v58
	ds_bpermute_b32 v63, v11, v59
	s_waitcnt lgkmcnt(3)
	v_max_f32_e32 v60, v60, v60
	v_max_f32_e32 v56, v56, v60
	s_waitcnt lgkmcnt(2)
	v_max_f32_e32 v61, v61, v61
	v_max_f32_e32 v57, v57, v61
	s_waitcnt lgkmcnt(1)
	v_max_f32_e32 v62, v62, v62
	v_max_f32_e32 v58, v58, v62
	s_waitcnt lgkmcnt(0)
	v_max_f32_e32 v63, v63, v63
	v_max_f32_e32 v59, v59, v63
	ds_bpermute_b32 v60, v12, v56
	ds_bpermute_b32 v61, v12, v57
	ds_bpermute_b32 v62, v12, v58
	ds_bpermute_b32 v63, v12, v59
	s_waitcnt lgkmcnt(3)
	v_max_f32_e32 v60, v60, v60
	v_max_f32_e32 v56, v56, v60
	s_waitcnt lgkmcnt(2)
	v_max_f32_e32 v61, v61, v61
	v_max_f32_e32 v57, v57, v61
	s_waitcnt lgkmcnt(1)
	v_max_f32_e32 v62, v62, v62
	v_max_f32_e32 v58, v58, v62
	s_waitcnt lgkmcnt(0)
	v_max_f32_e32 v63, v63, v63
	v_max_f32_e32 v59, v59, v63
	ds_bpermute_b32 v60, v13, v56
	ds_bpermute_b32 v61, v13, v57
	ds_bpermute_b32 v62, v13, v58
	ds_bpermute_b32 v63, v13, v59
	s_waitcnt lgkmcnt(3)
	v_max_f32_e32 v60, v60, v60
	v_max_f32_e32 v56, v56, v60
	s_waitcnt lgkmcnt(2)
	v_max_f32_e32 v61, v61, v61
	v_max_f32_e32 v57, v57, v61
	s_waitcnt lgkmcnt(1)
	v_max_f32_e32 v62, v62, v62
	v_max_f32_e32 v58, v58, v62
	s_waitcnt lgkmcnt(0)
	v_max_f32_e32 v63, v63, v63
	v_max_f32_e32 v59, v59, v63
	v_sub_f32_e32 v40, v40, v56
	v_sub_f32_e32 v41, v41, v56
	v_sub_f32_e32 v42, v42, v56
	v_sub_f32_e32 v43, v43, v56
	v_mul_f32_e32 v40, 0x3fb8aa3b, v40
	v_mul_f32_e32 v41, 0x3fb8aa3b, v41
	v_mul_f32_e32 v42, 0x3fb8aa3b, v42
	v_mul_f32_e32 v43, 0x3fb8aa3b, v43
	v_sub_f32_e32 v44, v44, v57
	v_sub_f32_e32 v45, v45, v57
	v_sub_f32_e32 v46, v46, v57
	v_sub_f32_e32 v47, v47, v57
	v_mul_f32_e32 v44, 0x3fb8aa3b, v44
	v_mul_f32_e32 v45, 0x3fb8aa3b, v45
	v_mul_f32_e32 v46, 0x3fb8aa3b, v46
	v_mul_f32_e32 v47, 0x3fb8aa3b, v47
	v_sub_f32_e32 v48, v48, v58
	v_sub_f32_e32 v49, v49, v58
	v_sub_f32_e32 v50, v50, v58
	v_sub_f32_e32 v51, v51, v58
	v_mul_f32_e32 v48, 0x3fb8aa3b, v48
	v_mul_f32_e32 v49, 0x3fb8aa3b, v49
	v_mul_f32_e32 v50, 0x3fb8aa3b, v50
	v_mul_f32_e32 v51, 0x3fb8aa3b, v51
	v_sub_f32_e32 v52, v52, v59
	v_sub_f32_e32 v53, v53, v59
	v_sub_f32_e32 v54, v54, v59
	v_sub_f32_e32 v55, v55, v59
	v_mul_f32_e32 v52, 0x3fb8aa3b, v52
	v_mul_f32_e32 v53, 0x3fb8aa3b, v53
	v_mul_f32_e32 v54, 0x3fb8aa3b, v54
	v_mul_f32_e32 v55, 0x3fb8aa3b, v55
	v_exp_f32_e32 v40, v40
	v_exp_f32_e32 v41, v41
	v_exp_f32_e32 v42, v42
	v_exp_f32_e32 v43, v43
	v_exp_f32_e32 v44, v44
	v_exp_f32_e32 v45, v45
	v_exp_f32_e32 v46, v46
	v_exp_f32_e32 v47, v47
	v_exp_f32_e32 v48, v48
	v_exp_f32_e32 v49, v49
	v_exp_f32_e32 v50, v50
	v_exp_f32_e32 v51, v51
	v_exp_f32_e32 v52, v52
	v_exp_f32_e32 v53, v53
	v_exp_f32_e32 v54, v54
	v_exp_f32_e32 v55, v55
	v_add_f32_e32 v56, v40, v41
	v_add_f32_e32 v56, v42, v56
	v_add_f32_e32 v56, v43, v56
	v_add_f32_e32 v57, v44, v45
	v_add_f32_e32 v57, v46, v57
	v_add_f32_e32 v57, v47, v57
	v_add_f32_e32 v58, v48, v49
	v_add_f32_e32 v58, v50, v58
	v_add_f32_e32 v58, v51, v58
	v_add_f32_e32 v59, v52, v53
	v_add_f32_e32 v59, v54, v59
	v_add_f32_e32 v59, v55, v59
	ds_bpermute_b32 v60, v8, v56
	ds_bpermute_b32 v61, v8, v57
	ds_bpermute_b32 v62, v8, v58
	ds_bpermute_b32 v63, v8, v59
	s_waitcnt lgkmcnt(3)
	v_add_f32_e32 v56, v56, v60
	s_waitcnt lgkmcnt(2)
	v_add_f32_e32 v57, v57, v61
	s_waitcnt lgkmcnt(1)
	v_add_f32_e32 v58, v58, v62
	s_waitcnt lgkmcnt(0)
	v_add_f32_e32 v59, v59, v63
	ds_bpermute_b32 v60, v9, v56
	ds_bpermute_b32 v61, v9, v57
	ds_bpermute_b32 v62, v9, v58
	ds_bpermute_b32 v63, v9, v59
	s_waitcnt lgkmcnt(3)
	v_add_f32_e32 v56, v56, v60
	s_waitcnt lgkmcnt(2)
	v_add_f32_e32 v57, v57, v61
	s_waitcnt lgkmcnt(1)
	v_add_f32_e32 v58, v58, v62
	s_waitcnt lgkmcnt(0)
	v_add_f32_e32 v59, v59, v63
	ds_bpermute_b32 v60, v10, v56
	ds_bpermute_b32 v61, v10, v57
	ds_bpermute_b32 v62, v10, v58
	ds_bpermute_b32 v63, v10, v59
	s_waitcnt lgkmcnt(3)
; DEV void store_bf4(bf16_t* p, f32x4 v) { uint2 w; w.x = cvt_pk_bf16(v[0], v[1]); w.y = cvt_pk_bf16(v[2], v[3]); *(uint2*)p = w; }
; DEV float wave_max(float v) {
; #pragma unroll
;     for (int o = 32; o >= 1; o >>= 1) v = fmaxf(v, __shfl_xor(v, o));
;     return v;
; __global__ void __launch_bounds__(512) hymba_fwd(Params p) {
;     ...
;         const float mx = wave_max(fmaxf(fmaxf(v[0], v[1]), fmaxf(v[2], v[3])));
;         f32x4 e; e[0] = __expf(v[0] - mx); e[1] = __expf(v[1] - mx); e[2] = __expf(v[2] - mx); e[3] = __expf(v[3] - mx);
;         const float inv = 1.f / wave_sum(e[0] + e[1] + e[2] + e[3]);
;         store_bf4(pb + (size_t)(r >> 2) * LDP + (r & 3) * 256 + lane * 4, e * inv);
	v_add_f32_e32 v56, v56, v60
	s_waitcnt lgkmcnt(2)
	v_add_f32_e32 v57, v57, v61
	s_waitcnt lgkmcnt(1)
	v_add_f32_e32 v58, v58, v62
	s_waitcnt lgkmcnt(0)
	v_add_f32_e32 v59, v59, v63
	ds_bpermute_b32 v60, v11, v56
	ds_bpermute_b32 v61, v11, v57
	ds_bpermute_b32 v62, v11, v58
	ds_bpermute_b32 v63, v11, v59
	s_waitcnt lgkmcnt(3)
	v_add_f32_e32 v56, v56, v60
	s_waitcnt lgkmcnt(2)
	v_add_f32_e32 v57, v57, v61
	s_waitcnt lgkmcnt(1)
	v_add_f32_e32 v58, v58, v62
	s_waitcnt lgkmcnt(0)
	v_add_f32_e32 v59, v59, v63
	ds_bpermute_b32 v60, v12, v56
	ds_bpermute_b32 v61, v12, v57
	ds_bpermute_b32 v62, v12, v58
	ds_bpermute_b32 v63, v12, v59
	s_waitcnt lgkmcnt(3)
	v_add_f32_e32 v56, v56, v60
	s_waitcnt lgkmcnt(2)
	v_add_f32_e32 v57, v57, v61
	s_waitcnt lgkmcnt(1)
	v_add_f32_e32 v58, v58, v62
	s_waitcnt lgkmcnt(0)
	v_add_f32_e32 v59, v59, v63
	ds_bpermute_b32 v60, v13, v56
	ds_bpermute_b32 v61, v13, v57
	ds_bpermute_b32 v62, v13, v58
	ds_bpermute_b32 v63, v13, v59
	s_waitcnt lgkmcnt(3)
	v_add_f32_e32 v56, v56, v60
	s_waitcnt lgkmcnt(2)
	v_add_f32_e32 v57, v57, v61
	s_waitcnt lgkmcnt(1)
	v_add_f32_e32 v58, v58, v62
	s_waitcnt lgkmcnt(0)
	v_add_f32_e32 v59, v59, v63
	v_div_scale_f32 v64, s[16:17], v56, v56, 1.0
	v_rcp_f32_e32 v65, v64
	v_div_scale_f32 v66, vcc, 1.0, v56, 1.0
	v_fma_f32 v67, -v64, v65, 1.0
	v_fmac_f32_e32 v65, v67, v65
	v_mul_f32_e32 v67, v66, v65
	v_fma_f32 v68, -v64, v67, v66
	v_fmac_f32_e32 v67, v68, v65
	v_fma_f32 v64, -v64, v67, v66
	v_div_fmas_f32 v64, v64, v65, v67
	v_div_fixup_f32 v56, v64, v56, 1.0
	v_mul_f32_e32 v40, v40, v56
	v_mul_f32_e32 v41, v41, v56
	v_mul_f32_e32 v42, v42, v56
	v_mul_f32_e32 v43, v43, v56
	v_cvt_pk_bf16_f32 v40, v40, v41
	v_cvt_pk_bf16_f32 v41, v42, v43
	global_store_dwordx2 v[20:21], v[40:41], off
	v_lshl_add_u64 v[20:21], v[20:21], 0, s[10:11]
	v_div_scale_f32 v64, s[16:17], v57, v57, 1.0
	v_rcp_f32_e32 v65, v64
	v_div_scale_f32 v66, vcc, 1.0, v57, 1.0
	v_fma_f32 v67, -v64, v65, 1.0
	v_fmac_f32_e32 v65, v67, v65
	v_mul_f32_e32 v67, v66, v65
	v_fma_f32 v68, -v64, v67, v66
	v_fmac_f32_e32 v67, v68, v65
	v_fma_f32 v64, -v64, v67, v66
	v_div_fmas_f32 v64, v64, v65, v67
	v_div_fixup_f32 v57, v64, v57, 1.0
	v_mul_f32_e32 v44, v44, v57
	v_mul_f32_e32 v45, v45, v57
	v_mul_f32_e32 v46, v46, v57
	v_mul_f32_e32 v47, v47, v57
	v_cvt_pk_bf16_f32 v44, v44, v45
	v_cvt_pk_bf16_f32 v45, v46, v47
	global_store_dwordx2 v[20:21], v[44:45], off
	v_lshl_add_u64 v[20:21], v[20:21], 0, s[10:11]
	v_div_scale_f32 v64, s[16:17], v58, v58, 1.0
	v_rcp_f32_e32 v65, v64
	v_div_scale_f32 v66, vcc, 1.0, v58, 1.0
	v_fma_f32 v67, -v64, v65, 1.0
	v_fmac_f32_e32 v65, v67, v65
	v_mul_f32_e32 v67, v66, v65
	v_fma_f32 v68, -v64, v67, v66
	v_fmac_f32_e32 v67, v68, v65
	v_fma_f32 v64, -v64, v67, v66
	v_div_fmas_f32 v64, v64, v65, v67
	v_div_fixup_f32 v58, v64, v58, 1.0
	v_mul_f32_e32 v48, v48, v58
	v_mul_f32_e32 v49, v49, v58
	v_mul_f32_e32 v50, v50, v58
	v_mul_f32_e32 v51, v51, v58
	v_cvt_pk_bf16_f32 v48, v48, v49
	v_cvt_pk_bf16_f32 v49, v50, v51
	global_store_dwordx2 v[20:21], v[48:49], off
	v_lshl_add_u64 v[20:21], v[20:21], 0, s[10:11]
	v_div_scale_f32 v64, s[16:17], v59, v59, 1.0
	v_rcp_f32_e32 v65, v64
	v_div_scale_f32 v66, vcc, 1.0, v59, 1.0
	v_fma_f32 v67, -v64, v65, 1.0
	v_fmac_f32_e32 v65, v67, v65
	v_mul_f32_e32 v67, v66, v65
	v_fma_f32 v68, -v64, v67, v66
	v_fmac_f32_e32 v67, v68, v65
	v_fma_f32 v64, -v64, v67, v66
	v_div_fmas_f32 v64, v64, v65, v67
	v_div_fixup_f32 v59, v64, v59, 1.0
	v_mul_f32_e32 v52, v52, v59
	v_mul_f32_e32 v53, v53, v59
	v_mul_f32_e32 v54, v54, v59
	v_mul_f32_e32 v55, v55, v59
	v_cvt_pk_bf16_f32 v52, v52, v53
	v_cvt_pk_bf16_f32 v53, v54, v55
	global_store_dwordx2 v[20:21], v[52:53], off
	v_lshl_add_u64 v[20:21], v[20:21], 0, s[10:11]
	global_load_dwordx4 v[40:43], v[4:5], off nt
	v_lshl_add_u64 v[4:5], v[4:5], 0, s[8:9]
	global_load_dwordx4 v[44:47], v[4:5], off nt
	v_lshl_add_u64 v[4:5], v[4:5], 0, s[8:9]
	global_load_dwordx4 v[48:51], v[4:5], off nt
	v_lshl_add_u64 v[4:5], v[4:5], 0, s[8:9]
	global_load_dwordx4 v[52:55], v[4:5], off nt
	v_lshl_add_u64 v[4:5], v[4:5], 0, s[8:9]
	s_waitcnt vmcnt(8)
	v_max_f32_e32 v56, v27, v27
	v_max_f32_e32 v60, v26, v26
	v_max_f32_e32 v56, v60, v56
	v_max3_f32 v56, v24, v25, v56
	v_max_f32_e32 v57, v31, v31
	v_max_f32_e32 v61, v30, v30
	v_max_f32_e32 v57, v61, v57
	v_max3_f32 v57, v28, v29, v57
	v_max_f32_e32 v58, v35, v35
	v_max_f32_e32 v62, v34, v34
	v_max_f32_e32 v58, v62, v58
	v_max3_f32 v58, v32, v33, v58
	v_max_f32_e32 v59, v39, v39
	v_max_f32_e32 v63, v38, v38
	v_max_f32_e32 v59, v63, v59
	v_max3_f32 v59, v36, v37, v59
	ds_bpermute_b32 v60, v8, v56
	ds_bpermute_b32 v61, v8, v57
	ds_bpermute_b32 v62, v8, v58
	ds_bpermute_b32 v63, v8, v59
	s_waitcnt lgkmcnt(3)
	v_max_f32_e32 v60, v60, v60
	v_max_f32_e32 v56, v56, v60
	s_waitcnt lgkmcnt(2)
	v_max_f32_e32 v61, v61, v61
	v_max_f32_e32 v57, v57, v61
	s_waitcnt lgkmcnt(1)
	v_max_f32_e32 v62, v62, v62
	v_max_f32_e32 v58, v58, v62
	s_waitcnt lgkmcnt(0)
	v_max_f32_e32 v63, v63, v63
	v_max_f32_e32 v59, v59, v63
	ds_bpermute_b32 v60, v9, v56
	ds_bpermute_b32 v61, v9, v57
	ds_bpermute_b32 v62, v9, v58
	ds_bpermute_b32 v63, v9, v59
	s_waitcnt lgkmcnt(3)
	v_max_f32_e32 v60, v60, v60
	v_max_f32_e32 v56, v56, v60
	s_waitcnt lgkmcnt(2)
	v_max_f32_e32 v61, v61, v61
	v_max_f32_e32 v57, v57, v61
	s_waitcnt lgkmcnt(1)
	v_max_f32_e32 v62, v62, v62
	v_max_f32_e32 v58, v58, v62
	s_waitcnt lgkmcnt(0)
	v_max_f32_e32 v63, v63, v63
	v_max_f32_e32 v59, v59, v63
	ds_bpermute_b32 v60, v10, v56
	ds_bpermute_b32 v61, v10, v57
	ds_bpermute_b32 v62, v10, v58
	ds_bpermute_b32 v63, v10, v59
	s_waitcnt lgkmcnt(3)
	v_max_f32_e32 v60, v60, v60
	v_max_f32_e32 v56, v56, v60
	s_waitcnt lgkmcnt(2)
; DEV float wave_sum(float v) {
; #pragma unroll
;     for (int o = 32; o >= 1; o >>= 1) v += __shfl_xor(v, o);
;     return v;
; }
; DEV float wave_max(float v) {
; #pragma unroll
;     for (int o = 32; o >= 1; o >>= 1) v = fmaxf(v, __shfl_xor(v, o));
;     return v;
; __global__ void __launch_bounds__(512) hymba_fwd(Params p) {
;     ...
;         const float mx = wave_max(fmaxf(fmaxf(v[0], v[1]), fmaxf(v[2], v[3])));
;         f32x4 e; e[0] = __expf(v[0] - mx); e[1] = __expf(v[1] - mx); e[2] = __expf(v[2] - mx); e[3] = __expf(v[3] - mx);
;         const float inv = 1.f / wave_sum(e[0] + e[1] + e[2] + e[3]);
	v_max_f32_e32 v61, v61, v61
	v_max_f32_e32 v57, v57, v61
	s_waitcnt lgkmcnt(1)
	v_max_f32_e32 v62, v62, v62
	v_max_f32_e32 v58, v58, v62
	s_waitcnt lgkmcnt(0)
	v_max_f32_e32 v63, v63, v63
	v_max_f32_e32 v59, v59, v63
	ds_bpermute_b32 v60, v11, v56
	ds_bpermute_b32 v61, v11, v57
	ds_bpermute_b32 v62, v11, v58
	ds_bpermute_b32 v63, v11, v59
	s_waitcnt lgkmcnt(3)
	v_max_f32_e32 v60, v60, v60
	v_max_f32_e32 v56, v56, v60
	s_waitcnt lgkmcnt(2)
	v_max_f32_e32 v61, v61, v61
	v_max_f32_e32 v57, v57, v61
	s_waitcnt lgkmcnt(1)
	v_max_f32_e32 v62, v62, v62
	v_max_f32_e32 v58, v58, v62
	s_waitcnt lgkmcnt(0)
	v_max_f32_e32 v63, v63, v63
	v_max_f32_e32 v59, v59, v63
	ds_bpermute_b32 v60, v12, v56
	ds_bpermute_b32 v61, v12, v57
	ds_bpermute_b32 v62, v12, v58
	ds_bpermute_b32 v63, v12, v59
	s_waitcnt lgkmcnt(3)
	v_max_f32_e32 v60, v60, v60
	v_max_f32_e32 v56, v56, v60
	s_waitcnt lgkmcnt(2)
	v_max_f32_e32 v61, v61, v61
	v_max_f32_e32 v57, v57, v61
	s_waitcnt lgkmcnt(1)
	v_max_f32_e32 v62, v62, v62
	v_max_f32_e32 v58, v58, v62
	s_waitcnt lgkmcnt(0)
	v_max_f32_e32 v63, v63, v63
	v_max_f32_e32 v59, v59, v63
	ds_bpermute_b32 v60, v13, v56
	ds_bpermute_b32 v61, v13, v57
	ds_bpermute_b32 v62, v13, v58
	ds_bpermute_b32 v63, v13, v59
	s_waitcnt lgkmcnt(3)
	v_max_f32_e32 v60, v60, v60
	v_max_f32_e32 v56, v56, v60
	s_waitcnt lgkmcnt(2)
	v_max_f32_e32 v61, v61, v61
	v_max_f32_e32 v57, v57, v61
	s_waitcnt lgkmcnt(1)
	v_max_f32_e32 v62, v62, v62
	v_max_f32_e32 v58, v58, v62
	s_waitcnt lgkmcnt(0)
	v_max_f32_e32 v63, v63, v63
	v_max_f32_e32 v59, v59, v63
	v_sub_f32_e32 v24, v24, v56
	v_sub_f32_e32 v25, v25, v56
	v_sub_f32_e32 v26, v26, v56
	v_sub_f32_e32 v27, v27, v56
	v_mul_f32_e32 v24, 0x3fb8aa3b, v24
	v_mul_f32_e32 v25, 0x3fb8aa3b, v25
	v_mul_f32_e32 v26, 0x3fb8aa3b, v26
	v_mul_f32_e32 v27, 0x3fb8aa3b, v27
	v_sub_f32_e32 v28, v28, v57
	v_sub_f32_e32 v29, v29, v57
	v_sub_f32_e32 v30, v30, v57
	v_sub_f32_e32 v31, v31, v57
	v_mul_f32_e32 v28, 0x3fb8aa3b, v28
	v_mul_f32_e32 v29, 0x3fb8aa3b, v29
	v_mul_f32_e32 v30, 0x3fb8aa3b, v30
	v_mul_f32_e32 v31, 0x3fb8aa3b, v31
	v_sub_f32_e32 v32, v32, v58
	v_sub_f32_e32 v33, v33, v58
	v_sub_f32_e32 v34, v34, v58
	v_sub_f32_e32 v35, v35, v58
	v_mul_f32_e32 v32, 0x3fb8aa3b, v32
	v_mul_f32_e32 v33, 0x3fb8aa3b, v33
	v_mul_f32_e32 v34, 0x3fb8aa3b, v34
	v_mul_f32_e32 v35, 0x3fb8aa3b, v35
	v_sub_f32_e32 v36, v36, v59
	v_sub_f32_e32 v37, v37, v59
	v_sub_f32_e32 v38, v38, v59
	v_sub_f32_e32 v39, v39, v59
	v_mul_f32_e32 v36, 0x3fb8aa3b, v36
	v_mul_f32_e32 v37, 0x3fb8aa3b, v37
	v_mul_f32_e32 v38, 0x3fb8aa3b, v38
	v_mul_f32_e32 v39, 0x3fb8aa3b, v39
	v_exp_f32_e32 v24, v24
	v_exp_f32_e32 v25, v25
	v_exp_f32_e32 v26, v26
	v_exp_f32_e32 v27, v27
	v_exp_f32_e32 v28, v28
	v_exp_f32_e32 v29, v29
	v_exp_f32_e32 v30, v30
	v_exp_f32_e32 v31, v31
	v_exp_f32_e32 v32, v32
	v_exp_f32_e32 v33, v33
	v_exp_f32_e32 v34, v34
	v_exp_f32_e32 v35, v35
	v_exp_f32_e32 v36, v36
	v_exp_f32_e32 v37, v37
	v_exp_f32_e32 v38, v38
	v_exp_f32_e32 v39, v39
	v_add_f32_e32 v56, v24, v25
	v_add_f32_e32 v56, v26, v56
	v_add_f32_e32 v56, v27, v56
	v_add_f32_e32 v57, v28, v29
	v_add_f32_e32 v57, v30, v57
	v_add_f32_e32 v57, v31, v57
	v_add_f32_e32 v58, v32, v33
	v_add_f32_e32 v58, v34, v58
	v_add_f32_e32 v58, v35, v58
	v_add_f32_e32 v59, v36, v37
	v_add_f32_e32 v59, v38, v59
	v_add_f32_e32 v59, v39, v59
	ds_bpermute_b32 v60, v8, v56
	ds_bpermute_b32 v61, v8, v57
	ds_bpermute_b32 v62, v8, v58
	ds_bpermute_b32 v63, v8, v59
	s_waitcnt lgkmcnt(3)
	v_add_f32_e32 v56, v56, v60
	s_waitcnt lgkmcnt(2)
	v_add_f32_e32 v57, v57, v61
	s_waitcnt lgkmcnt(1)
	v_add_f32_e32 v58, v58, v62
	s_waitcnt lgkmcnt(0)
	v_add_f32_e32 v59, v59, v63
	ds_bpermute_b32 v60, v9, v56
	ds_bpermute_b32 v61, v9, v57
	ds_bpermute_b32 v62, v9, v58
	ds_bpermute_b32 v63, v9, v59
	s_waitcnt lgkmcnt(3)
	v_add_f32_e32 v56, v56, v60
	s_waitcnt lgkmcnt(2)
	v_add_f32_e32 v57, v57, v61
	s_waitcnt lgkmcnt(1)
	v_add_f32_e32 v58, v58, v62
	s_waitcnt lgkmcnt(0)
	v_add_f32_e32 v59, v59, v63
	ds_bpermute_b32 v60, v10, v56
	ds_bpermute_b32 v61, v10, v57
	ds_bpermute_b32 v62, v10, v58
	ds_bpermute_b32 v63, v10, v59
	s_waitcnt lgkmcnt(3)
	v_add_f32_e32 v56, v56, v60
	s_waitcnt lgkmcnt(2)
	v_add_f32_e32 v57, v57, v61
	s_waitcnt lgkmcnt(1)
	v_add_f32_e32 v58, v58, v62
	s_waitcnt lgkmcnt(0)
	v_add_f32_e32 v59, v59, v63
	ds_bpermute_b32 v60, v11, v56
	ds_bpermute_b32 v61, v11, v57
	ds_bpermute_b32 v62, v11, v58
	ds_bpermute_b32 v63, v11, v59
	s_waitcnt lgkmcnt(3)
	v_add_f32_e32 v56, v56, v60
	s_waitcnt lgkmcnt(2)
	v_add_f32_e32 v57, v57, v61
	s_waitcnt lgkmcnt(1)
	v_add_f32_e32 v58, v58, v62
	s_waitcnt lgkmcnt(0)
	v_add_f32_e32 v59, v59, v63
	ds_bpermute_b32 v60, v12, v56
	ds_bpermute_b32 v61, v12, v57
	ds_bpermute_b32 v62, v12, v58
	ds_bpermute_b32 v63, v12, v59
	s_waitcnt lgkmcnt(3)
	v_add_f32_e32 v56, v56, v60
	s_waitcnt lgkmcnt(2)
	v_add_f32_e32 v57, v57, v61
	s_waitcnt lgkmcnt(1)
	v_add_f32_e32 v58, v58, v62
	s_waitcnt lgkmcnt(0)
	v_add_f32_e32 v59, v59, v63
	ds_bpermute_b32 v60, v13, v56
	ds_bpermute_b32 v61, v13, v57
	ds_bpermute_b32 v62, v13, v58
	ds_bpermute_b32 v63, v13, v59
	s_waitcnt lgkmcnt(3)
	v_add_f32_e32 v56, v56, v60
	s_waitcnt lgkmcnt(2)
	v_add_f32_e32 v57, v57, v61
	s_waitcnt lgkmcnt(1)
	v_add_f32_e32 v58, v58, v62
	s_waitcnt lgkmcnt(0)
; DEV void store_bf4(bf16_t* p, f32x4 v) { uint2 w; w.x = cvt_pk_bf16(v[0], v[1]); w.y = cvt_pk_bf16(v[2], v[3]); *(uint2*)p = w; }
; DEV float wave_max(float v) {
; #pragma unroll
;     for (int o = 32; o >= 1; o >>= 1) v = fmaxf(v, __shfl_xor(v, o));
;     return v;
; __global__ void __launch_bounds__(512) hymba_fwd(Params p) {
;     ...
;         f32x4 e; e[0] = __expf(v[0] - mx); e[1] = __expf(v[1] - mx); e[2] = __expf(v[2] - mx); e[3] = __expf(v[3] - mx);
;         const float inv = 1.f / wave_sum(e[0] + e[1] + e[2] + e[3]);
;         store_bf4(pb + (size_t)(r >> 2) * LDP + (r & 3) * 256 + lane * 4, e * inv);
	v_add_f32_e32 v59, v59, v63
	v_div_scale_f32 v64, s[16:17], v56, v56, 1.0
	v_rcp_f32_e32 v65, v64
	v_div_scale_f32 v66, vcc, 1.0, v56, 1.0
	v_fma_f32 v67, -v64, v65, 1.0
	v_fmac_f32_e32 v65, v67, v65
	v_mul_f32_e32 v67, v66, v65
	v_fma_f32 v68, -v64, v67, v66
	v_fmac_f32_e32 v67, v68, v65
	v_fma_f32 v64, -v64, v67, v66
	v_div_fmas_f32 v64, v64, v65, v67
	v_div_fixup_f32 v56, v64, v56, 1.0
	v_mul_f32_e32 v24, v24, v56
	v_mul_f32_e32 v25, v25, v56
	v_mul_f32_e32 v26, v26, v56
	v_mul_f32_e32 v27, v27, v56
	v_cvt_pk_bf16_f32 v24, v24, v25
	v_cvt_pk_bf16_f32 v25, v26, v27
	global_store_dwordx2 v[20:21], v[24:25], off
	v_lshl_add_u64 v[20:21], v[20:21], 0, s[10:11]
	v_div_scale_f32 v64, s[16:17], v57, v57, 1.0
	v_rcp_f32_e32 v65, v64
	v_div_scale_f32 v66, vcc, 1.0, v57, 1.0
	v_fma_f32 v67, -v64, v65, 1.0
	v_fmac_f32_e32 v65, v67, v65
	v_mul_f32_e32 v67, v66, v65
	v_fma_f32 v68, -v64, v67, v66
	v_fmac_f32_e32 v67, v68, v65
	v_fma_f32 v64, -v64, v67, v66
	v_div_fmas_f32 v64, v64, v65, v67
	v_div_fixup_f32 v57, v64, v57, 1.0
	v_mul_f32_e32 v28, v28, v57
	v_mul_f32_e32 v29, v29, v57
	v_mul_f32_e32 v30, v30, v57
	v_mul_f32_e32 v31, v31, v57
	v_cvt_pk_bf16_f32 v28, v28, v29
	v_cvt_pk_bf16_f32 v29, v30, v31
	global_store_dwordx2 v[20:21], v[28:29], off
	v_lshl_add_u64 v[20:21], v[20:21], 0, s[10:11]
	v_div_scale_f32 v64, s[16:17], v58, v58, 1.0
	v_rcp_f32_e32 v65, v64
	v_div_scale_f32 v66, vcc, 1.0, v58, 1.0
	v_fma_f32 v67, -v64, v65, 1.0
	v_fmac_f32_e32 v65, v67, v65
	v_mul_f32_e32 v67, v66, v65
	v_fma_f32 v68, -v64, v67, v66
	v_fmac_f32_e32 v67, v68, v65
	v_fma_f32 v64, -v64, v67, v66
	v_div_fmas_f32 v64, v64, v65, v67
	v_div_fixup_f32 v58, v64, v58, 1.0
	v_mul_f32_e32 v32, v32, v58
	v_mul_f32_e32 v33, v33, v58
	v_mul_f32_e32 v34, v34, v58
	v_mul_f32_e32 v35, v35, v58
	v_cvt_pk_bf16_f32 v32, v32, v33
	v_cvt_pk_bf16_f32 v33, v34, v35
	global_store_dwordx2 v[20:21], v[32:33], off
	v_lshl_add_u64 v[20:21], v[20:21], 0, s[10:11]
	v_div_scale_f32 v64, s[16:17], v59, v59, 1.0
	v_rcp_f32_e32 v65, v64
	v_div_scale_f32 v66, vcc, 1.0, v59, 1.0
	v_fma_f32 v67, -v64, v65, 1.0
	v_fmac_f32_e32 v65, v67, v65
	v_mul_f32_e32 v67, v66, v65
	v_fma_f32 v68, -v64, v67, v66
	v_fmac_f32_e32 v67, v68, v65
	v_fma_f32 v64, -v64, v67, v66
	v_div_fmas_f32 v64, v64, v65, v67
	v_div_fixup_f32 v59, v64, v59, 1.0
	v_mul_f32_e32 v36, v36, v59
	v_mul_f32_e32 v37, v37, v59
	v_mul_f32_e32 v38, v38, v59
	v_mul_f32_e32 v39, v39, v59
	v_cvt_pk_bf16_f32 v36, v36, v37
	v_cvt_pk_bf16_f32 v37, v38, v39
	global_store_dwordx2 v[20:21], v[36:37], off
	v_lshl_add_u64 v[20:21], v[20:21], 0, s[10:11]
	s_waitcnt vmcnt(4)
	v_max_f32_e32 v56, v43, v43
	v_max_f32_e32 v60, v42, v42
	v_max_f32_e32 v56, v60, v56
	v_max3_f32 v56, v40, v41, v56
	v_max_f32_e32 v57, v47, v47
	v_max_f32_e32 v61, v46, v46
	v_max_f32_e32 v57, v61, v57
	v_max3_f32 v57, v44, v45, v57
	v_max_f32_e32 v58, v51, v51
	v_max_f32_e32 v62, v50, v50
	v_max_f32_e32 v58, v62, v58
	v_max3_f32 v58, v48, v49, v58
	v_max_f32_e32 v59, v55, v55
	v_max_f32_e32 v63, v54, v54
	v_max_f32_e32 v59, v63, v59
	v_max3_f32 v59, v52, v53, v59
	ds_bpermute_b32 v60, v8, v56
	ds_bpermute_b32 v61, v8, v57
	ds_bpermute_b32 v62, v8, v58
	ds_bpermute_b32 v63, v8, v59
	s_waitcnt lgkmcnt(3)
	v_max_f32_e32 v60, v60, v60
	v_max_f32_e32 v56, v56, v60
	s_waitcnt lgkmcnt(2)
	v_max_f32_e32 v61, v61, v61
	v_max_f32_e32 v57, v57, v61
	s_waitcnt lgkmcnt(1)
	v_max_f32_e32 v62, v62, v62
	v_max_f32_e32 v58, v58, v62
	s_waitcnt lgkmcnt(0)
	v_max_f32_e32 v63, v63, v63
	v_max_f32_e32 v59, v59, v63
	ds_bpermute_b32 v60, v9, v56
	ds_bpermute_b32 v61, v9, v57
	ds_bpermute_b32 v62, v9, v58
	ds_bpermute_b32 v63, v9, v59
	s_waitcnt lgkmcnt(3)
	v_max_f32_e32 v60, v60, v60
	v_max_f32_e32 v56, v56, v60
	s_waitcnt lgkmcnt(2)
	v_max_f32_e32 v61, v61, v61
	v_max_f32_e32 v57, v57, v61
	s_waitcnt lgkmcnt(1)
	v_max_f32_e32 v62, v62, v62
	v_max_f32_e32 v58, v58, v62
	s_waitcnt lgkmcnt(0)
	v_max_f32_e32 v63, v63, v63
	v_max_f32_e32 v59, v59, v63
	ds_bpermute_b32 v60, v10, v56
	ds_bpermute_b32 v61, v10, v57
	ds_bpermute_b32 v62, v10, v58
	ds_bpermute_b32 v63, v10, v59
	s_waitcnt lgkmcnt(3)
	v_max_f32_e32 v60, v60, v60
	v_max_f32_e32 v56, v56, v60
	s_waitcnt lgkmcnt(2)
	v_max_f32_e32 v61, v61, v61
	v_max_f32_e32 v57, v57, v61
	s_waitcnt lgkmcnt(1)
	v_max_f32_e32 v62, v62, v62
	v_max_f32_e32 v58, v58, v62
	s_waitcnt lgkmcnt(0)
	v_max_f32_e32 v63, v63, v63
	v_max_f32_e32 v59, v59, v63
	ds_bpermute_b32 v60, v11, v56
	ds_bpermute_b32 v61, v11, v57
	ds_bpermute_b32 v62, v11, v58
	ds_bpermute_b32 v63, v11, v59
	s_waitcnt lgkmcnt(3)
	v_max_f32_e32 v60, v60, v60
	v_max_f32_e32 v56, v56, v60
	s_waitcnt lgkmcnt(2)
	v_max_f32_e32 v61, v61, v61
	v_max_f32_e32 v57, v57, v61
	s_waitcnt lgkmcnt(1)
	v_max_f32_e32 v62, v62, v62
	v_max_f32_e32 v58, v58, v62
	s_waitcnt lgkmcnt(0)
	v_max_f32_e32 v63, v63, v63
	v_max_f32_e32 v59, v59, v63
	ds_bpermute_b32 v60, v12, v56
	ds_bpermute_b32 v61, v12, v57
	ds_bpermute_b32 v62, v12, v58
	ds_bpermute_b32 v63, v12, v59
	s_waitcnt lgkmcnt(3)
	v_max_f32_e32 v60, v60, v60
	v_max_f32_e32 v56, v56, v60
	s_waitcnt lgkmcnt(2)
	v_max_f32_e32 v61, v61, v61
	v_max_f32_e32 v57, v57, v61
	s_waitcnt lgkmcnt(1)
	v_max_f32_e32 v62, v62, v62
	v_max_f32_e32 v58, v58, v62
	s_waitcnt lgkmcnt(0)
	v_max_f32_e32 v63, v63, v63
	v_max_f32_e32 v59, v59, v63
	ds_bpermute_b32 v60, v13, v56
	ds_bpermute_b32 v61, v13, v57
	ds_bpermute_b32 v62, v13, v58
	ds_bpermute_b32 v63, v13, v59
	s_waitcnt lgkmcnt(3)
	v_max_f32_e32 v60, v60, v60
	v_max_f32_e32 v56, v56, v60
	s_waitcnt lgkmcnt(2)
	v_max_f32_e32 v61, v61, v61
	v_max_f32_e32 v57, v57, v61
	s_waitcnt lgkmcnt(1)
	v_max_f32_e32 v62, v62, v62
	v_max_f32_e32 v58, v58, v62
	s_waitcnt lgkmcnt(0)
; DEV void store_bf4(bf16_t* p, f32x4 v) { uint2 w; w.x = cvt_pk_bf16(v[0], v[1]); w.y = cvt_pk_bf16(v[2], v[3]); *(uint2*)p = w; }
; #define VLOOP(t, N) for (int t##0_ = 2 * bid, t = min(t##0_ + vb, (N) - 1); t##0_ < (N); t##0_ += VG, t = min(t##0_ + vb, (N) - 1))
; DEV float wave_sum(float v) {
; #pragma unroll
;     for (int o = 32; o >= 1; o >>= 1) v += __shfl_xor(v, o);
;     return v;
; __global__ void __launch_bounds__(512) hymba_fwd(Params p) {
;     ...
;         const float mx = wave_max(fmaxf(fmaxf(v[0], v[1]), fmaxf(v[2], v[3])));
;         f32x4 e; e[0] = __expf(v[0] - mx); e[1] = __expf(v[1] - mx); e[2] = __expf(v[2] - mx); e[3] = __expf(v[3] - mx);
;         const float inv = 1.f / wave_sum(e[0] + e[1] + e[2] + e[3]);
;         store_bf4(pb + (size_t)(r >> 2) * LDP + (r & 3) * 256 + lane * 4, e * inv);
;     ...
;     if (IN_PH(10)) { PH_LOCALS
;         VLOOP(t, 16 * 16 * 4) { const int bhd = t >> 6, v = t & 63, mt = v >> 2, nt = v & 3, b = bhd >> 2, hd = bhd & 3;
;             EpiBfS e{ctx + (size_t)(b * SEQ + mt * 128) * LDB + hd * 512 + nt * 128, LDB};
;             gemm_tile<64>(pb + (size_t)(b * SEQ + mt * 128) * LDP + hd * 256, LDP, mvt + ((size_t)b * D + hd * 512 + nt * 128) * LDM, LDM, 256, vlds, e);
	v_max_f32_e32 v63, v63, v63
	v_max_f32_e32 v59, v59, v63
	v_sub_f32_e32 v40, v40, v56
	v_sub_f32_e32 v41, v41, v56
	v_sub_f32_e32 v42, v42, v56
	v_sub_f32_e32 v43, v43, v56
	v_mul_f32_e32 v40, 0x3fb8aa3b, v40
	v_mul_f32_e32 v41, 0x3fb8aa3b, v41
	v_mul_f32_e32 v42, 0x3fb8aa3b, v42
	v_mul_f32_e32 v43, 0x3fb8aa3b, v43
	v_sub_f32_e32 v44, v44, v57
	v_sub_f32_e32 v45, v45, v57
	v_sub_f32_e32 v46, v46, v57
	v_sub_f32_e32 v47, v47, v57
	v_mul_f32_e32 v44, 0x3fb8aa3b, v44
	v_mul_f32_e32 v45, 0x3fb8aa3b, v45
	v_mul_f32_e32 v46, 0x3fb8aa3b, v46
	v_mul_f32_e32 v47, 0x3fb8aa3b, v47
	v_sub_f32_e32 v48, v48, v58
	v_sub_f32_e32 v49, v49, v58
	v_sub_f32_e32 v50, v50, v58
	v_sub_f32_e32 v51, v51, v58
	v_mul_f32_e32 v48, 0x3fb8aa3b, v48
	v_mul_f32_e32 v49, 0x3fb8aa3b, v49
	v_mul_f32_e32 v50, 0x3fb8aa3b, v50
	v_mul_f32_e32 v51, 0x3fb8aa3b, v51
	v_sub_f32_e32 v52, v52, v59
	v_sub_f32_e32 v53, v53, v59
	v_sub_f32_e32 v54, v54, v59
	v_sub_f32_e32 v55, v55, v59
	v_mul_f32_e32 v52, 0x3fb8aa3b, v52
	v_mul_f32_e32 v53, 0x3fb8aa3b, v53
	v_mul_f32_e32 v54, 0x3fb8aa3b, v54
	v_mul_f32_e32 v55, 0x3fb8aa3b, v55
	v_exp_f32_e32 v40, v40
	v_exp_f32_e32 v41, v41
	v_exp_f32_e32 v42, v42
	v_exp_f32_e32 v43, v43
	v_exp_f32_e32 v44, v44
	v_exp_f32_e32 v45, v45
	v_exp_f32_e32 v46, v46
	v_exp_f32_e32 v47, v47
	v_exp_f32_e32 v48, v48
	v_exp_f32_e32 v49, v49
	v_exp_f32_e32 v50, v50
	v_exp_f32_e32 v51, v51
	v_exp_f32_e32 v52, v52
	v_exp_f32_e32 v53, v53
	v_exp_f32_e32 v54, v54
	v_exp_f32_e32 v55, v55
	v_add_f32_e32 v56, v40, v41
	v_add_f32_e32 v56, v42, v56
	v_add_f32_e32 v56, v43, v56
	v_add_f32_e32 v57, v44, v45
	v_add_f32_e32 v57, v46, v57
	v_add_f32_e32 v57, v47, v57
	v_add_f32_e32 v58, v48, v49
	v_add_f32_e32 v58, v50, v58
	v_add_f32_e32 v58, v51, v58
	v_add_f32_e32 v59, v52, v53
	v_add_f32_e32 v59, v54, v59
	v_add_f32_e32 v59, v55, v59
	ds_bpermute_b32 v60, v8, v56
	ds_bpermute_b32 v61, v8, v57
	ds_bpermute_b32 v62, v8, v58
	ds_bpermute_b32 v63, v8, v59
	s_waitcnt lgkmcnt(3)
	v_add_f32_e32 v56, v56, v60
	s_waitcnt lgkmcnt(2)
	v_add_f32_e32 v57, v57, v61
	s_waitcnt lgkmcnt(1)
	v_add_f32_e32 v58, v58, v62
	s_waitcnt lgkmcnt(0)
	v_add_f32_e32 v59, v59, v63
	ds_bpermute_b32 v60, v9, v56
	ds_bpermute_b32 v61, v9, v57
	ds_bpermute_b32 v62, v9, v58
	ds_bpermute_b32 v63, v9, v59
	s_waitcnt lgkmcnt(3)
	v_add_f32_e32 v56, v56, v60
	s_waitcnt lgkmcnt(2)
	v_add_f32_e32 v57, v57, v61
	s_waitcnt lgkmcnt(1)
	v_add_f32_e32 v58, v58, v62
	s_waitcnt lgkmcnt(0)
	v_add_f32_e32 v59, v59, v63
	ds_bpermute_b32 v60, v10, v56
	ds_bpermute_b32 v61, v10, v57
	ds_bpermute_b32 v62, v10, v58
	ds_bpermute_b32 v63, v10, v59
	s_waitcnt lgkmcnt(3)
	v_add_f32_e32 v56, v56, v60
	s_waitcnt lgkmcnt(2)
	v_add_f32_e32 v57, v57, v61
	s_waitcnt lgkmcnt(1)
	v_add_f32_e32 v58, v58, v62
	s_waitcnt lgkmcnt(0)
	v_add_f32_e32 v59, v59, v63
	ds_bpermute_b32 v60, v11, v56
	ds_bpermute_b32 v61, v11, v57
	ds_bpermute_b32 v62, v11, v58
	ds_bpermute_b32 v63, v11, v59
	s_waitcnt lgkmcnt(3)
	v_add_f32_e32 v56, v56, v60
	s_waitcnt lgkmcnt(2)
	v_add_f32_e32 v57, v57, v61
	s_waitcnt lgkmcnt(1)
	v_add_f32_e32 v58, v58, v62
	s_waitcnt lgkmcnt(0)
	v_add_f32_e32 v59, v59, v63
	ds_bpermute_b32 v60, v12, v56
	ds_bpermute_b32 v61, v12, v57
	ds_bpermute_b32 v62, v12, v58
	ds_bpermute_b32 v63, v12, v59
	s_waitcnt lgkmcnt(3)
	v_add_f32_e32 v56, v56, v60
	s_waitcnt lgkmcnt(2)
	v_add_f32_e32 v57, v57, v61
	s_waitcnt lgkmcnt(1)
	v_add_f32_e32 v58, v58, v62
	s_waitcnt lgkmcnt(0)
	v_add_f32_e32 v59, v59, v63
	ds_bpermute_b32 v60, v13, v56
	ds_bpermute_b32 v61, v13, v57
	ds_bpermute_b32 v62, v13, v58
	ds_bpermute_b32 v63, v13, v59
	s_waitcnt lgkmcnt(3)
	v_add_f32_e32 v56, v56, v60
	s_waitcnt lgkmcnt(2)
	v_add_f32_e32 v57, v57, v61
	s_waitcnt lgkmcnt(1)
	v_add_f32_e32 v58, v58, v62
	s_waitcnt lgkmcnt(0)
	v_add_f32_e32 v59, v59, v63
	v_div_scale_f32 v64, s[16:17], v56, v56, 1.0
	v_rcp_f32_e32 v65, v64
	v_div_scale_f32 v66, vcc, 1.0, v56, 1.0
	v_fma_f32 v67, -v64, v65, 1.0
	v_fmac_f32_e32 v65, v67, v65
	v_mul_f32_e32 v67, v66, v65
	v_fma_f32 v68, -v64, v67, v66
	v_fmac_f32_e32 v67, v68, v65
	v_fma_f32 v64, -v64, v67, v66
	v_div_fmas_f32 v64, v64, v65, v67
	v_div_fixup_f32 v56, v64, v56, 1.0
	v_mul_f32_e32 v40, v40, v56
	v_mul_f32_e32 v41, v41, v56
	v_mul_f32_e32 v42, v42, v56
	v_mul_f32_e32 v43, v43, v56
	v_cvt_pk_bf16_f32 v40, v40, v41
	v_cvt_pk_bf16_f32 v41, v42, v43
	global_store_dwordx2 v[20:21], v[40:41], off
	v_lshl_add_u64 v[20:21], v[20:21], 0, s[10:11]
	v_div_scale_f32 v64, s[16:17], v57, v57, 1.0
	v_rcp_f32_e32 v65, v64
	v_div_scale_f32 v66, vcc, 1.0, v57, 1.0
	v_fma_f32 v67, -v64, v65, 1.0
	v_fmac_f32_e32 v65, v67, v65
	v_mul_f32_e32 v67, v66, v65
	v_fma_f32 v68, -v64, v67, v66
	v_fmac_f32_e32 v67, v68, v65
	v_fma_f32 v64, -v64, v67, v66
	v_div_fmas_f32 v64, v64, v65, v67
	v_div_fixup_f32 v57, v64, v57, 1.0
	v_mul_f32_e32 v44, v44, v57
	v_mul_f32_e32 v45, v45, v57
	v_mul_f32_e32 v46, v46, v57
	v_mul_f32_e32 v47, v47, v57
	v_cvt_pk_bf16_f32 v44, v44, v45
	v_cvt_pk_bf16_f32 v45, v46, v47
	global_store_dwordx2 v[20:21], v[44:45], off
	v_lshl_add_u64 v[20:21], v[20:21], 0, s[10:11]
	v_div_scale_f32 v64, s[16:17], v58, v58, 1.0
	v_rcp_f32_e32 v65, v64
	v_div_scale_f32 v66, vcc, 1.0, v58, 1.0
	v_fma_f32 v67, -v64, v65, 1.0
	v_fmac_f32_e32 v65, v67, v65
	v_mul_f32_e32 v67, v66, v65
	v_fma_f32 v68, -v64, v67, v66
	v_fmac_f32_e32 v67, v68, v65
	v_fma_f32 v64, -v64, v67, v66
	v_div_fmas_f32 v64, v64, v65, v67
	v_div_fixup_f32 v58, v64, v58, 1.0
	v_mul_f32_e32 v48, v48, v58
	v_mul_f32_e32 v49, v49, v58
	v_mul_f32_e32 v50, v50, v58
	v_mul_f32_e32 v51, v51, v58
	v_cvt_pk_bf16_f32 v48, v48, v49
	v_cvt_pk_bf16_f32 v49, v50, v51
	global_store_dwordx2 v[20:21], v[48:49], off
	v_lshl_add_u64 v[20:21], v[20:21], 0, s[10:11]
	v_div_scale_f32 v64, s[16:17], v59, v59, 1.0
	v_rcp_f32_e32 v65, v64
	v_div_scale_f32 v66, vcc, 1.0, v59, 1.0
	v_fma_f32 v67, -v64, v65, 1.0
	v_fmac_f32_e32 v65, v67, v65
	v_mul_f32_e32 v67, v66, v65
	v_fma_f32 v68, -v64, v67, v66
	v_fmac_f32_e32 v67, v68, v65
	v_fma_f32 v64, -v64, v67, v66
	v_div_fmas_f32 v64, v64, v65, v67
	v_div_fixup_f32 v59, v64, v59, 1.0
	v_mul_f32_e32 v52, v52, v59
	v_mul_f32_e32 v53, v53, v59
	v_mul_f32_e32 v54, v54, v59
	v_mul_f32_e32 v55, v55, v59
	v_cvt_pk_bf16_f32 v52, v52, v53
	v_cvt_pk_bf16_f32 v53, v54, v55
	global_store_dwordx2 v[20:21], v[52:53], off
	v_lshl_add_u64 v[20:21], v[20:21], 0, s[10:11]
	s_waitcnt vmcnt(0)
	s_barrier
	s_mov_b64 s[6:7], 0x20f39000
	v_lshl_add_u64 v[86:87], v[158:159], 0, s[6:7]
	s_branch .Lp10_guard

; #define LAS __attribute__((address_space(3)))
; #define GLDS_STAGE(st, kt_) do { \
;         _Pragma("unroll") for (int i_ = 0; i_ < FI; ++i_) { \
;             glds16(ap + (size_t)(32 * i_) * lda + (kt_) * 64, l3a + (st) + tid * 16 + i_ * 4096); \
;             glds16(bp + (size_t)(32 * i_) * ldb + (kt_) * 64, l3a + (st) + OPB + tid * 16 + i_ * 4096); } } while (0)
; #define GLDS_STAGE(st, kt_) do { \
;         _Pragma("unroll") for (int i_ = 0; i_ < 4; ++i_) { \
;             glds16(ap + (size_t)(64 * i_) * lda + (kt_) * 64, l3a + (st) + tid * 16 + i_ * 8192); \
;             glds16(bp + (size_t)(64 * i_) * ldb + (kt_) * 64, l3a + (st) + 32768 + tid * 16 + i_ * 8192); } } while (0)
; #define VLOOP(t, N) for (int t##0_ = 2 * bid, t = min(t##0_ + vb, (N) - 1); t##0_ < (N); t##0_ += VG, t = min(t##0_ + vb, (N) - 1))
; template <int WT, class Epi>
; DEV void gemm_tile(const bf16_t* __restrict__ A, int lda, const bf16_t* __restrict__ Bt, int ldb, int K, unsigned char* lds, const Epi& epi) {
;     ...
;     const int lrow = tid >> 3, lcs = (tid & 7) ^ (lrow & 7);
;     const bf16_t* ap = A + (size_t)lrow * lda + lcs * 8;
;     const bf16_t* bp = Bt + (size_t)lrow * ldb + lcs * 8;
;     const unsigned l3a = (unsigned)(size_t)(LAS unsigned char*)lds;
;     const int nk = K >> 6;
;     ...
;     constexpr int NSTG = 65536 / STB;
; #pragma unroll
;     for (int s_ = 0; s_ < NSTG - 1; ++s_) if (s_ < nk) GLDS_STAGE(s_ * STB, s_);
;     const int aoff = (wr * WT + fr) * 128, boff = OPB + (wc * WT + fr) * 128, sw = fr & 7;
;     int cur = 0, nxt = (NSTG - 1) * STB;
;     for (int kt = 0; kt < nk; ++kt) {
;         if (NSTG == 4 && kt + 2 < nk) { if (FI == 2) asm volatile("s_waitcnt vmcnt(8)" ::: "memory"); else asm volatile("s_waitcnt vmcnt(0)" ::: "memory"); }
;         else asm volatile("s_waitcnt vmcnt(0)" ::: "memory");
;         __syncthreads();
;         if (kt + NSTG - 1 < nk) GLDS_STAGE(nxt, kt + NSTG - 1);
; __global__ void __launch_bounds__(512) hymba_fwd(Params p) {
;     ...
;     if (IN_PH(10)) { PH_LOCALS
;         VLOOP(t, 16 * 16 * 4) { const int bhd = t >> 6, v = t & 63, mt = v >> 2, nt = v & 3, b = bhd >> 2, hd = bhd & 3;
;             EpiBfS e{ctx + (size_t)(b * SEQ + mt * 128) * LDB + hd * 512 + nt * 128, LDB};
;             gemm_tile<64>(pb + (size_t)(b * SEQ + mt * 128) * LDP + hd * 256, LDP, mvt + ((size_t)b * D + hd * 512 + nt * 128) * LDM, LDM, 256, vlds, e);
.Lp10_guard:
	s_load_dwordx2 s[4:5], s[0:1], 0xd0
	s_mov_b64 s[6:7], 0x22039000
	v_lshl_add_u64 v[132:133], v[158:159], 0, s[6:7]
	s_waitcnt lgkmcnt(0)
	s_cmp_lt_i32 s4, 11
	s_cselect_b64 s[8:9], -1, 0
	s_cmp_gt_i32 s5, 10
	s_cselect_b64 s[4:5], -1, 0
	s_and_b64 s[4:5], s[8:9], s[4:5]
	s_andn2_b64 vcc, exec, s[4:5]
	s_cbranch_vccnz .LBB0_1410
	v_mov_b32_e32 v1, v0
	s_cmpk_gt_i32 s2, 0x1ff
	v_readfirstlane_b32 s4, v1
	s_cbranch_scc1 .LBB0_1410
	s_ashr_i32 s72, s4, 8
	s_lshl_b32 s74, s2, 1
	s_lshl_b32 s70, s72, 16
	s_add_i32 s4, s72, s74
	s_min_i32 s88, s4, 0x3ff
	v_and_b32_e32 v1, 0xff, v0
	s_or_b32 s71, s70, 0x8000
	s_add_i32 s72, s72, s75
	s_movk_i32 s96, 0x400
	s_mov_b32 s97, s75
	s_cmpk_lg_i32 s33, 0x100
	s_cbranch_scc1 .Lp10_go
	s_sub_i32 s72, s72, s75
	s_lshl_b32 s74, s2, 2
	s_add_i32 s88, s72, s74
	s_add_i32 s72, s72, 2
	s_add_i32 s96, s74, 4
	s_mov_b32 s97, 2
.Lp10_go:
	s_movk_i32 s73, 0x1080
	v_mov_b32_e32 v94, 0x1080
	s_mov_b32 s5, 0
	s_movk_i32 s76, 0x880
	v_mov_b32_e32 v95, 0x880
	s_movk_i32 s77, 0x240
	v_mov_b32_e32 v96, 0x240
	v_mov_b32_e32 v89, 0
	s_mov_b64 s[6:7], 0x11000
	s_mov_b64 s[8:9], 0x4800
	s_mov_b64 s[10:11], 0x22000
	s_mov_b64 s[12:13], 0x9000
	s_mov_b64 s[16:17], 0x33000
	s_mov_b64 s[18:19], 0xd800
	s_movk_i32 s78, 0xffc0
	s_mov_b64 s[20:21], 0x80
	s_mov_b64 s[22:23], 0x11080
	s_mov_b64 s[24:25], 0x4880
	s_mov_b64 s[26:27], 0x22080
	s_mov_b64 s[30:31], 0x9080
	s_mov_b64 s[34:35], 0x33080
	s_mov_b64 s[36:37], 0xd880
	s_mov_b64 s[38:39], 0x100
	s_mov_b64 s[40:41], 0x11100
	s_mov_b64 s[42:43], 0x4900
	s_mov_b64 s[44:45], 0x22100
	s_mov_b64 s[46:47], 0x9100
	s_mov_b64 s[48:49], 0x33100
	s_mov_b64 s[50:51], 0xd900
	s_mov_b64 s[52:53], 0x180
	s_mov_b64 s[54:55], 0x11180
	s_mov_b64 s[56:57], 0x4980
	s_mov_b64 s[58:59], 0x22180
	s_mov_b64 s[60:61], 0x9180
	s_mov_b64 s[62:63], 0x33180
	s_mov_b64 s[64:65], 0xd980
.LBB0_1409:
	s_ashr_i32 s68, s88, 8
	s_bfe_u32 s66, s88, 0x20006
	s_lshl_b32 s4, s88, 5
	s_ashr_i32 s69, s68, 31
	s_lshl_b32 s14, s88, 7
	v_mov_b32_e32 v97, v1
	s_lshl_b32 s15, s68, 11
	s_and_b32 s67, s4, 0x780
	s_lshl_b32 s4, s66, 9
	s_lshl_b64 s[68:69], s[68:69], 11
	s_and_b32 s80, s14, 0x180
	s_or_b32 s79, s15, s67
	v_lshrrev_b32_e32 v4, 4, v97
	v_and_b32_e32 v99, 15, v97
	v_ashrrev_i32_e32 v6, 3, v97
	v_lshlrev_b32_e32 v5, 4, v97
	v_ashrrev_i32_e32 v7, 1, v97
	v_lshlrev_b32_e32 v8, 7, v97
	v_and_b32_e32 v74, 7, v97
	s_or_b32 s14, s68, s4
	v_mad_i64_i32 v[2:3], s[82:83], s79, v95, v[86:87]
	v_xor_b32_e32 v9, v6, v97
	v_add_u32_e32 v10, s70, v5
	v_and_or_b32 v102, v7, s78, v99
	v_and_b32_e32 v7, 0x2780, v8
	v_add_u32_e32 v128, 0x4000, v5
	v_add_u32_e32 v5, s71, v5
	v_bitop3_b32 v4, v4, v74, 3 bitop3:0x6c
	s_or_b32 s14, s14, s80
	s_mul_i32 s15, s69, 0x240
	v_lshl_add_u64 v[2:3], v[2:3], 0, s[4:5]
	v_lshlrev_b32_e32 v8, 4, v9
	v_readfirstlane_b32 s4, v5
	v_add_u32_e32 v79, s70, v7
	v_lshlrev_b32_e32 v7, 4, v4
	v_mad_u64_u32 v[4:5], s[68:69], s14, v96, v[162:163]
	v_mad_i64_i32 v[2:3], s[68:69], v6, s76, v[2:3]
	v_and_b32_e32 v88, 0x70, v8
	v_add_u32_e32 v5, s15, v5
	v_add_u32_e32 v9, 0x4000, v10
	v_readfirstlane_b32 s67, v10
	v_lshl_add_u64 v[90:91], v[2:3], 0, v[88:89]
	v_mad_i64_i32 v[2:3], s[68:69], v6, s77, v[4:5]
	s_mov_b32 s68, m0
	s_mov_b32 m0, s67
	s_nop 0
	global_load_lds_dwordx4 v[90:91], off
	s_mov_b32 m0, s68
	v_readfirstlane_b32 s14, v9
	v_lshl_add_u64 v[92:93], v[2:3], 0, v[88:89]
	s_mov_b32 s68, m0
	s_mov_b32 m0, s14
	s_nop 0
	global_load_lds_dwordx4 v[92:93], off
	s_mov_b32 m0, s68
	s_add_i32 s88, s67, 0x1000
	s_add_i32 s15, s14, 0x1000
	s_add_i32 s91, s14, 0x2000
	s_add_i32 s92, s14, 0x3000
	v_lshl_add_u64 v[4:5], v[90:91], 0, s[6:7]
	s_mov_b32 s14, m0
	s_mov_b32 m0, s88
	s_nop 0
	global_load_lds_dwordx4 v[4:5], off
	s_mov_b32 m0, s14
	v_lshl_add_u32 v78, v102, 7, s70
	v_lshl_add_u64 v[2:3], v[92:93], 0, s[8:9]
	s_mov_b32 s14, m0
	s_mov_b32 m0, s15
	s_nop 0
	global_load_lds_dwordx4 v[2:3], off
	s_mov_b32 m0, s14
	s_add_i32 s89, s67, 0x2000
	v_add_u32_e32 v98, v78, v7
	v_add_u32_e32 v100, v79, v7
	v_lshl_add_u64 v[6:7], v[90:91], 0, s[10:11]
	s_mov_b32 s14, m0
	s_mov_b32 m0, s89
	s_nop 0
	global_load_lds_dwordx4 v[6:7], off
	s_mov_b32 m0, s14
	v_lshl_add_u64 v[18:19], v[92:93], 0, s[12:13]
	s_mov_b32 s14, m0
	s_mov_b32 m0, s91
	s_nop 0
	global_load_lds_dwordx4 v[18:19], off
	s_mov_b32 m0, s14
	s_add_i32 s90, s67, 0x3000
	v_lshl_add_u64 v[8:9], v[90:91], 0, s[16:17]
	s_mov_b32 s14, m0
	s_mov_b32 m0, s90
	s_nop 0
	global_load_lds_dwordx4 v[8:9], off
	s_mov_b32 m0, s14
	v_add_u32_e32 v10, s71, v128
	v_lshl_add_u64 v[20:21], v[92:93], 0, s[18:19]
	s_mov_b32 s14, m0
	s_mov_b32 m0, s92
	s_nop 0
	global_load_lds_dwordx4 v[20:21], off
	s_mov_b32 m0, s14
	v_readfirstlane_b32 s84, v10
	v_lshl_add_u64 v[10:11], v[90:91], 0, s[20:21]
	s_waitcnt vmcnt(0)
	s_barrier
; #define GLDS_STAGE(st, kt_) do { \
;         _Pragma("unroll") for (int i_ = 0; i_ < FI; ++i_) { \
;             glds16(ap + (size_t)(32 * i_) * lda + (kt_) * 64, l3a + (st) + tid * 16 + i_ * 4096); \
;             glds16(bp + (size_t)(32 * i_) * ldb + (kt_) * 64, l3a + (st) + OPB + tid * 16 + i_ * 4096); } } while (0)
; #define GLDS_STAGE(st, kt_) do { \
;         _Pragma("unroll") for (int i_ = 0; i_ < 4; ++i_) { \
;             glds16(ap + (size_t)(64 * i_) * lda + (kt_) * 64, l3a + (st) + tid * 16 + i_ * 8192); \
;             glds16(bp + (size_t)(64 * i_) * ldb + (kt_) * 64, l3a + (st) + 32768 + tid * 16 + i_ * 8192); } } while (0)
; template <int WT, class Epi>
; DEV void gemm_tile(const bf16_t* __restrict__ A, int lda, const bf16_t* __restrict__ Bt, int ldb, int K, unsigned char* lds, const Epi& epi) {
;     ...
;     for (int s_ = 0; s_ < NSTG - 1; ++s_) if (s_ < nk) GLDS_STAGE(s_ * STB, s_);
;     const int aoff = (wr * WT + fr) * 128, boff = OPB + (wc * WT + fr) * 128, sw = fr & 7;
;     int cur = 0, nxt = (NSTG - 1) * STB;
;     for (int kt = 0; kt < nk; ++kt) {
;         if (NSTG == 4 && kt + 2 < nk) { if (FI == 2) asm volatile("s_waitcnt vmcnt(8)" ::: "memory"); else asm volatile("s_waitcnt vmcnt(0)" ::: "memory"); }
;         else asm volatile("s_waitcnt vmcnt(0)" ::: "memory");
;         __syncthreads();
;         if (kt + NSTG - 1 < nk) GLDS_STAGE(nxt, kt + NSTG - 1);
; #pragma unroll
;         for (int kh = 0; kh < 2; ++kh) {
;             bf16x8 af[FI], bfr[FI];
;             const int ch = ((kh * 4 + fq) ^ sw) << 4;
; #pragma unroll
;             for (int i = 0; i < FI; ++i) { af[i] = *(const bf16x8*)(lds + cur + aoff + i * 2048 + ch); bfr[i] = *(const bf16x8*)(lds + cur + boff + i * 2048 + ch); }
; #pragma unroll
;             for (int mi = 0; mi < FI; ++mi)
; #pragma unroll
;                 for (int ni = 0; ni < FI; ++ni) acc[mi][ni] = __builtin_amdgcn_mfma_f32_16x16x32_bf16(bfr[ni], af[mi], acc[mi][ni], 0, 0, 0);
;         }
	s_mov_b32 s14, m0
	s_mov_b32 m0, s4
	s_nop 0
	global_load_lds_dwordx4 v[10:11], off
	s_mov_b32 m0, s14
	v_lshl_add_u64 v[22:23], v[92:93], 0, s[20:21]
	s_mov_b32 s14, m0
	s_mov_b32 m0, s84
	s_nop 0
	global_load_lds_dwordx4 v[22:23], off
	s_mov_b32 m0, s14
	s_add_i32 s83, s4, 0x1000
	v_lshl_add_u64 v[12:13], v[90:91], 0, s[22:23]
	s_mov_b32 s14, m0
	s_mov_b32 m0, s83
	s_nop 0
	global_load_lds_dwordx4 v[12:13], off
	s_mov_b32 m0, s14
	s_add_i32 s87, s84, 0x1000
	v_lshl_add_u64 v[24:25], v[92:93], 0, s[24:25]
	s_mov_b32 s14, m0
	s_mov_b32 m0, s87
	s_nop 0
	global_load_lds_dwordx4 v[24:25], off
	s_mov_b32 m0, s14
	s_add_i32 s82, s4, 0x2000
	v_lshl_add_u64 v[14:15], v[90:91], 0, s[26:27]
	s_mov_b32 s14, m0
	s_mov_b32 m0, s82
	s_nop 0
	global_load_lds_dwordx4 v[14:15], off
	s_mov_b32 m0, s14
	s_add_i32 s86, s84, 0x2000
	v_lshl_add_u64 v[26:27], v[92:93], 0, s[30:31]
	s_mov_b32 s14, m0
	s_mov_b32 m0, s86
	s_nop 0
	global_load_lds_dwordx4 v[26:27], off
	s_mov_b32 m0, s14
	s_add_i32 s81, s4, 0x3000
	v_lshl_add_u64 v[16:17], v[90:91], 0, s[34:35]
	s_mov_b32 s14, m0
	s_mov_b32 m0, s81
	s_nop 0
	global_load_lds_dwordx4 v[16:17], off
	s_mov_b32 m0, s14
	s_add_i32 s85, s84, 0x3000
	v_lshl_add_u64 v[28:29], v[92:93], 0, s[36:37]
	s_mov_b32 s14, m0
	s_mov_b32 m0, s85
	s_nop 0
	global_load_lds_dwordx4 v[28:29], off
	s_mov_b32 m0, s14
	ds_read_b128 v[2:5], v100 offset:16384
	ds_read_b128 v[6:9], v100 offset:18432
	ds_read_b128 v[10:13], v98
	ds_read_b128 v[14:17], v98 offset:2048
	ds_read_b128 v[22:25], v100 offset:20480
	ds_read_b128 v[30:33], v100 offset:22528
	ds_read_b128 v[50:53], v98 offset:4096
	ds_read_b128 v[54:57], v98 offset:6144
	v_bfe_u32 v103, v97, 4, 2
	s_waitcnt lgkmcnt(5)
	v_mfma_f32_16x16x32_bf16 v[18:21], v[2:5], v[10:13], 0
	s_waitcnt lgkmcnt(4)
	v_mfma_f32_16x16x32_bf16 v[38:41], v[2:5], v[14:17], 0
	s_waitcnt lgkmcnt(1)
	v_mfma_f32_16x16x32_bf16 v[58:61], v[2:5], v[50:53], 0
	s_waitcnt lgkmcnt(0)
	v_mfma_f32_16x16x32_bf16 v[70:73], v[2:5], v[54:57], 0
	v_bitop3_b32 v2, v103, v74, 4 bitop3:0x36
	v_lshlrev_b32_e32 v2, 4, v2
	v_add_u32_e32 v88, v78, v2
	v_add_u32_e32 v101, v79, v2
	v_mfma_f32_16x16x32_bf16 v[34:37], v[22:25], v[10:13], 0
	ds_read_b128 v[82:85], v101 offset:16384
	ds_read_b128 v[104:107], v101 offset:18432
	v_mfma_f32_16x16x32_bf16 v[46:49], v[22:25], v[14:17], 0
	v_mfma_f32_16x16x32_bf16 v[66:69], v[22:25], v[50:53], 0
	v_mfma_f32_16x16x32_bf16 v[78:81], v[22:25], v[54:57], 0
	ds_read_b128 v[2:5], v88
	ds_read_b128 v[22:25], v88 offset:2048
	ds_read_b128 v[112:115], v101 offset:20480
	ds_read_b128 v[120:123], v101 offset:22528
	v_mfma_f32_16x16x32_bf16 v[26:29], v[6:9], v[10:13], 0
	v_mfma_f32_16x16x32_bf16 v[10:13], v[30:33], v[10:13], 0
	v_mfma_f32_16x16x32_bf16 v[42:45], v[6:9], v[14:17], 0
	s_waitcnt lgkmcnt(0)
	v_mfma_f32_16x16x32_bf16 v[134:137], v[120:123], v[2:5], v[10:13]
	s_nop 4
	v_add_u32_e32 v10, s70, v128
	v_mfma_f32_16x16x32_bf16 v[14:17], v[30:33], v[14:17], 0
	v_readfirstlane_b32 s14, v10
	s_add_i32 s15, s14, 0x1000
	s_add_i32 s68, s14, 0x2000
	v_mfma_f32_16x16x32_bf16 v[62:65], v[6:9], v[50:53], 0
	s_add_i32 s69, s14, 0x3000
	v_lshl_add_u32 v128, v102, 8, s70
	v_mfma_f32_16x16x32_bf16 v[50:53], v[30:33], v[50:53], 0
	v_mfma_f32_16x16x32_bf16 v[74:77], v[6:9], v[54:57], 0
	v_mfma_f32_16x16x32_bf16 v[54:57], v[30:33], v[54:57], 0
	v_mfma_f32_16x16x32_bf16 v[124:127], v[112:115], v[2:5], v[34:37]
	v_mfma_f32_16x16x32_bf16 v[10:13], v[112:115], v[22:25], v[46:49]
	s_nop 1
	v_lshl_add_u64 v[34:35], v[90:91], 0, s[38:39]
	ds_read_b128 v[30:33], v88 offset:4096
	ds_read_b128 v[46:49], v88 offset:6144
	s_waitcnt vmcnt(0)
	s_waitcnt lgkmcnt(0)
	s_barrier
	s_mov_b32 s91, m0
	s_mov_b32 m0, s67
	s_nop 0
	global_load_lds_dwordx4 v[34:35], off
	s_mov_b32 m0, s91
	v_lshl_add_u64 v[36:37], v[92:93], 0, s[38:39]
	s_mov_b32 s67, m0
	s_mov_b32 m0, s14
	s_nop 0
	global_load_lds_dwordx4 v[36:37], off
	s_mov_b32 m0, s67
	v_mfma_f32_16x16x32_bf16 v[108:111], v[82:85], v[2:5], v[18:21]
	s_mov_b32 s67, s5
	v_mfma_f32_16x16x32_bf16 v[116:119], v[104:107], v[2:5], v[26:29]
	v_mfma_f32_16x16x32_bf16 v[2:5], v[82:85], v[22:25], v[38:41]
	s_nop 2
	v_lshl_add_u64 v[38:39], v[90:91], 0, s[40:41]
	s_mov_b32 s14, m0
	s_mov_b32 m0, s88
	s_nop 0
	global_load_lds_dwordx4 v[38:39], off
	s_mov_b32 m0, s14
	v_mfma_f32_16x16x32_bf16 v[6:9], v[104:107], v[22:25], v[42:45]
	v_lshl_add_u64 v[40:41], v[90:91], 0, s[44:45]
	s_nop 1
	v_lshl_add_u64 v[44:45], v[92:93], 0, s[42:43]
	s_mov_b32 s14, m0
	s_mov_b32 m0, s15
	s_nop 0
	global_load_lds_dwordx4 v[44:45], off
	s_mov_b32 m0, s14
	v_mfma_f32_16x16x32_bf16 v[18:21], v[82:85], v[30:33], v[58:61]
	s_mov_b32 s14, m0
	s_mov_b32 m0, s89
	s_nop 0
	global_load_lds_dwordx4 v[40:41], off
	s_mov_b32 m0, s14
	v_lshl_add_u64 v[42:43], v[90:91], 0, s[48:49]
	s_add_i32 s89, s74, s97
	v_mfma_f32_16x16x32_bf16 v[14:17], v[120:123], v[22:25], v[14:17]
	v_lshl_add_u64 v[58:59], v[92:93], 0, s[46:47]
	s_mov_b32 s14, m0
	s_mov_b32 m0, s68
	s_nop 0
	global_load_lds_dwordx4 v[58:59], off
	s_mov_b32 m0, s14
	v_lshl_add_u64 v[60:61], v[92:93], 0, s[50:51]
	s_mov_b32 s14, m0
	s_mov_b32 m0, s90
	s_nop 0
	global_load_lds_dwordx4 v[42:43], off
	s_mov_b32 m0, s14
	v_mfma_f32_16x16x32_bf16 v[22:25], v[104:107], v[30:33], v[62:65]
	s_mov_b32 s14, m0
	s_mov_b32 m0, s69
	s_nop 0
	global_load_lds_dwordx4 v[60:61], off
	s_mov_b32 m0, s14
	s_mov_b32 s69, s5
	s_lshl_b32 s68, s66, 10
	v_mfma_f32_16x16x32_bf16 v[26:29], v[112:115], v[30:33], v[66:69]
	s_add_i32 s14, s72, s74
	s_lshl_b32 s66, s80, 1
	s_min_i32 s88, s14, 0x3ff
	v_mfma_f32_16x16x32_bf16 v[30:33], v[120:123], v[30:33], v[50:53]
	s_mov_b32 s74, s89
	s_cmp_lt_i32 s89, s96
	v_mfma_f32_16x16x32_bf16 v[34:37], v[82:85], v[46:49], v[70:73]
	s_nop 2
	ds_read_b128 v[70:73], v100 offset:49152
	ds_read_b128 v[66:69], v100 offset:51200
	ds_read_b128 v[50:53], v98 offset:32768
	ds_read_b128 v[82:85], v98 offset:34816
	v_mfma_f32_16x16x32_bf16 v[38:41], v[104:107], v[46:49], v[74:77]
	v_mfma_f32_16x16x32_bf16 v[42:45], v[112:115], v[46:49], v[78:81]
	s_nop 1
	ds_read_b128 v[74:77], v100 offset:55296
	v_ashrrev_i32_e32 v112, 31, v97
	ds_read_b128 v[78:81], v100 offset:53248
	s_waitcnt lgkmcnt(2)
; #define GLDS_STAGE(st, kt_) do { \
;         _Pragma("unroll") for (int i_ = 0; i_ < FI; ++i_) { \
;             glds16(ap + (size_t)(32 * i_) * lda + (kt_) * 64, l3a + (st) + tid * 16 + i_ * 4096); \
;             glds16(bp + (size_t)(32 * i_) * ldb + (kt_) * 64, l3a + (st) + OPB + tid * 16 + i_ * 4096); } } while (0)
; #define GLDS_STAGE(st, kt_) do { \
;         _Pragma("unroll") for (int i_ = 0; i_ < 4; ++i_) { \
;             glds16(ap + (size_t)(64 * i_) * lda + (kt_) * 64, l3a + (st) + tid * 16 + i_ * 8192); \
;             glds16(bp + (size_t)(64 * i_) * ldb + (kt_) * 64, l3a + (st) + 32768 + tid * 16 + i_ * 8192); } } while (0)
; template <int WT, class Epi>
; DEV void gemm_tile(const bf16_t* __restrict__ A, int lda, const bf16_t* __restrict__ Bt, int ldb, int K, unsigned char* lds, const Epi& epi) {
;     ...
;     for (int kt = 0; kt < nk; ++kt) {
;         if (NSTG == 4 && kt + 2 < nk) { if (FI == 2) asm volatile("s_waitcnt vmcnt(8)" ::: "memory"); else asm volatile("s_waitcnt vmcnt(0)" ::: "memory"); }
;         else asm volatile("s_waitcnt vmcnt(0)" ::: "memory");
;         __syncthreads();
;         if (kt + NSTG - 1 < nk) GLDS_STAGE(nxt, kt + NSTG - 1);
; #pragma unroll
;         for (int kh = 0; kh < 2; ++kh) {
;             bf16x8 af[FI], bfr[FI];
;             const int ch = ((kh * 4 + fq) ^ sw) << 4;
; #pragma unroll
;             for (int i = 0; i < FI; ++i) { af[i] = *(const bf16x8*)(lds + cur + aoff + i * 2048 + ch); bfr[i] = *(const bf16x8*)(lds + cur + boff + i * 2048 + ch); }
; #pragma unroll
;             for (int mi = 0; mi < FI; ++mi)
; #pragma unroll
;                 for (int ni = 0; ni < FI; ++ni) acc[mi][ni] = __builtin_amdgcn_mfma_f32_16x16x32_bf16(bfr[ni], af[mi], acc[mi][ni], 0, 0, 0);
;         }
;         nxt = cur; cur += STB; if (cur == NSTG * STB) cur = 0;
	v_mfma_f32_16x16x32_bf16 v[2:5], v[70:73], v[82:85], v[2:5]
	v_mfma_f32_16x16x32_bf16 v[6:9], v[66:69], v[82:85], v[6:9]
	s_waitcnt lgkmcnt(0)
	v_mfma_f32_16x16x32_bf16 v[10:13], v[78:81], v[82:85], v[10:13]
	v_mfma_f32_16x16x32_bf16 v[14:17], v[74:77], v[82:85], v[14:17]
	ds_read_b128 v[82:85], v98 offset:36864
	ds_read_b128 v[104:107], v98 offset:38912
	v_mfma_f32_16x16x32_bf16 v[46:49], v[120:123], v[46:49], v[54:57]
	v_add_u32_e32 v123, 0x400, v97
	v_add_u32_e32 v120, 0x100, v97
	v_ashrrev_i32_e32 v114, 31, v123
	v_mfma_f32_16x16x32_bf16 v[54:57], v[70:73], v[50:53], v[108:111]
	v_lshrrev_b32_e32 v138, 28, v114
	v_add_u32_e32 v121, 0x200, v97
	v_add_u32_e32 v122, 0x300, v97
	v_mfma_f32_16x16x32_bf16 v[58:61], v[66:69], v[50:53], v[116:119]
	v_and_b32_e32 v110, 64, v97
	v_mad_i64_i32 v[108:109], s[90:91], s79, v94, v[132:133]
	v_mfma_f32_16x16x32_bf16 v[62:65], v[78:81], v[50:53], v[124:127]
	v_lshl_or_b32 v103, v103, 2, v110
	v_lshl_add_u64 v[108:109], v[108:109], 0, s[68:69]
	v_lshrrev_b32_e32 v111, 1, v97
	v_mfma_f32_16x16x32_bf16 v[50:53], v[74:77], v[50:53], v[134:137]
	v_add_u32_e32 v124, 0x500, v97
	v_ashrrev_i32_e32 v115, 31, v124
	v_lshrrev_b32_e32 v129, 3, v103
	s_waitcnt lgkmcnt(1)
	v_mfma_f32_16x16x32_bf16 v[18:21], v[70:73], v[82:85], v[18:21]
	v_lshl_add_u64 v[102:103], v[108:109], 0, s[66:67]
	v_lshl_add_u64 v[108:109], v[90:91], 0, s[52:53]
	v_add_u32_e32 v125, 0x600, v97
	v_mfma_f32_16x16x32_bf16 v[22:25], v[66:69], v[82:85], v[22:25]
	v_add_u32_e32 v126, 0x700, v97
	v_and_b32_e32 v127, 8, v111
	v_lshrrev_b32_e32 v110, 28, v112
	v_mfma_f32_16x16x32_bf16 v[26:29], v[78:81], v[82:85], v[26:29]
	v_ashrrev_i32_e32 v111, 31, v120
	v_lshrrev_b32_e32 v139, 28, v115
	v_lshl_add_u64 v[114:115], v[92:93], 0, s[52:53]
	v_mfma_f32_16x16x32_bf16 v[30:33], v[74:77], v[82:85], v[30:33]
	v_ashrrev_i32_e32 v116, 31, v125
	v_ashrrev_i32_e32 v117, 31, v126
	v_add_u32_e32 v134, v97, v110
	s_waitcnt lgkmcnt(0)
	v_mfma_f32_16x16x32_bf16 v[34:37], v[70:73], v[104:107], v[34:37]
	v_lshrrev_b32_e32 v135, 28, v111
	v_lshl_add_u64 v[110:111], v[90:91], 0, s[54:55]
	v_ashrrev_i32_e32 v112, 31, v121
	v_mfma_f32_16x16x32_bf16 v[38:41], v[66:69], v[104:107], v[38:41]
	ds_read_b128 v[66:69], v101 offset:49152
	ds_read_b128 v[70:73], v101 offset:51200
	v_ashrrev_i32_e32 v113, 31, v122
	v_lshrrev_b32_e32 v140, 28, v116
	v_mfma_f32_16x16x32_bf16 v[42:45], v[78:81], v[104:107], v[42:45]
	v_lshrrev_b32_e32 v141, 28, v117
	v_lshl_add_u64 v[116:117], v[92:93], 0, s[56:57]
	v_lshrrev_b32_e32 v136, 28, v112
	v_mfma_f32_16x16x32_bf16 v[46:49], v[74:77], v[104:107], v[46:49]
	ds_read_b128 v[74:77], v88 offset:32768
	ds_read_b128 v[78:81], v88 offset:34816
	ds_read_b128 v[82:85], v101 offset:53248
	ds_read_b128 v[104:107], v101 offset:55296
	s_waitcnt lgkmcnt(3)
	v_mfma_f32_16x16x32_bf16 v[54:57], v[66:69], v[74:77], v[54:57]
	v_lshrrev_b32_e32 v137, 28, v113
	v_lshl_add_u64 v[112:113], v[90:91], 0, s[58:59]
	v_lshl_add_u64 v[118:119], v[92:93], 0, s[60:61]
	v_mfma_f32_16x16x32_bf16 v[58:61], v[70:73], v[74:77], v[58:61]
	v_lshl_add_u64 v[90:91], v[90:91], 0, s[62:63]
	v_lshl_add_u64 v[92:93], v[92:93], 0, s[64:65]
	v_bitop3_b32 v142, v129, v97, 15 bitop3:0x78
	s_waitcnt lgkmcnt(1)
	v_mfma_f32_16x16x32_bf16 v[62:65], v[82:85], v[74:77], v[62:65]
	s_waitcnt lgkmcnt(0)
	v_mfma_f32_16x16x32_bf16 v[50:53], v[104:107], v[74:77], v[50:53]
	v_mfma_f32_16x16x32_bf16 v[2:5], v[66:69], v[78:81], v[2:5]
	v_mfma_f32_16x16x32_bf16 v[6:9], v[70:73], v[78:81], v[6:9]
	v_mfma_f32_16x16x32_bf16 v[10:13], v[82:85], v[78:81], v[10:13]
	v_mfma_f32_16x16x32_bf16 v[14:17], v[104:107], v[78:81], v[14:17]
	ds_read_b128 v[74:77], v88 offset:36864
	ds_read_b128 v[78:81], v88 offset:38912
	s_waitcnt vmcnt(0)
	s_waitcnt lgkmcnt(0)
	s_barrier
	s_mov_b32 s14, m0
	s_mov_b32 m0, s4
	s_nop 0
	global_load_lds_dwordx4 v[108:109], off
	s_mov_b32 m0, s14
	s_mov_b32 s4, m0
	s_mov_b32 m0, s84
	s_nop 0
	global_load_lds_dwordx4 v[114:115], off
	s_mov_b32 m0, s4
	v_mfma_f32_16x16x32_bf16 v[18:21], v[66:69], v[74:77], v[18:21]
	s_mov_b32 s4, m0
	s_mov_b32 m0, s83
	s_nop 0
	global_load_lds_dwordx4 v[110:111], off
	s_mov_b32 m0, s4
	v_add_u32_e32 v108, v120, v135
	s_mov_b32 s4, m0
	s_mov_b32 m0, s87
	s_nop 0
	global_load_lds_dwordx4 v[116:117], off
	s_mov_b32 m0, s4
	v_mfma_f32_16x16x32_bf16 v[22:25], v[70:73], v[74:77], v[22:25]
	s_mov_b32 s4, m0
	s_mov_b32 m0, s82
	s_nop 0
	global_load_lds_dwordx4 v[112:113], off
	s_mov_b32 m0, s4
	v_add_u32_e32 v109, v121, v136
	s_mov_b32 s4, m0
	s_mov_b32 m0, s86
	s_nop 0
	global_load_lds_dwordx4 v[118:119], off
	s_mov_b32 m0, s4
	v_mfma_f32_16x16x32_bf16 v[26:29], v[82:85], v[74:77], v[26:29]
	s_mov_b32 s4, m0
	s_mov_b32 m0, s81
	s_nop 0
	global_load_lds_dwordx4 v[90:91], off
	s_mov_b32 m0, s4
	v_add_u32_e32 v110, v122, v137
	s_mov_b32 s4, m0
	s_mov_b32 m0, s85
	s_nop 0
	global_load_lds_dwordx4 v[92:93], off
	s_mov_b32 m0, s4
	v_mfma_f32_16x16x32_bf16 v[30:33], v[104:107], v[74:77], v[30:33]
	v_add_u32_e32 v111, v123, v138
	v_add_u32_e32 v112, v124, v139
	v_add_u32_e32 v113, v125, v140
	v_mfma_f32_16x16x32_bf16 v[34:37], v[66:69], v[78:81], v[34:37]
	v_add_u32_e32 v114, v126, v141
	v_lshl_or_b32 v115, v142, 4, v127
	v_ashrrev_i32_e32 v119, 4, v108
	v_mfma_f32_16x16x32_bf16 v[38:41], v[70:73], v[78:81], v[38:41]
	ds_read_b128 v[66:69], v100 offset:16384
	ds_read_b128 v[70:73], v100 offset:18432
	v_and_b32_e32 v135, -16, v111
	v_and_b32_e32 v137, -16, v112
	v_mfma_f32_16x16x32_bf16 v[42:45], v[82:85], v[78:81], v[42:45]
	v_and_b32_e32 v139, -16, v113
	v_and_b32_e32 v141, -16, v114
	v_ashrrev_i32_e32 v136, 4, v112
	v_mfma_f32_16x16x32_bf16 v[46:49], v[104:107], v[78:81], v[46:49]
	ds_read_b128 v[74:77], v98
	ds_read_b128 v[78:81], v98 offset:2048
	ds_read_b128 v[82:85], v100 offset:20480
	ds_read_b128 v[90:93], v100 offset:22528
	s_waitcnt lgkmcnt(3)
; #define GLDS_STAGE(st, kt_) do { \
;         _Pragma("unroll") for (int i_ = 0; i_ < FI; ++i_) { \
;             glds16(ap + (size_t)(32 * i_) * lda + (kt_) * 64, l3a + (st) + tid * 16 + i_ * 4096); \
;             glds16(bp + (size_t)(32 * i_) * ldb + (kt_) * 64, l3a + (st) + OPB + tid * 16 + i_ * 4096); } } while (0)
; #define GLDS_STAGE(st, kt_) do { \
;         _Pragma("unroll") for (int i_ = 0; i_ < 4; ++i_) { \
;             glds16(ap + (size_t)(64 * i_) * lda + (kt_) * 64, l3a + (st) + tid * 16 + i_ * 8192); \
;             glds16(bp + (size_t)(64 * i_) * ldb + (kt_) * 64, l3a + (st) + 32768 + tid * 16 + i_ * 8192); } } while (0)
; template <int WT, class Epi>
; DEV void gemm_tile(const bf16_t* __restrict__ A, int lda, const bf16_t* __restrict__ Bt, int ldb, int K, unsigned char* lds, const Epi& epi) {
;     ...
;     for (int kt = 0; kt < nk; ++kt) {
;         if (NSTG == 4 && kt + 2 < nk) { if (FI == 2) asm volatile("s_waitcnt vmcnt(8)" ::: "memory"); else asm volatile("s_waitcnt vmcnt(0)" ::: "memory"); }
;         else asm volatile("s_waitcnt vmcnt(0)" ::: "memory");
;         __syncthreads();
;         if (kt + NSTG - 1 < nk) GLDS_STAGE(nxt, kt + NSTG - 1);
; #pragma unroll
;         for (int kh = 0; kh < 2; ++kh) {
;             bf16x8 af[FI], bfr[FI];
;             const int ch = ((kh * 4 + fq) ^ sw) << 4;
; #pragma unroll
;             for (int i = 0; i < FI; ++i) { af[i] = *(const bf16x8*)(lds + cur + aoff + i * 2048 + ch); bfr[i] = *(const bf16x8*)(lds + cur + boff + i * 2048 + ch); }
; #pragma unroll
;             for (int mi = 0; mi < FI; ++mi)
; #pragma unroll
;                 for (int ni = 0; ni < FI; ++ni) acc[mi][ni] = __builtin_amdgcn_mfma_f32_16x16x32_bf16(bfr[ni], af[mi], acc[mi][ni], 0, 0, 0);
;         }
;         nxt = cur; cur += STB; if (cur == NSTG * STB) cur = 0;
;     ...
;         for (int i = 0; i < (2 * WT * CPR) / 256; ++i) {
;             const int idx = tid + 256 * i, row = idx / CPR, cp = idx % CPR, c = cp ^ (row & (CPR - 1));
;             const uint4 d = *(const uint4*)(lds + row * RB + (cp << 4));
;             *(uint4*)(epi.obase + (size_t)row * epi.old + c * 8) = epi.finish(row, c * 8, d);
	v_mfma_f32_16x16x32_bf16 v[54:57], v[66:69], v[74:77], v[54:57]
	v_bitop3_b32 v104, v129, v99, 2 bitop3:0x36
	v_bitop3_b32 v105, v129, v99, 4 bitop3:0x36
	v_bitop3_b32 v99, v129, v99, 6 bitop3:0x36
	v_mfma_f32_16x16x32_bf16 v[58:61], v[70:73], v[74:77], v[58:61]
	v_and_b32_e32 v107, -16, v134
	v_ashrrev_i32_e32 v106, 4, v134
	v_lshl_or_b32 v116, v104, 4, v127
	s_waitcnt lgkmcnt(1)
	v_mfma_f32_16x16x32_bf16 v[62:65], v[82:85], v[74:77], v[62:65]
	v_lshl_or_b32 v117, v105, 4, v127
	v_lshl_or_b32 v99, v99, 4, v127
	v_sub_u32_e32 v97, v97, v107
	s_waitcnt lgkmcnt(0)
	v_mfma_f32_16x16x32_bf16 v[50:53], v[90:93], v[74:77], v[50:53]
	v_and_b32_e32 v107, -16, v108
	v_and_b32_e32 v108, -16, v109
	v_ashrrev_i32_e32 v129, 4, v110
	v_mfma_f32_16x16x32_bf16 v[2:5], v[66:69], v[78:81], v[2:5]
	v_and_b32_e32 v110, -16, v110
	v_lshlrev_b32_e32 v118, 8, v106
	v_ashrrev_i32_e32 v127, 4, v109
	v_mfma_f32_16x16x32_bf16 v[6:9], v[70:73], v[78:81], v[6:9]
	v_ashrrev_i32_e32 v134, 4, v111
	v_ashrrev_i32_e32 v138, 4, v113
	v_ashrrev_i32_e32 v140, 4, v114
	v_mfma_f32_16x16x32_bf16 v[10:13], v[82:85], v[78:81], v[10:13]
	v_add_u32_e32 v142, v128, v115
	v_add_u32_e32 v143, v128, v116
	v_add_u32_e32 v144, v128, v117
	v_mfma_f32_16x16x32_bf16 v[14:17], v[90:93], v[78:81], v[14:17]
	ds_read_b128 v[74:77], v98 offset:4096
	ds_read_b128 v[78:81], v98 offset:6144
	v_add_u32_e32 v128, v128, v99
	v_bitop3_b32 v99, v106, v97, 15 bitop3:0x6c
	s_waitcnt lgkmcnt(1)
	v_mfma_f32_16x16x32_bf16 v[18:21], v[66:69], v[74:77], v[18:21]
	v_lshlrev_b32_e32 v97, 4, v97
	v_sub_u32_e32 v120, v120, v107
	v_sub_u32_e32 v121, v121, v108
	v_mfma_f32_16x16x32_bf16 v[22:25], v[70:73], v[74:77], v[22:25]
	v_sub_u32_e32 v122, v122, v110
	v_sub_u32_e32 v123, v123, v135
	v_sub_u32_e32 v124, v124, v137
	v_mfma_f32_16x16x32_bf16 v[26:29], v[82:85], v[74:77], v[26:29]
	v_sub_u32_e32 v125, v125, v139
	v_sub_u32_e32 v126, v126, v141
	v_mad_i64_i32 v[104:105], s[66:67], v106, s73, v[102:103]
	v_mfma_f32_16x16x32_bf16 v[30:33], v[90:93], v[74:77], v[30:33]
	v_lshlrev_b32_e32 v145, 8, v119
	v_mad_i64_i32 v[106:107], s[66:67], v119, s73, v[102:103]
	s_waitcnt lgkmcnt(0)
	v_mfma_f32_16x16x32_bf16 v[34:37], v[66:69], v[78:81], v[34:37]
	v_lshlrev_b32_e32 v146, 8, v127
	v_mad_i64_i32 v[108:109], s[66:67], v127, s73, v[102:103]
	v_mfma_f32_16x16x32_bf16 v[38:41], v[70:73], v[78:81], v[38:41]
	ds_read_b128 v[66:69], v101 offset:16384
	ds_read_b128 v[70:73], v101 offset:18432
	v_lshlrev_b32_e32 v147, 8, v129
	v_mad_i64_i32 v[110:111], s[66:67], v129, s73, v[102:103]
	v_mfma_f32_16x16x32_bf16 v[42:45], v[82:85], v[78:81], v[42:45]
	v_lshlrev_b32_e32 v135, 8, v134
	v_mad_i64_i32 v[112:113], s[66:67], v134, s73, v[102:103]
	v_mfma_f32_16x16x32_bf16 v[46:49], v[90:93], v[78:81], v[46:49]
	ds_read_b128 v[74:77], v88
	ds_read_b128 v[78:81], v88 offset:2048
	ds_read_b128 v[82:85], v101 offset:20480
	ds_read_b128 v[90:93], v101 offset:22528
	s_waitcnt lgkmcnt(3)
	v_mfma_f32_16x16x32_bf16 v[54:57], v[66:69], v[74:77], v[54:57]
	v_lshlrev_b32_e32 v137, 8, v136
	v_mad_i64_i32 v[114:115], s[66:67], v136, s73, v[102:103]
	v_mfma_f32_16x16x32_bf16 v[58:61], v[70:73], v[74:77], v[58:61]
	v_lshlrev_b32_e32 v139, 8, v138
	v_mad_i64_i32 v[116:117], s[66:67], v138, s73, v[102:103]
	s_waitcnt lgkmcnt(1)
	v_mfma_f32_16x16x32_bf16 v[62:65], v[82:85], v[74:77], v[62:65]
	v_lshlrev_b32_e32 v141, 8, v140
	v_add3_u32 v97, s70, v118, v97
	v_bitop3_b32 v118, v129, v122, 15 bitop3:0x6c
	s_waitcnt lgkmcnt(0)
	v_mfma_f32_16x16x32_bf16 v[50:53], v[90:93], v[74:77], v[50:53]
	v_mfma_f32_16x16x32_bf16 v[2:5], v[66:69], v[78:81], v[2:5]
	v_mfma_f32_16x16x32_bf16 v[6:9], v[70:73], v[78:81], v[6:9]
	v_mfma_f32_16x16x32_bf16 v[10:13], v[82:85], v[78:81], v[10:13]
	v_mfma_f32_16x16x32_bf16 v[14:17], v[90:93], v[78:81], v[14:17]
	ds_read_b128 v[74:77], v88 offset:4096
	ds_read_b128 v[78:81], v88 offset:6144
	s_waitcnt vmcnt(0)
	s_waitcnt lgkmcnt(0)
	v_mfma_f32_16x16x32_bf16 v[18:21], v[66:69], v[74:77], v[18:21]
	s_barrier
	v_mfma_f32_16x16x32_bf16 v[22:25], v[70:73], v[74:77], v[22:25]
	v_mfma_f32_16x16x32_bf16 v[26:29], v[82:85], v[74:77], v[26:29]
	v_mfma_f32_16x16x32_bf16 v[30:33], v[90:93], v[74:77], v[30:33]
	ds_read_b128 v[74:77], v100 offset:51200
	v_mfma_f32_16x16x32_bf16 v[34:37], v[66:69], v[78:81], v[34:37]
	ds_read_b128 v[66:69], v100 offset:49152
	v_mfma_f32_16x16x32_bf16 v[38:41], v[70:73], v[78:81], v[38:41]
	ds_read_b128 v[70:73], v98 offset:32768
	v_mfma_f32_16x16x32_bf16 v[42:45], v[82:85], v[78:81], v[42:45]
	ds_read_b128 v[82:85], v100 offset:55296
	v_mfma_f32_16x16x32_bf16 v[46:49], v[90:93], v[78:81], v[46:49]
	ds_read_b128 v[78:81], v100 offset:53248
	v_mad_i64_i32 v[90:91], s[66:67], v140, s73, v[102:103]
	s_waitcnt lgkmcnt(2)
	v_mfma_f32_16x16x32_bf16 v[54:57], v[66:69], v[70:73], v[54:57]
	v_lshlrev_b32_e32 v92, 3, v99
	v_bitop3_b32 v99, v119, v120, 15 bitop3:0x6c
	v_lshlrev_b32_e32 v100, 4, v120
	v_mfma_f32_16x16x32_bf16 v[58:61], v[74:77], v[70:73], v[58:61]
	v_bitop3_b32 v102, v127, v121, 15 bitop3:0x6c
	v_lshlrev_b32_e32 v103, 4, v121
	v_lshlrev_b32_e32 v119, 4, v122
	s_waitcnt lgkmcnt(0)
	v_mfma_f32_16x16x32_bf16 v[62:65], v[78:81], v[70:73], v[62:65]
	v_bitop3_b32 v120, v134, v123, 15 bitop3:0x6c
	v_lshlrev_b32_e32 v121, 4, v123
	v_bitop3_b32 v122, v136, v124, 15 bitop3:0x6c
	v_mfma_f32_16x16x32_bf16 v[50:53], v[82:85], v[70:73], v[50:53]
	ds_read_b128 v[70:73], v98 offset:34816
	v_lshlrev_b32_e32 v123, 4, v124
	v_bitop3_b32 v124, v138, v125, 15 bitop3:0x6c
	s_waitcnt lgkmcnt(0)
; DEV unsigned cvt_pk_bf16(float lo, float hi) { const f32x2_t v = {lo, hi}; const bf16x2_t b = __builtin_convertvector(v, bf16x2_t); return __builtin_bit_cast(unsigned, b); }
; template <int WT, class Epi>
; DEV void gemm_tile(const bf16_t* __restrict__ A, int lda, const bf16_t* __restrict__ Bt, int ldb, int K, unsigned char* lds, const Epi& epi) {
;     ...
; #pragma unroll
;         for (int kh = 0; kh < 2; ++kh) {
;             bf16x8 af[FI], bfr[FI];
;             const int ch = ((kh * 4 + fq) ^ sw) << 4;
; #pragma unroll
;             for (int i = 0; i < FI; ++i) { af[i] = *(const bf16x8*)(lds + cur + aoff + i * 2048 + ch); bfr[i] = *(const bf16x8*)(lds + cur + boff + i * 2048 + ch); }
; #pragma unroll
;             for (int mi = 0; mi < FI; ++mi)
; #pragma unroll
;                 for (int ni = 0; ni < FI; ++ni) acc[mi][ni] = __builtin_amdgcn_mfma_f32_16x16x32_bf16(bfr[ni], af[mi], acc[mi][ni], 0, 0, 0);
;         }
;         nxt = cur; cur += STB; if (cur == NSTG * STB) cur = 0;
;     }
;     ...
;     __syncthreads();
;     if constexpr (Epi::STAGE) {
;         constexpr int RB = 4 * WT, CPR = RB / 16;
; #pragma unroll
;         for (int mi = 0; mi < FI; ++mi)
; #pragma unroll
;             for (int ni = 0; ni < FI; ++ni) {
;                 const int row = wr * WT + mi * 16 + fr, col = wc * WT + ni * 16 + fq * 4;
;                 const f32x4 v = epi.xform(row, col, acc[mi][ni]);
;                 uint2 w; w.x = cvt_pk_bf16(v[0], v[1]); w.y = cvt_pk_bf16(v[2], v[3]);
;                 *(uint2*)(lds + row * RB + ((((col >> 3) ^ (row & (CPR - 1))) << 4) | (((col >> 2) & 1) << 3))) = w;
;             }
;         __syncthreads();
; #pragma unroll
;         for (int i = 0; i < (2 * WT * CPR) / 256; ++i) {
;             const int idx = tid + 256 * i, row = idx / CPR, cp = idx % CPR, c = cp ^ (row & (CPR - 1));
;             const uint4 d = *(const uint4*)(lds + row * RB + (cp << 4));
;             *(uint4*)(epi.obase + (size_t)row * epi.old + c * 8) = epi.finish(row, c * 8, d);
;         }
	v_mfma_f32_16x16x32_bf16 v[2:5], v[66:69], v[70:73], v[2:5]
	v_lshlrev_b32_e32 v125, 4, v125
	v_bitop3_b32 v127, v140, v126, 15 bitop3:0x6c
	v_lshlrev_b32_e32 v126, 4, v126
	v_mfma_f32_16x16x32_bf16 v[6:9], v[74:77], v[70:73], v[6:9]
	v_add3_u32 v129, s70, v145, v100
	v_add3_u32 v134, s70, v146, v103
	v_add3_u32 v136, s70, v147, v119
	v_mfma_f32_16x16x32_bf16 v[10:13], v[78:81], v[70:73], v[10:13]
	v_add3_u32 v135, s70, v135, v121
	v_add3_u32 v137, s70, v137, v123
	v_add3_u32 v138, s70, v139, v125
	v_mfma_f32_16x16x32_bf16 v[14:17], v[82:85], v[70:73], v[14:17]
	ds_read_b128 v[70:73], v98 offset:36864
	v_add3_u32 v126, s70, v141, v126
	v_ashrrev_i32_e32 v93, 31, v92
	s_waitcnt lgkmcnt(0)
	v_mfma_f32_16x16x32_bf16 v[18:21], v[66:69], v[70:73], v[18:21]
	v_lshlrev_b32_e32 v100, 3, v102
	v_lshlrev_b32_e32 v102, 3, v118
	v_lshlrev_b32_e32 v118, 3, v120
	v_mfma_f32_16x16x32_bf16 v[22:25], v[74:77], v[70:73], v[22:25]
	v_lshlrev_b32_e32 v120, 3, v122
	v_lshlrev_b32_e32 v122, 3, v124
	v_lshlrev_b32_e32 v124, 3, v127
	v_mfma_f32_16x16x32_bf16 v[26:29], v[78:81], v[70:73], v[26:29]
	v_lshl_add_u64 v[92:93], v[92:93], 1, v[104:105]
	v_ashrrev_i32_e32 v103, 31, v102
	v_ashrrev_i32_e32 v119, 31, v118
	v_mfma_f32_16x16x32_bf16 v[30:33], v[82:85], v[70:73], v[30:33]
	ds_read_b128 v[70:73], v98 offset:38912
	v_lshlrev_b32_e32 v98, 3, v99
	v_ashrrev_i32_e32 v99, 31, v98
	s_waitcnt lgkmcnt(0)
	v_mfma_f32_16x16x32_bf16 v[34:37], v[66:69], v[70:73], v[34:37]
	ds_read_b128 v[66:69], v101 offset:49152
	v_ashrrev_i32_e32 v121, 31, v120
	v_ashrrev_i32_e32 v123, 31, v122
	v_mfma_f32_16x16x32_bf16 v[38:41], v[74:77], v[70:73], v[38:41]
	ds_read_b128 v[74:77], v101 offset:51200
	v_ashrrev_i32_e32 v125, 31, v124
	v_lshl_add_u64 v[98:99], v[98:99], 1, v[106:107]
	v_mfma_f32_16x16x32_bf16 v[42:45], v[78:81], v[70:73], v[42:45]
	ds_read_b128 v[78:81], v101 offset:53248
	v_lshl_add_u64 v[90:91], v[124:125], 1, v[90:91]
	v_mfma_f32_16x16x32_bf16 v[46:49], v[82:85], v[70:73], v[46:49]
	ds_read_b128 v[82:85], v101 offset:55296
	ds_read_b128 v[70:73], v88 offset:32768
	v_ashrrev_i32_e32 v101, 31, v100
	s_waitcnt lgkmcnt(0)
	v_mfma_f32_16x16x32_bf16 v[54:57], v[66:69], v[70:73], v[54:57]
	v_mfma_f32_16x16x32_bf16 v[58:61], v[74:77], v[70:73], v[58:61]
	s_nop 6
	v_cvt_pk_bf16_f32 v54, v54, v55
	v_cvt_pk_bf16_f32 v55, v56, v57
	v_mfma_f32_16x16x32_bf16 v[62:65], v[78:81], v[70:73], v[62:65]
	v_mfma_f32_16x16x32_bf16 v[50:53], v[82:85], v[70:73], v[50:53]
	ds_read_b128 v[70:73], v88 offset:34816
	v_cvt_pk_bf16_f32 v56, v58, v59
	v_cvt_pk_bf16_f32 v57, v60, v61
	s_waitcnt lgkmcnt(0)
	v_mfma_f32_16x16x32_bf16 v[2:5], v[66:69], v[70:73], v[2:5]
	s_nop 1
	v_cvt_pk_bf16_f32 v58, v62, v63
	v_cvt_pk_bf16_f32 v59, v64, v65
	v_cvt_pk_bf16_f32 v50, v50, v51
	v_mfma_f32_16x16x32_bf16 v[6:9], v[74:77], v[70:73], v[6:9]
	s_nop 1
	v_cvt_pk_bf16_f32 v2, v2, v3
	v_cvt_pk_bf16_f32 v3, v4, v5
	v_cvt_pk_bf16_f32 v51, v52, v53
	v_mfma_f32_16x16x32_bf16 v[10:13], v[78:81], v[70:73], v[10:13]
	v_mfma_f32_16x16x32_bf16 v[14:17], v[82:85], v[70:73], v[14:17]
	ds_read_b128 v[70:73], v88 offset:36864
	v_cvt_pk_bf16_f32 v4, v6, v7
	v_cvt_pk_bf16_f32 v5, v8, v9
	s_waitcnt lgkmcnt(0)
	v_mfma_f32_16x16x32_bf16 v[18:21], v[66:69], v[70:73], v[18:21]
	s_nop 1
	v_cvt_pk_bf16_f32 v6, v10, v11
	v_cvt_pk_bf16_f32 v7, v12, v13
	v_cvt_pk_bf16_f32 v8, v14, v15
	v_mfma_f32_16x16x32_bf16 v[22:25], v[74:77], v[70:73], v[22:25]
	v_cvt_pk_bf16_f32 v9, v16, v17
	s_nop 0
	v_cvt_pk_bf16_f32 v10, v18, v19
	v_cvt_pk_bf16_f32 v11, v20, v21
	v_mfma_f32_16x16x32_bf16 v[26:29], v[78:81], v[70:73], v[26:29]
	v_mfma_f32_16x16x32_bf16 v[30:33], v[82:85], v[70:73], v[30:33]
	ds_read_b128 v[70:73], v88 offset:38912
	s_nop 0
	v_cvt_pk_bf16_f32 v12, v22, v23
	v_cvt_pk_bf16_f32 v13, v24, v25
	s_waitcnt lgkmcnt(0)
	v_mfma_f32_16x16x32_bf16 v[34:37], v[66:69], v[70:73], v[34:37]
	s_nop 0
	v_cvt_pk_bf16_f32 v14, v26, v27
	v_cvt_pk_bf16_f32 v15, v28, v29
	v_cvt_pk_bf16_f32 v16, v30, v31
	v_mfma_f32_16x16x32_bf16 v[38:41], v[74:77], v[70:73], v[38:41]
	v_cvt_pk_bf16_f32 v17, v32, v33
	s_nop 1
	v_cvt_pk_bf16_f32 v18, v34, v35
	v_cvt_pk_bf16_f32 v19, v36, v37
	v_mfma_f32_16x16x32_bf16 v[42:45], v[78:81], v[70:73], v[42:45]
	s_nop 1
	v_cvt_pk_bf16_f32 v20, v38, v39
	v_cvt_pk_bf16_f32 v21, v40, v41
	v_mfma_f32_16x16x32_bf16 v[46:49], v[82:85], v[70:73], v[46:49]
	s_barrier
	s_nop 1
	v_cvt_pk_bf16_f32 v22, v42, v43
	v_cvt_pk_bf16_f32 v23, v44, v45
	v_lshl_add_u64 v[66:67], v[100:101], 1, v[108:109]
	s_nop 1
	v_cvt_pk_bf16_f32 v24, v46, v47
	v_cvt_pk_bf16_f32 v25, v48, v49
	ds_write_b64 v142, v[54:55]
	ds_write_b64 v143, v[56:57]
	ds_write_b64 v144, v[58:59]
	ds_write_b64 v128, v[50:51]
	ds_write_b64 v142, v[2:3] offset:4096
	ds_write_b64 v143, v[4:5] offset:4096
	ds_write_b64 v144, v[6:7] offset:4096
	ds_write_b64 v128, v[8:9] offset:4096
	ds_write_b64 v142, v[10:11] offset:8192
	ds_write_b64 v143, v[12:13] offset:8192
	ds_write_b64 v144, v[14:15] offset:8192
	ds_write_b64 v128, v[16:17] offset:8192
	ds_write_b64 v142, v[18:19] offset:12288
	ds_write_b64 v143, v[20:21] offset:12288
	ds_write_b64 v144, v[22:23] offset:12288
	ds_write_b64 v128, v[24:25] offset:12288
	s_waitcnt lgkmcnt(0)
	s_barrier
	ds_read_b128 v[2:5], v97
	ds_read_b128 v[6:9], v129
	ds_read_b128 v[10:13], v134
	ds_read_b128 v[14:17], v136
	ds_read_b128 v[18:21], v135
	ds_read_b128 v[22:25], v137
	ds_read_b128 v[26:29], v138
	ds_read_b128 v[30:33], v126
	v_lshl_add_u64 v[68:69], v[102:103], 1, v[110:111]
	v_lshl_add_u64 v[100:101], v[118:119], 1, v[112:113]
	v_lshl_add_u64 v[74:75], v[120:121], 1, v[114:115]
	v_lshl_add_u64 v[76:77], v[122:123], 1, v[116:117]
	s_waitcnt lgkmcnt(7)
	global_store_dwordx4 v[92:93], v[2:5], off
	s_waitcnt lgkmcnt(6)
	global_store_dwordx4 v[98:99], v[6:9], off
	s_waitcnt lgkmcnt(5)
	global_store_dwordx4 v[66:67], v[10:13], off
	s_waitcnt lgkmcnt(4)
	global_store_dwordx4 v[68:69], v[14:17], off
	s_waitcnt lgkmcnt(3)
	global_store_dwordx4 v[100:101], v[18:21], off
	s_waitcnt lgkmcnt(2)
	global_store_dwordx4 v[74:75], v[22:25], off
	s_waitcnt lgkmcnt(1)
	global_store_dwordx4 v[76:77], v[26:29], off
	s_waitcnt lgkmcnt(0)
	global_store_dwordx4 v[90:91], v[30:33], off
	s_waitcnt vmcnt(63) expcnt(7) lgkmcnt(15)
	s_barrier
	s_cbranch_scc1 .LBB0_1409
